# v22 + leading half of the ping-pong K-loops waits for its LDS-DMA pieces only at the barrier that ends its MFMA block (loop duplicated per half)
# baseline (speedup 1.0000x reference)
; #define PG8_STAGE(bufoff, gbase, voff) do { _Pragma("unroll") for (int _i = 0; _i < 2; ++_i) \
;         __builtin_amdgcn_global_load_lds((const unsigned*)((const char*)(gbase) + (voff)[_i]), (PG8_LAS unsigned*)(lds + (bufoff) + ldsw + _i * 8192), 16, 0, 0); } while (0)
; #define PG8_LDA(dst, b, h) do { _Pragma("unroll") for (int m = 0; m < 4; ++m) _Pragma("unroll") for (int k = 0; k < 2; ++k) dst[m][k] = *(const PG8_LAS bf16x8*)(lds + PG8_SA(b, h) + aoff + m * 2048 + k * 1024); } while (0)
; #define PG8_LDB(dst, b, h) do { _Pragma("unroll") for (int n = 0; n < 2; ++n) _Pragma("unroll") for (int k = 0; k < 2; ++k) dst[n][k] = *(const PG8_LAS bf16x8*)(lds + PG8_SB(b, h) + boff + n * 2048 + k * 1024); } while (0)
; #define PG8_WAIT_V(n) asm volatile("s_waitcnt vmcnt(" #n ")" ::: "memory")
; #define PG8_BAR __builtin_amdgcn_s_barrier()
; template <class Epi, class Sched, bool ALIGN_EPI = false, bool SP2 = false>
; __device__ __forceinline__ void gemm_phase(PG8_LAS unsigned char* lds, const Gemm g, const Sched& S, const Epi& E, int tid_in) {
;     ...
;     for (;;) {
;         const bool has_next = S.next(ui + 1, nxt);
;         const char* nA = has_next ? (const char*)g.A + (size_t)nxt.pm * tstep : cA; const char* nB = has_next ? (const char*)g.Bt + (size_t)nxt.pn * tstep : cB;
;         for (int t = 0; t < nt; t += 2) {
;             if constexpr (Epi::MIDK) { if (t == Epi::MIDK_T) { if (wr == 0) PG8_BAR; E.mid(acc, cur, wr, wc, fr, fq); if (wr == 1) PG8_BAR; } }
;             const bool last = (t == nt - 2);
;             const char* a1 = cA + (size_t)(t + 1) * kstep;
;             const char* a2 = last ? nA : cA + (size_t)(t + 2) * kstep; const char* b2 = last ? nB : cB + (size_t)(t + 2) * kstep;
;             const char* a3 = a2 + kstep; const char* b3 = b2 + kstep;
;             if (last && has_next) S.a_ready(nxt);
;             if constexpr (SP2) {
;             PG8_LDB(B0, 0, 0); PG8_LDB(B1, 0, 1); PG8_SCHED; PG8_LDA(At, 0, 0); PG8_STAGE(PG8_SA(1, 1), a1 + hstep, voffA);
;             PG8_WAIT_V(8); PG8_WAIT_L(0); PG8_BAR; PG8_MMA(0, 0, At, B0); PG8_MMA(0, 1, At, B1); PG8_BAR; PG8_SCHED;
;     ...
;         for (int a = 0; a < 2; ++a)
; #pragma unroll
;             for (int b = 0; b < 2; ++b)
; #pragma unroll
;                 for (int m = 0; m < 4; ++m)
; #pragma unroll
;                     for (int n = 0; n < 2; ++n) acc[a][b][m][n] = (f32x4){0.f, 0.f, 0.f, 0.f};
.LBB0_375:
	s_ashr_i32 s17, s16, 31
	s_lshl_b64 s[18:19], s[16:17], 19
	s_add_u32 s18, s0, s18
	s_addc_u32 s19, s1, s19
	s_and_b64 s[20:21], s[2:3], exec
	s_cselect_b32 s17, s19, s25
	s_cselect_b32 s52, s18, s24
	s_ashr_i32 s15, s14, 31
	s_lshl_b64 s[20:21], s[14:15], 19
	s_add_u32 s20, s30, s20
	s_addc_u32 s21, s31, s21
	s_and_b64 s[28:29], s[2:3], exec
	s_cselect_b32 s15, s21, s27
	s_cselect_b32 s53, s20, s26
	s_add_u32 s24, s24, 0x40080
	s_addc_u32 s25, s25, 0
	s_add_u32 s54, s26, 0x100
	v_mov_b32_e32 v0, 0
	s_addc_u32 s55, s27, 0
	s_mov_b32 s56, -2
	v_mov_b32_e32 v1, v0
	v_mov_b32_e32 v2, v0
	v_mov_b32_e32 v3, v0
	v_mov_b32_e32 v4, v0
	v_mov_b32_e32 v5, v0
	v_mov_b32_e32 v6, v0
	v_mov_b32_e32 v7, v0
	v_mov_b32_e32 v16, v0
	v_mov_b32_e32 v17, v0
	v_mov_b32_e32 v18, v0
	v_mov_b32_e32 v19, v0
	v_mov_b32_e32 v20, v0
	v_mov_b32_e32 v21, v0
	v_mov_b32_e32 v22, v0
	v_mov_b32_e32 v23, v0
	v_mov_b32_e32 v32, v0
	v_mov_b32_e32 v33, v0
	v_mov_b32_e32 v34, v0
	v_mov_b32_e32 v35, v0
	v_mov_b32_e32 v36, v0
	v_mov_b32_e32 v37, v0
	v_mov_b32_e32 v38, v0
	v_mov_b32_e32 v39, v0
	v_mov_b32_e32 v48, v0
	v_mov_b32_e32 v49, v0
	v_mov_b32_e32 v50, v0
	v_mov_b32_e32 v51, v0
	v_mov_b32_e32 v52, v0
	v_mov_b32_e32 v53, v0
	v_mov_b32_e32 v54, v0
	v_mov_b32_e32 v55, v0
	v_mov_b32_e32 v8, v0
	v_mov_b32_e32 v9, v0
	v_mov_b32_e32 v10, v0
	v_mov_b32_e32 v11, v0
	v_mov_b32_e32 v12, v0
	v_mov_b32_e32 v13, v0
	v_mov_b32_e32 v14, v0
	v_mov_b32_e32 v15, v0
	v_mov_b32_e32 v24, v0
	v_mov_b32_e32 v25, v0
	v_mov_b32_e32 v26, v0
	v_mov_b32_e32 v27, v0
	v_mov_b32_e32 v28, v0
	v_mov_b32_e32 v29, v0
	v_mov_b32_e32 v30, v0
	v_mov_b32_e32 v31, v0
	v_mov_b32_e32 v40, v0
	v_mov_b32_e32 v41, v0
	v_mov_b32_e32 v42, v0
	v_mov_b32_e32 v43, v0
	v_mov_b32_e32 v44, v0
	v_mov_b32_e32 v45, v0
	v_mov_b32_e32 v46, v0
	v_mov_b32_e32 v47, v0
	v_mov_b32_e32 v56, v0
	v_mov_b32_e32 v57, v0
	v_mov_b32_e32 v58, v0
	v_mov_b32_e32 v59, v0
	v_mov_b32_e32 v60, v0
	v_mov_b32_e32 v61, v0
	v_mov_b32_e32 v62, v0
	v_mov_b32_e32 v63, v0
	v_mov_b32_e32 v64, v0
	v_mov_b32_e32 v65, v0
	v_mov_b32_e32 v66, v0
	v_mov_b32_e32 v67, v0
	v_mov_b32_e32 v68, v0
	v_mov_b32_e32 v69, v0
	v_mov_b32_e32 v70, v0
	v_mov_b32_e32 v71, v0
	v_mov_b32_e32 v80, v0
	v_mov_b32_e32 v81, v0
	v_mov_b32_e32 v82, v0
	v_mov_b32_e32 v83, v0
	v_mov_b32_e32 v84, v0
	v_mov_b32_e32 v85, v0
	v_mov_b32_e32 v86, v0
	v_mov_b32_e32 v87, v0
	v_mov_b32_e32 v96, v0
	v_mov_b32_e32 v97, v0
	v_mov_b32_e32 v98, v0
	v_mov_b32_e32 v99, v0
	v_mov_b32_e32 v100, v0
	v_mov_b32_e32 v101, v0
	v_mov_b32_e32 v102, v0
	v_mov_b32_e32 v103, v0
	v_mov_b32_e32 v112, v0
	v_mov_b32_e32 v113, v0
	v_mov_b32_e32 v114, v0
	v_mov_b32_e32 v115, v0
	v_mov_b32_e32 v116, v0
	v_mov_b32_e32 v117, v0
	v_mov_b32_e32 v118, v0
	v_mov_b32_e32 v119, v0
	v_mov_b32_e32 v72, v0
	v_mov_b32_e32 v73, v0
	v_mov_b32_e32 v74, v0
	v_mov_b32_e32 v75, v0
	v_mov_b32_e32 v76, v0
	v_mov_b32_e32 v77, v0
	v_mov_b32_e32 v78, v0
	v_mov_b32_e32 v79, v0
	v_mov_b32_e32 v88, v0
	v_mov_b32_e32 v89, v0
	v_mov_b32_e32 v90, v0
	v_mov_b32_e32 v91, v0
	v_mov_b32_e32 v92, v0
	v_mov_b32_e32 v93, v0
	v_mov_b32_e32 v94, v0
	v_mov_b32_e32 v95, v0
	v_mov_b32_e32 v104, v0
	v_mov_b32_e32 v105, v0
	v_mov_b32_e32 v106, v0
	v_mov_b32_e32 v107, v0
	v_mov_b32_e32 v108, v0
	v_mov_b32_e32 v109, v0
	v_mov_b32_e32 v110, v0
	v_mov_b32_e32 v111, v0
	v_mov_b32_e32 v120, v0
	v_mov_b32_e32 v121, v0
	v_mov_b32_e32 v122, v0
	v_mov_b32_e32 v123, v0
	v_mov_b32_e32 v124, v0
	v_mov_b32_e32 v125, v0
	v_mov_b32_e32 v126, v0
	v_mov_b32_e32 v127, v0
	s_cmp_lg_u64 s[12:13], 0
	s_cbranch_scc0 .Lasym_T_376
.LBB0_376:
	s_add_u32 s26, s24, 0xfffc0080
	s_addc_u32 s27, s25, -1
	s_cmp_eq_u32 s56, 12
	s_cselect_b32 s29, s17, s27
	s_cselect_b32 s28, s52, s26
	s_cselect_b32 s27, s15, s55
	s_cselect_b32 s26, s53, s54
	s_add_i32 m0, s23, 0xc000
	ds_read_b128 v[150:153], v147
	global_load_lds_dwordx4 v136, s[24:25]
	s_add_i32 m0, s23, 0xe000
	ds_read_b128 v[154:157], v147 offset:1024
	global_load_lds_dwordx4 v138, s[24:25]
	ds_read_b128 v[158:161], v147 offset:2048
	ds_read_b128 v[162:165], v147 offset:3072
	ds_read_b128 v[166:169], v148
	ds_read_b128 v[170:173], v148 offset:1024
	ds_read_b128 v[174:177], v148 offset:2048
	ds_read_b128 v[178:181], v148 offset:3072
	ds_read_b128 v[182:185], v149
	ds_read_b128 v[186:189], v149 offset:1024
	ds_read_b128 v[190:193], v149 offset:2048
	ds_read_b128 v[194:197], v149 offset:3072
	ds_read_b128 v[198:201], v149 offset:4096
	ds_read_b128 v[202:205], v149 offset:5120
	ds_read_b128 v[206:209], v149 offset:6144
	ds_read_b128 v[210:213], v149 offset:7168
	s_waitcnt lgkmcnt(0)
	s_barrier
; #define PG8_STAGE(bufoff, gbase, voff) do { _Pragma("unroll") for (int _i = 0; _i < 2; ++_i) \
;         __builtin_amdgcn_global_load_lds((const unsigned*)((const char*)(gbase) + (voff)[_i]), (PG8_LAS unsigned*)(lds + (bufoff) + ldsw + _i * 8192), 16, 0, 0); } while (0)
; #define PG8_LDA(dst, b, h) do { _Pragma("unroll") for (int m = 0; m < 4; ++m) _Pragma("unroll") for (int k = 0; k < 2; ++k) dst[m][k] = *(const PG8_LAS bf16x8*)(lds + PG8_SA(b, h) + aoff + m * 2048 + k * 1024); } while (0)
; #define PG8_MMA(ai, bj, At, Bt) do { __builtin_amdgcn_s_setprio(1); _Pragma("unroll") for (int m = 0; m < 4; ++m) _Pragma("unroll") for (int n = 0; n < 2; ++n) _Pragma("unroll") for (int k = 0; k < 2; ++k) \
;         acc[ai][bj][m][n] = __builtin_amdgcn_mfma_f32_16x16x32_bf16(Bt[n][k], At[m][k], acc[ai][bj][m][n], 0, 0, 0); __builtin_amdgcn_s_setprio(0); } while (0)
; #define PG8_WAIT_V(n) asm volatile("s_waitcnt vmcnt(" #n ")" ::: "memory")
; #define PG8_WAIT_L(n) asm volatile("s_waitcnt lgkmcnt(" #n ")" ::: "memory")
; #define PG8_BAR __builtin_amdgcn_s_barrier()
; #define PG8_SCHED __builtin_amdgcn_sched_barrier(0)
; template <class Epi, class Sched, bool ALIGN_EPI = false, bool SP2 = false>
; __device__ __forceinline__ void gemm_phase(PG8_LAS unsigned char* lds, const Gemm g, const Sched& S, const Epi& E, int tid_in) {
;     ...
;             PG8_WAIT_V(8); PG8_WAIT_L(0); PG8_BAR; PG8_MMA(0, 0, At, B0); PG8_MMA(0, 1, At, B1); PG8_BAR; PG8_SCHED;
;             PG8_LDA(At, 0, 1); PG8_STAGE(PG8_SB(0, 0), b2, voffB); PG8_STAGE(PG8_SB(0, 1), b2 + hstep, voffB); PG8_STAGE(PG8_SA(0, 0), a2, voffA);
;             PG8_WAIT_V(8); PG8_WAIT_L(0); PG8_BAR; PG8_MMA(1, 0, At, B0); PG8_MMA(1, 1, At, B1); PG8_BAR; PG8_SCHED;
	v_mfma_f32_16x16x32_bf16 v[124:127], v[150:153], v[182:185], v[124:127]
	v_mfma_f32_16x16x32_bf16 v[120:123], v[158:161], v[182:185], v[120:123]
	v_mfma_f32_16x16x32_bf16 v[108:111], v[150:153], v[190:193], v[108:111]
	v_mfma_f32_16x16x32_bf16 v[104:107], v[158:161], v[190:193], v[104:107]
	v_mfma_f32_16x16x32_bf16 v[92:95], v[150:153], v[198:201], v[92:95]
	v_mfma_f32_16x16x32_bf16 v[88:91], v[158:161], v[198:201], v[88:91]
	v_mfma_f32_16x16x32_bf16 v[76:79], v[150:153], v[206:209], v[76:79]
	v_mfma_f32_16x16x32_bf16 v[72:75], v[158:161], v[206:209], v[72:75]
	v_mfma_f32_16x16x32_bf16 v[124:127], v[154:157], v[186:189], v[124:127]
	v_mfma_f32_16x16x32_bf16 v[120:123], v[162:165], v[186:189], v[120:123]
	v_mfma_f32_16x16x32_bf16 v[108:111], v[154:157], v[194:197], v[108:111]
	v_mfma_f32_16x16x32_bf16 v[104:107], v[162:165], v[194:197], v[104:107]
	v_mfma_f32_16x16x32_bf16 v[92:95], v[154:157], v[202:205], v[92:95]
	v_mfma_f32_16x16x32_bf16 v[88:91], v[162:165], v[202:205], v[88:91]
	v_mfma_f32_16x16x32_bf16 v[76:79], v[154:157], v[210:213], v[76:79]
	v_mfma_f32_16x16x32_bf16 v[72:75], v[162:165], v[210:213], v[72:75]
	v_mfma_f32_16x16x32_bf16 v[116:119], v[166:169], v[182:185], v[116:119]
	v_mfma_f32_16x16x32_bf16 v[112:115], v[174:177], v[182:185], v[112:115]
	v_mfma_f32_16x16x32_bf16 v[100:103], v[166:169], v[190:193], v[100:103]
	v_mfma_f32_16x16x32_bf16 v[96:99], v[174:177], v[190:193], v[96:99]
	v_mfma_f32_16x16x32_bf16 v[84:87], v[166:169], v[198:201], v[84:87]
	v_mfma_f32_16x16x32_bf16 v[80:83], v[174:177], v[198:201], v[80:83]
	v_mfma_f32_16x16x32_bf16 v[68:71], v[166:169], v[206:209], v[68:71]
	v_mfma_f32_16x16x32_bf16 v[64:67], v[174:177], v[206:209], v[64:67]
	v_mfma_f32_16x16x32_bf16 v[116:119], v[170:173], v[186:189], v[116:119]
	v_mfma_f32_16x16x32_bf16 v[112:115], v[178:181], v[186:189], v[112:115]
	v_mfma_f32_16x16x32_bf16 v[100:103], v[170:173], v[194:197], v[100:103]
	v_mfma_f32_16x16x32_bf16 v[96:99], v[178:181], v[194:197], v[96:99]
	v_mfma_f32_16x16x32_bf16 v[84:87], v[170:173], v[202:205], v[84:87]
	v_mfma_f32_16x16x32_bf16 v[80:83], v[178:181], v[202:205], v[80:83]
	v_mfma_f32_16x16x32_bf16 v[68:71], v[170:173], v[210:213], v[68:71]
	v_mfma_f32_16x16x32_bf16 v[64:67], v[178:181], v[210:213], v[64:67]
	s_waitcnt vmcnt(8)
	s_barrier
	s_add_u32 s98, s26, s10
	s_addc_u32 s99, s27, s11
	s_add_u32 s100, s28, s10
	s_addc_u32 s101, s29, s11
	s_add_i32 s57, s48, s34
	s_mov_b32 m0, s57
	ds_read_b128 v[182:185], v149 offset:16384
	global_load_lds_dwordx4 v132, s[26:27]
	s_add_i32 m0, s57, 0x2000
	s_add_u32 s60, s26, 0x40000
	s_addc_u32 s61, s27, 0
	s_add_i32 s57, s49, s34
	global_load_lds_dwordx4 v128, s[26:27]
	s_mov_b32 m0, s57
	ds_read_b128 v[186:189], v149 offset:17408
	global_load_lds_dwordx4 v132, s[60:61]
	s_add_i32 m0, s57, 0x2000
	ds_read_b128 v[190:193], v149 offset:18432
	global_load_lds_dwordx4 v128, s[60:61]
	s_mov_b32 m0, s23
	ds_read_b128 v[194:197], v149 offset:19456
	global_load_lds_dwordx4 v134, s[28:29]
	s_mov_b32 m0, s37
	ds_read_b128 v[198:201], v149 offset:20480
	global_load_lds_dwordx4 v130, s[28:29]
	ds_read_b128 v[202:205], v149 offset:21504
	ds_read_b128 v[206:209], v149 offset:22528
	ds_read_b128 v[210:213], v149 offset:23552
	s_waitcnt lgkmcnt(0)
	s_barrier
	v_mfma_f32_16x16x32_bf16 v[60:63], v[150:153], v[182:185], v[60:63]
	v_mfma_f32_16x16x32_bf16 v[56:59], v[158:161], v[182:185], v[56:59]
	v_mfma_f32_16x16x32_bf16 v[44:47], v[150:153], v[190:193], v[44:47]
	v_mfma_f32_16x16x32_bf16 v[40:43], v[158:161], v[190:193], v[40:43]
	v_mfma_f32_16x16x32_bf16 v[28:31], v[150:153], v[198:201], v[28:31]
	v_mfma_f32_16x16x32_bf16 v[24:27], v[158:161], v[198:201], v[24:27]
	v_mfma_f32_16x16x32_bf16 v[12:15], v[150:153], v[206:209], v[12:15]
	v_mfma_f32_16x16x32_bf16 v[8:11], v[158:161], v[206:209], v[8:11]
	v_mfma_f32_16x16x32_bf16 v[60:63], v[154:157], v[186:189], v[60:63]
	v_mfma_f32_16x16x32_bf16 v[56:59], v[162:165], v[186:189], v[56:59]
	v_mfma_f32_16x16x32_bf16 v[44:47], v[154:157], v[194:197], v[44:47]
	v_mfma_f32_16x16x32_bf16 v[40:43], v[162:165], v[194:197], v[40:43]
	v_mfma_f32_16x16x32_bf16 v[28:31], v[154:157], v[202:205], v[28:31]
	v_mfma_f32_16x16x32_bf16 v[24:27], v[162:165], v[202:205], v[24:27]
	v_mfma_f32_16x16x32_bf16 v[12:15], v[154:157], v[210:213], v[12:15]
	v_mfma_f32_16x16x32_bf16 v[8:11], v[162:165], v[210:213], v[8:11]
	v_mfma_f32_16x16x32_bf16 v[52:55], v[166:169], v[182:185], v[52:55]
	v_mfma_f32_16x16x32_bf16 v[48:51], v[174:177], v[182:185], v[48:51]
	v_mfma_f32_16x16x32_bf16 v[36:39], v[166:169], v[190:193], v[36:39]
	v_mfma_f32_16x16x32_bf16 v[32:35], v[174:177], v[190:193], v[32:35]
	v_mfma_f32_16x16x32_bf16 v[20:23], v[166:169], v[198:201], v[20:23]
	v_mfma_f32_16x16x32_bf16 v[16:19], v[174:177], v[198:201], v[16:19]
	v_mfma_f32_16x16x32_bf16 v[4:7], v[166:169], v[206:209], v[4:7]
	v_mfma_f32_16x16x32_bf16 v[0:3], v[174:177], v[206:209], v[0:3]
	v_mfma_f32_16x16x32_bf16 v[52:55], v[170:173], v[186:189], v[52:55]
	v_mfma_f32_16x16x32_bf16 v[48:51], v[178:181], v[186:189], v[48:51]
	v_mfma_f32_16x16x32_bf16 v[36:39], v[170:173], v[194:197], v[36:39]
	v_mfma_f32_16x16x32_bf16 v[32:35], v[178:181], v[194:197], v[32:35]
	v_mfma_f32_16x16x32_bf16 v[20:23], v[170:173], v[202:205], v[20:23]
	v_mfma_f32_16x16x32_bf16 v[16:19], v[178:181], v[202:205], v[16:19]
	v_mfma_f32_16x16x32_bf16 v[4:7], v[170:173], v[210:213], v[4:7]
	v_mfma_f32_16x16x32_bf16 v[0:3], v[178:181], v[210:213], v[0:3]
	s_waitcnt vmcnt(8)
	s_barrier
; #define PG8_STAGE(bufoff, gbase, voff) do { _Pragma("unroll") for (int _i = 0; _i < 2; ++_i) \
;         __builtin_amdgcn_global_load_lds((const unsigned*)((const char*)(gbase) + (voff)[_i]), (PG8_LAS unsigned*)(lds + (bufoff) + ldsw + _i * 8192), 16, 0, 0); } while (0)
; #define PG8_LDA(dst, b, h) do { _Pragma("unroll") for (int m = 0; m < 4; ++m) _Pragma("unroll") for (int k = 0; k < 2; ++k) dst[m][k] = *(const PG8_LAS bf16x8*)(lds + PG8_SA(b, h) + aoff + m * 2048 + k * 1024); } while (0)
; #define PG8_LDB(dst, b, h) do { _Pragma("unroll") for (int n = 0; n < 2; ++n) _Pragma("unroll") for (int k = 0; k < 2; ++k) dst[n][k] = *(const PG8_LAS bf16x8*)(lds + PG8_SB(b, h) + boff + n * 2048 + k * 1024); } while (0)
; #define PG8_MMA(ai, bj, At, Bt) do { __builtin_amdgcn_s_setprio(1); _Pragma("unroll") for (int m = 0; m < 4; ++m) _Pragma("unroll") for (int n = 0; n < 2; ++n) _Pragma("unroll") for (int k = 0; k < 2; ++k) \
;         acc[ai][bj][m][n] = __builtin_amdgcn_mfma_f32_16x16x32_bf16(Bt[n][k], At[m][k], acc[ai][bj][m][n], 0, 0, 0); __builtin_amdgcn_s_setprio(0); } while (0)
; #define PG8_WAIT_V(n) asm volatile("s_waitcnt vmcnt(" #n ")" ::: "memory")
; #define PG8_WAIT_L(n) asm volatile("s_waitcnt lgkmcnt(" #n ")" ::: "memory")
; #define PG8_BAR __builtin_amdgcn_s_barrier()
; #define PG8_SCHED __builtin_amdgcn_sched_barrier(0)
; template <class Epi, class Sched, bool ALIGN_EPI = false, bool SP2 = false>
; __device__ __forceinline__ void gemm_phase(PG8_LAS unsigned char* lds, const Gemm g, const Sched& S, const Epi& E, int tid_in) {
;     ...
;             PG8_LDB(B0, 1, 0); PG8_LDB(B1, 1, 1); PG8_SCHED; PG8_LDA(At, 1, 0); PG8_STAGE(PG8_SA(0, 1), a2 + hstep, voffA);
;             PG8_WAIT_V(8); PG8_WAIT_L(0); PG8_BAR; PG8_MMA(0, 0, At, B0); PG8_MMA(0, 1, At, B1); PG8_BAR; PG8_SCHED;
;             PG8_LDA(At, 1, 1); PG8_STAGE(PG8_SB(1, 0), b3, voffB); PG8_STAGE(PG8_SB(1, 1), b3 + hstep, voffB); PG8_STAGE(PG8_SA(1, 0), a3, voffA);
;             PG8_WAIT_V(8); PG8_WAIT_L(0); PG8_BAR; PG8_MMA(1, 0, At, B0); PG8_MMA(1, 1, At, B1); PG8_BAR; PG8_SCHED;
	s_add_i32 s57, 0, 0x18000
	s_add_i32 s59, 0, 0x1c000
	s_add_u32 s28, s28, 0x40000
	s_addc_u32 s29, s29, 0
	s_mov_b32 m0, s38
	s_nop 0
	global_load_lds_dwordx4 v134, s[28:29]
	s_mov_b32 m0, s39
	s_nop 0
	global_load_lds_dwordx4 v130, s[28:29]
	v_add_u32_e32 v162, s57, v145
	v_add_u32_e32 v178, s59, v145
	ds_read_b128 v[150:153], v162
	ds_read_b128 v[154:157], v162 offset:1024
	ds_read_b128 v[158:161], v162 offset:2048
	ds_read_b128 v[162:165], v162 offset:3072
	ds_read_b128 v[166:169], v178
	ds_read_b128 v[170:173], v178 offset:1024
	ds_read_b128 v[174:177], v178 offset:2048
	ds_read_b128 v[178:181], v178 offset:3072
	ds_read_b128 v[182:185], v149 offset:32768
	ds_read_b128 v[186:189], v149 offset:33792
	ds_read_b128 v[190:193], v149 offset:34816
	ds_read_b128 v[194:197], v149 offset:35840
	ds_read_b128 v[198:201], v149 offset:36864
	ds_read_b128 v[202:205], v149 offset:37888
	ds_read_b128 v[206:209], v149 offset:38912
	ds_read_b128 v[210:213], v149 offset:39936
	s_waitcnt lgkmcnt(0)
	s_barrier
	v_mfma_f32_16x16x32_bf16 v[124:127], v[150:153], v[182:185], v[124:127]
	v_mfma_f32_16x16x32_bf16 v[120:123], v[158:161], v[182:185], v[120:123]
	v_mfma_f32_16x16x32_bf16 v[108:111], v[150:153], v[190:193], v[108:111]
	v_mfma_f32_16x16x32_bf16 v[104:107], v[158:161], v[190:193], v[104:107]
	v_mfma_f32_16x16x32_bf16 v[92:95], v[150:153], v[198:201], v[92:95]
	v_mfma_f32_16x16x32_bf16 v[88:91], v[158:161], v[198:201], v[88:91]
	v_mfma_f32_16x16x32_bf16 v[76:79], v[150:153], v[206:209], v[76:79]
	v_mfma_f32_16x16x32_bf16 v[72:75], v[158:161], v[206:209], v[72:75]
	v_mfma_f32_16x16x32_bf16 v[124:127], v[154:157], v[186:189], v[124:127]
	v_mfma_f32_16x16x32_bf16 v[120:123], v[162:165], v[186:189], v[120:123]
	v_mfma_f32_16x16x32_bf16 v[108:111], v[154:157], v[194:197], v[108:111]
	v_mfma_f32_16x16x32_bf16 v[104:107], v[162:165], v[194:197], v[104:107]
	v_mfma_f32_16x16x32_bf16 v[92:95], v[154:157], v[202:205], v[92:95]
	v_mfma_f32_16x16x32_bf16 v[88:91], v[162:165], v[202:205], v[88:91]
	v_mfma_f32_16x16x32_bf16 v[76:79], v[154:157], v[210:213], v[76:79]
	v_mfma_f32_16x16x32_bf16 v[72:75], v[162:165], v[210:213], v[72:75]
	v_mfma_f32_16x16x32_bf16 v[116:119], v[166:169], v[182:185], v[116:119]
	v_mfma_f32_16x16x32_bf16 v[112:115], v[174:177], v[182:185], v[112:115]
	v_mfma_f32_16x16x32_bf16 v[100:103], v[166:169], v[190:193], v[100:103]
	v_mfma_f32_16x16x32_bf16 v[96:99], v[174:177], v[190:193], v[96:99]
	v_mfma_f32_16x16x32_bf16 v[84:87], v[166:169], v[198:201], v[84:87]
	v_mfma_f32_16x16x32_bf16 v[80:83], v[174:177], v[198:201], v[80:83]
	v_mfma_f32_16x16x32_bf16 v[68:71], v[166:169], v[206:209], v[68:71]
	v_mfma_f32_16x16x32_bf16 v[64:67], v[174:177], v[206:209], v[64:67]
	v_mfma_f32_16x16x32_bf16 v[116:119], v[170:173], v[186:189], v[116:119]
	v_mfma_f32_16x16x32_bf16 v[112:115], v[178:181], v[186:189], v[112:115]
	v_mfma_f32_16x16x32_bf16 v[100:103], v[170:173], v[194:197], v[100:103]
	v_mfma_f32_16x16x32_bf16 v[96:99], v[178:181], v[194:197], v[96:99]
	v_mfma_f32_16x16x32_bf16 v[84:87], v[170:173], v[202:205], v[84:87]
	v_mfma_f32_16x16x32_bf16 v[80:83], v[178:181], v[202:205], v[80:83]
	v_mfma_f32_16x16x32_bf16 v[68:71], v[170:173], v[210:213], v[68:71]
	v_mfma_f32_16x16x32_bf16 v[64:67], v[178:181], v[210:213], v[64:67]
	s_waitcnt vmcnt(8)
	s_barrier
	s_add_i32 s28, s57, s34
	s_mov_b32 m0, s28
	ds_read_b128 v[182:185], v149 offset:49152
	global_load_lds_dwordx4 v132, s[98:99]
	s_add_i32 m0, s28, 0x2000
	s_add_u32 s26, s26, 0x40080
	s_addc_u32 s27, s27, 0
	s_add_i32 s28, s59, s34
	global_load_lds_dwordx4 v128, s[98:99]
	s_mov_b32 m0, s28
	ds_read_b128 v[186:189], v149 offset:50176
	global_load_lds_dwordx4 v132, s[26:27]
	s_add_i32 m0, s28, 0x2000
	ds_read_b128 v[190:193], v149 offset:51200
	global_load_lds_dwordx4 v128, s[26:27]
	s_mov_b32 m0, s44
	ds_read_b128 v[194:197], v149 offset:52224
	global_load_lds_dwordx4 v134, s[100:101]
	s_mov_b32 m0, s45
	ds_read_b128 v[198:201], v149 offset:53248
	global_load_lds_dwordx4 v130, s[100:101]
	ds_read_b128 v[202:205], v149 offset:54272
	ds_read_b128 v[206:209], v149 offset:55296
	ds_read_b128 v[210:213], v149 offset:56320
	s_waitcnt lgkmcnt(0)
	s_barrier
	v_mfma_f32_16x16x32_bf16 v[60:63], v[150:153], v[182:185], v[60:63]
	v_mfma_f32_16x16x32_bf16 v[56:59], v[158:161], v[182:185], v[56:59]
	v_mfma_f32_16x16x32_bf16 v[44:47], v[150:153], v[190:193], v[44:47]
	v_mfma_f32_16x16x32_bf16 v[40:43], v[158:161], v[190:193], v[40:43]
	v_mfma_f32_16x16x32_bf16 v[28:31], v[150:153], v[198:201], v[28:31]
	v_mfma_f32_16x16x32_bf16 v[24:27], v[158:161], v[198:201], v[24:27]
	v_mfma_f32_16x16x32_bf16 v[12:15], v[150:153], v[206:209], v[12:15]
	v_mfma_f32_16x16x32_bf16 v[8:11], v[158:161], v[206:209], v[8:11]
	v_mfma_f32_16x16x32_bf16 v[60:63], v[154:157], v[186:189], v[60:63]
	v_mfma_f32_16x16x32_bf16 v[56:59], v[162:165], v[186:189], v[56:59]
	v_mfma_f32_16x16x32_bf16 v[44:47], v[154:157], v[194:197], v[44:47]
	v_mfma_f32_16x16x32_bf16 v[40:43], v[162:165], v[194:197], v[40:43]
	v_mfma_f32_16x16x32_bf16 v[28:31], v[154:157], v[202:205], v[28:31]
	v_mfma_f32_16x16x32_bf16 v[24:27], v[162:165], v[202:205], v[24:27]
	v_mfma_f32_16x16x32_bf16 v[12:15], v[154:157], v[210:213], v[12:15]
	v_mfma_f32_16x16x32_bf16 v[8:11], v[162:165], v[210:213], v[8:11]
	v_mfma_f32_16x16x32_bf16 v[52:55], v[166:169], v[182:185], v[52:55]
	v_mfma_f32_16x16x32_bf16 v[48:51], v[174:177], v[182:185], v[48:51]
	v_mfma_f32_16x16x32_bf16 v[36:39], v[166:169], v[190:193], v[36:39]
	v_mfma_f32_16x16x32_bf16 v[32:35], v[174:177], v[190:193], v[32:35]
	v_mfma_f32_16x16x32_bf16 v[20:23], v[166:169], v[198:201], v[20:23]
	v_mfma_f32_16x16x32_bf16 v[16:19], v[174:177], v[198:201], v[16:19]
	v_mfma_f32_16x16x32_bf16 v[4:7], v[166:169], v[206:209], v[4:7]
	v_mfma_f32_16x16x32_bf16 v[0:3], v[174:177], v[206:209], v[0:3]
	v_mfma_f32_16x16x32_bf16 v[52:55], v[170:173], v[186:189], v[52:55]
	v_mfma_f32_16x16x32_bf16 v[48:51], v[178:181], v[186:189], v[48:51]
	v_mfma_f32_16x16x32_bf16 v[36:39], v[170:173], v[194:197], v[36:39]
	v_mfma_f32_16x16x32_bf16 v[32:35], v[178:181], v[194:197], v[32:35]
	v_mfma_f32_16x16x32_bf16 v[20:23], v[170:173], v[202:205], v[20:23]
	v_mfma_f32_16x16x32_bf16 v[16:19], v[178:181], v[202:205], v[16:19]
	v_mfma_f32_16x16x32_bf16 v[4:7], v[170:173], v[210:213], v[4:7]
	v_mfma_f32_16x16x32_bf16 v[0:3], v[178:181], v[210:213], v[0:3]
	s_waitcnt vmcnt(8)
	s_barrier
	s_add_i32 s56, s56, 2
	s_add_u32 s24, s24, 0x100
	s_addc_u32 s25, s25, 0
	s_add_u32 s54, s54, 0x100
	s_addc_u32 s55, s55, 0
	s_cmp_gt_u32 s56, 13
	s_cbranch_scc0 .LBB0_376
	s_branch .Lasym_J_376
; #define PG8_STAGE(bufoff, gbase, voff) do { _Pragma("unroll") for (int _i = 0; _i < 2; ++_i) \
;         __builtin_amdgcn_global_load_lds((const unsigned*)((const char*)(gbase) + (voff)[_i]), (PG8_LAS unsigned*)(lds + (bufoff) + ldsw + _i * 8192), 16, 0, 0); } while (0)
; #define PG8_LDA(dst, b, h) do { _Pragma("unroll") for (int m = 0; m < 4; ++m) _Pragma("unroll") for (int k = 0; k < 2; ++k) dst[m][k] = *(const PG8_LAS bf16x8*)(lds + PG8_SA(b, h) + aoff + m * 2048 + k * 1024); } while (0)
; #define PG8_LDB(dst, b, h) do { _Pragma("unroll") for (int n = 0; n < 2; ++n) _Pragma("unroll") for (int k = 0; k < 2; ++k) dst[n][k] = *(const PG8_LAS bf16x8*)(lds + PG8_SB(b, h) + boff + n * 2048 + k * 1024); } while (0)
; #define PG8_MMA(ai, bj, At, Bt) do { __builtin_amdgcn_s_setprio(1); _Pragma("unroll") for (int m = 0; m < 4; ++m) _Pragma("unroll") for (int n = 0; n < 2; ++n) _Pragma("unroll") for (int k = 0; k < 2; ++k) \
;         acc[ai][bj][m][n] = __builtin_amdgcn_mfma_f32_16x16x32_bf16(Bt[n][k], At[m][k], acc[ai][bj][m][n], 0, 0, 0); __builtin_amdgcn_s_setprio(0); } while (0)
; #define PG8_WAIT_V(n) asm volatile("s_waitcnt vmcnt(" #n ")" ::: "memory")
; #define PG8_WAIT_L(n) asm volatile("s_waitcnt lgkmcnt(" #n ")" ::: "memory")
; template <class Epi, class Sched, bool ALIGN_EPI = false, bool SP2 = false>
; __device__ __forceinline__ void gemm_phase(PG8_LAS unsigned char* lds, const Gemm g, const Sched& S, const Epi& E, int tid_in) {
;     ...
;             const bool last = (t == nt - 2);
;             const char* a1 = cA + (size_t)(t + 1) * kstep;
;             const char* a2 = last ? nA : cA + (size_t)(t + 2) * kstep; const char* b2 = last ? nB : cB + (size_t)(t + 2) * kstep;
;             const char* a3 = a2 + kstep; const char* b3 = b2 + kstep;
;             if (last && has_next) S.a_ready(nxt);
;             if constexpr (SP2) {
;             PG8_LDB(B0, 0, 0); PG8_LDB(B1, 0, 1); PG8_SCHED; PG8_LDA(At, 0, 0); PG8_STAGE(PG8_SA(1, 1), a1 + hstep, voffA);
;             PG8_WAIT_V(8); PG8_WAIT_L(0); PG8_BAR; PG8_MMA(0, 0, At, B0); PG8_MMA(0, 1, At, B1); PG8_BAR; PG8_SCHED;
;             PG8_LDA(At, 0, 1); PG8_STAGE(PG8_SB(0, 0), b2, voffB); PG8_STAGE(PG8_SB(0, 1), b2 + hstep, voffB); PG8_STAGE(PG8_SA(0, 0), a2, voffA);
;             PG8_WAIT_V(8); PG8_WAIT_L(0); PG8_BAR; PG8_MMA(1, 0, At, B0); PG8_MMA(1, 1, At, B1); PG8_BAR; PG8_SCHED;
.Lasym_T_376:
	s_add_u32 s26, s24, 0xfffc0080
	s_addc_u32 s27, s25, -1
	s_cmp_eq_u32 s56, 12
	s_cselect_b32 s29, s17, s27
	s_cselect_b32 s28, s52, s26
	s_cselect_b32 s27, s15, s55
	s_cselect_b32 s26, s53, s54
	s_add_i32 m0, s23, 0xc000
	ds_read_b128 v[150:153], v147
	global_load_lds_dwordx4 v136, s[24:25]
	s_add_i32 m0, s23, 0xe000
	ds_read_b128 v[154:157], v147 offset:1024
	global_load_lds_dwordx4 v138, s[24:25]
	ds_read_b128 v[158:161], v147 offset:2048
	ds_read_b128 v[162:165], v147 offset:3072
	ds_read_b128 v[166:169], v148
	ds_read_b128 v[170:173], v148 offset:1024
	ds_read_b128 v[174:177], v148 offset:2048
	ds_read_b128 v[178:181], v148 offset:3072
	ds_read_b128 v[182:185], v149
	ds_read_b128 v[186:189], v149 offset:1024
	ds_read_b128 v[190:193], v149 offset:2048
	ds_read_b128 v[194:197], v149 offset:3072
	ds_read_b128 v[198:201], v149 offset:4096
	ds_read_b128 v[202:205], v149 offset:5120
	ds_read_b128 v[206:209], v149 offset:6144
	ds_read_b128 v[210:213], v149 offset:7168
	s_waitcnt vmcnt(8)
	s_waitcnt lgkmcnt(0)
	s_barrier
	v_mfma_f32_16x16x32_bf16 v[124:127], v[150:153], v[182:185], v[124:127]
	v_mfma_f32_16x16x32_bf16 v[120:123], v[158:161], v[182:185], v[120:123]
	v_mfma_f32_16x16x32_bf16 v[108:111], v[150:153], v[190:193], v[108:111]
	v_mfma_f32_16x16x32_bf16 v[104:107], v[158:161], v[190:193], v[104:107]
	v_mfma_f32_16x16x32_bf16 v[92:95], v[150:153], v[198:201], v[92:95]
	v_mfma_f32_16x16x32_bf16 v[88:91], v[158:161], v[198:201], v[88:91]
	v_mfma_f32_16x16x32_bf16 v[76:79], v[150:153], v[206:209], v[76:79]
	v_mfma_f32_16x16x32_bf16 v[72:75], v[158:161], v[206:209], v[72:75]
	v_mfma_f32_16x16x32_bf16 v[124:127], v[154:157], v[186:189], v[124:127]
	v_mfma_f32_16x16x32_bf16 v[120:123], v[162:165], v[186:189], v[120:123]
	v_mfma_f32_16x16x32_bf16 v[108:111], v[154:157], v[194:197], v[108:111]
	v_mfma_f32_16x16x32_bf16 v[104:107], v[162:165], v[194:197], v[104:107]
	v_mfma_f32_16x16x32_bf16 v[92:95], v[154:157], v[202:205], v[92:95]
	v_mfma_f32_16x16x32_bf16 v[88:91], v[162:165], v[202:205], v[88:91]
	v_mfma_f32_16x16x32_bf16 v[76:79], v[154:157], v[210:213], v[76:79]
	v_mfma_f32_16x16x32_bf16 v[72:75], v[162:165], v[210:213], v[72:75]
	v_mfma_f32_16x16x32_bf16 v[116:119], v[166:169], v[182:185], v[116:119]
	v_mfma_f32_16x16x32_bf16 v[112:115], v[174:177], v[182:185], v[112:115]
	v_mfma_f32_16x16x32_bf16 v[100:103], v[166:169], v[190:193], v[100:103]
	v_mfma_f32_16x16x32_bf16 v[96:99], v[174:177], v[190:193], v[96:99]
	v_mfma_f32_16x16x32_bf16 v[84:87], v[166:169], v[198:201], v[84:87]
	v_mfma_f32_16x16x32_bf16 v[80:83], v[174:177], v[198:201], v[80:83]
	v_mfma_f32_16x16x32_bf16 v[68:71], v[166:169], v[206:209], v[68:71]
	v_mfma_f32_16x16x32_bf16 v[64:67], v[174:177], v[206:209], v[64:67]
	v_mfma_f32_16x16x32_bf16 v[116:119], v[170:173], v[186:189], v[116:119]
	v_mfma_f32_16x16x32_bf16 v[112:115], v[178:181], v[186:189], v[112:115]
	v_mfma_f32_16x16x32_bf16 v[100:103], v[170:173], v[194:197], v[100:103]
	v_mfma_f32_16x16x32_bf16 v[96:99], v[178:181], v[194:197], v[96:99]
	v_mfma_f32_16x16x32_bf16 v[84:87], v[170:173], v[202:205], v[84:87]
	v_mfma_f32_16x16x32_bf16 v[80:83], v[178:181], v[202:205], v[80:83]
	v_mfma_f32_16x16x32_bf16 v[68:71], v[170:173], v[210:213], v[68:71]
	v_mfma_f32_16x16x32_bf16 v[64:67], v[178:181], v[210:213], v[64:67]
	s_barrier
	s_add_u32 s98, s26, s10
	s_addc_u32 s99, s27, s11
	s_add_u32 s100, s28, s10
	s_addc_u32 s101, s29, s11
	s_add_i32 s57, s48, s34
	s_mov_b32 m0, s57
	ds_read_b128 v[182:185], v149 offset:16384
	global_load_lds_dwordx4 v132, s[26:27]
	s_add_i32 m0, s57, 0x2000
	s_add_u32 s60, s26, 0x40000
	s_addc_u32 s61, s27, 0
	s_add_i32 s57, s49, s34
	global_load_lds_dwordx4 v128, s[26:27]
	s_mov_b32 m0, s57
	ds_read_b128 v[186:189], v149 offset:17408
	global_load_lds_dwordx4 v132, s[60:61]
	s_add_i32 m0, s57, 0x2000
	ds_read_b128 v[190:193], v149 offset:18432
	global_load_lds_dwordx4 v128, s[60:61]
	s_mov_b32 m0, s23
	ds_read_b128 v[194:197], v149 offset:19456
	global_load_lds_dwordx4 v134, s[28:29]
	s_mov_b32 m0, s37
	ds_read_b128 v[198:201], v149 offset:20480
	global_load_lds_dwordx4 v130, s[28:29]
	ds_read_b128 v[202:205], v149 offset:21504
	ds_read_b128 v[206:209], v149 offset:22528
	ds_read_b128 v[210:213], v149 offset:23552
	s_waitcnt vmcnt(8)
	s_waitcnt lgkmcnt(0)
	s_barrier
	v_mfma_f32_16x16x32_bf16 v[60:63], v[150:153], v[182:185], v[60:63]
	v_mfma_f32_16x16x32_bf16 v[56:59], v[158:161], v[182:185], v[56:59]
	v_mfma_f32_16x16x32_bf16 v[44:47], v[150:153], v[190:193], v[44:47]
	v_mfma_f32_16x16x32_bf16 v[40:43], v[158:161], v[190:193], v[40:43]
	v_mfma_f32_16x16x32_bf16 v[28:31], v[150:153], v[198:201], v[28:31]
	v_mfma_f32_16x16x32_bf16 v[24:27], v[158:161], v[198:201], v[24:27]
	v_mfma_f32_16x16x32_bf16 v[12:15], v[150:153], v[206:209], v[12:15]
	v_mfma_f32_16x16x32_bf16 v[8:11], v[158:161], v[206:209], v[8:11]
	v_mfma_f32_16x16x32_bf16 v[60:63], v[154:157], v[186:189], v[60:63]
	v_mfma_f32_16x16x32_bf16 v[56:59], v[162:165], v[186:189], v[56:59]
	v_mfma_f32_16x16x32_bf16 v[44:47], v[154:157], v[194:197], v[44:47]
	v_mfma_f32_16x16x32_bf16 v[40:43], v[162:165], v[194:197], v[40:43]
	v_mfma_f32_16x16x32_bf16 v[28:31], v[154:157], v[202:205], v[28:31]
	v_mfma_f32_16x16x32_bf16 v[24:27], v[162:165], v[202:205], v[24:27]
	v_mfma_f32_16x16x32_bf16 v[12:15], v[154:157], v[210:213], v[12:15]
	v_mfma_f32_16x16x32_bf16 v[8:11], v[162:165], v[210:213], v[8:11]
	v_mfma_f32_16x16x32_bf16 v[52:55], v[166:169], v[182:185], v[52:55]
	v_mfma_f32_16x16x32_bf16 v[48:51], v[174:177], v[182:185], v[48:51]
	v_mfma_f32_16x16x32_bf16 v[36:39], v[166:169], v[190:193], v[36:39]
	v_mfma_f32_16x16x32_bf16 v[32:35], v[174:177], v[190:193], v[32:35]
	v_mfma_f32_16x16x32_bf16 v[20:23], v[166:169], v[198:201], v[20:23]
	v_mfma_f32_16x16x32_bf16 v[16:19], v[174:177], v[198:201], v[16:19]
	v_mfma_f32_16x16x32_bf16 v[4:7], v[166:169], v[206:209], v[4:7]
	v_mfma_f32_16x16x32_bf16 v[0:3], v[174:177], v[206:209], v[0:3]
	v_mfma_f32_16x16x32_bf16 v[52:55], v[170:173], v[186:189], v[52:55]
	v_mfma_f32_16x16x32_bf16 v[48:51], v[178:181], v[186:189], v[48:51]
	v_mfma_f32_16x16x32_bf16 v[36:39], v[170:173], v[194:197], v[36:39]
	v_mfma_f32_16x16x32_bf16 v[32:35], v[178:181], v[194:197], v[32:35]
	v_mfma_f32_16x16x32_bf16 v[20:23], v[170:173], v[202:205], v[20:23]
	v_mfma_f32_16x16x32_bf16 v[16:19], v[178:181], v[202:205], v[16:19]
	v_mfma_f32_16x16x32_bf16 v[4:7], v[170:173], v[210:213], v[4:7]
	v_mfma_f32_16x16x32_bf16 v[0:3], v[178:181], v[210:213], v[0:3]
	s_barrier
; #define PG8_STAGE(bufoff, gbase, voff) do { _Pragma("unroll") for (int _i = 0; _i < 2; ++_i) \
;         __builtin_amdgcn_global_load_lds((const unsigned*)((const char*)(gbase) + (voff)[_i]), (PG8_LAS unsigned*)(lds + (bufoff) + ldsw + _i * 8192), 16, 0, 0); } while (0)
; #define PG8_LDA(dst, b, h) do { _Pragma("unroll") for (int m = 0; m < 4; ++m) _Pragma("unroll") for (int k = 0; k < 2; ++k) dst[m][k] = *(const PG8_LAS bf16x8*)(lds + PG8_SA(b, h) + aoff + m * 2048 + k * 1024); } while (0)
; #define PG8_LDB(dst, b, h) do { _Pragma("unroll") for (int n = 0; n < 2; ++n) _Pragma("unroll") for (int k = 0; k < 2; ++k) dst[n][k] = *(const PG8_LAS bf16x8*)(lds + PG8_SB(b, h) + boff + n * 2048 + k * 1024); } while (0)
; #define PG8_MMA(ai, bj, At, Bt) do { __builtin_amdgcn_s_setprio(1); _Pragma("unroll") for (int m = 0; m < 4; ++m) _Pragma("unroll") for (int n = 0; n < 2; ++n) _Pragma("unroll") for (int k = 0; k < 2; ++k) \
;         acc[ai][bj][m][n] = __builtin_amdgcn_mfma_f32_16x16x32_bf16(Bt[n][k], At[m][k], acc[ai][bj][m][n], 0, 0, 0); __builtin_amdgcn_s_setprio(0); } while (0)
; #define PG8_WAIT_V(n) asm volatile("s_waitcnt vmcnt(" #n ")" ::: "memory")
; #define PG8_WAIT_L(n) asm volatile("s_waitcnt lgkmcnt(" #n ")" ::: "memory")
; #define PG8_BAR __builtin_amdgcn_s_barrier()
; #define PG8_SCHED __builtin_amdgcn_sched_barrier(0)
; template <class Epi, class Sched, bool ALIGN_EPI = false, bool SP2 = false>
; __device__ __forceinline__ void gemm_phase(PG8_LAS unsigned char* lds, const Gemm g, const Sched& S, const Epi& E, int tid_in) {
;     ...
;             PG8_LDB(B0, 1, 0); PG8_LDB(B1, 1, 1); PG8_SCHED; PG8_LDA(At, 1, 0); PG8_STAGE(PG8_SA(0, 1), a2 + hstep, voffA);
;             PG8_WAIT_V(8); PG8_WAIT_L(0); PG8_BAR; PG8_MMA(0, 0, At, B0); PG8_MMA(0, 1, At, B1); PG8_BAR; PG8_SCHED;
;             PG8_LDA(At, 1, 1); PG8_STAGE(PG8_SB(1, 0), b3, voffB); PG8_STAGE(PG8_SB(1, 1), b3 + hstep, voffB); PG8_STAGE(PG8_SA(1, 0), a3, voffA);
;             PG8_WAIT_V(8); PG8_WAIT_L(0); PG8_BAR; PG8_MMA(1, 0, At, B0); PG8_MMA(1, 1, At, B1); PG8_BAR; PG8_SCHED;
	s_add_i32 s57, 0, 0x18000
	s_add_i32 s59, 0, 0x1c000
	s_add_u32 s28, s28, 0x40000
	s_addc_u32 s29, s29, 0
	s_mov_b32 m0, s38
	s_nop 0
	global_load_lds_dwordx4 v134, s[28:29]
	s_mov_b32 m0, s39
	s_nop 0
	global_load_lds_dwordx4 v130, s[28:29]
	v_add_u32_e32 v162, s57, v145
	v_add_u32_e32 v178, s59, v145
	ds_read_b128 v[150:153], v162
	ds_read_b128 v[154:157], v162 offset:1024
	ds_read_b128 v[158:161], v162 offset:2048
	ds_read_b128 v[162:165], v162 offset:3072
	ds_read_b128 v[166:169], v178
	ds_read_b128 v[170:173], v178 offset:1024
	ds_read_b128 v[174:177], v178 offset:2048
	ds_read_b128 v[178:181], v178 offset:3072
	ds_read_b128 v[182:185], v149 offset:32768
	ds_read_b128 v[186:189], v149 offset:33792
	ds_read_b128 v[190:193], v149 offset:34816
	ds_read_b128 v[194:197], v149 offset:35840
	ds_read_b128 v[198:201], v149 offset:36864
	ds_read_b128 v[202:205], v149 offset:37888
	ds_read_b128 v[206:209], v149 offset:38912
	ds_read_b128 v[210:213], v149 offset:39936
	s_waitcnt vmcnt(8)
	s_waitcnt lgkmcnt(0)
	s_barrier
	v_mfma_f32_16x16x32_bf16 v[124:127], v[150:153], v[182:185], v[124:127]
	v_mfma_f32_16x16x32_bf16 v[120:123], v[158:161], v[182:185], v[120:123]
	v_mfma_f32_16x16x32_bf16 v[108:111], v[150:153], v[190:193], v[108:111]
	v_mfma_f32_16x16x32_bf16 v[104:107], v[158:161], v[190:193], v[104:107]
	v_mfma_f32_16x16x32_bf16 v[92:95], v[150:153], v[198:201], v[92:95]
	v_mfma_f32_16x16x32_bf16 v[88:91], v[158:161], v[198:201], v[88:91]
	v_mfma_f32_16x16x32_bf16 v[76:79], v[150:153], v[206:209], v[76:79]
	v_mfma_f32_16x16x32_bf16 v[72:75], v[158:161], v[206:209], v[72:75]
	v_mfma_f32_16x16x32_bf16 v[124:127], v[154:157], v[186:189], v[124:127]
	v_mfma_f32_16x16x32_bf16 v[120:123], v[162:165], v[186:189], v[120:123]
	v_mfma_f32_16x16x32_bf16 v[108:111], v[154:157], v[194:197], v[108:111]
	v_mfma_f32_16x16x32_bf16 v[104:107], v[162:165], v[194:197], v[104:107]
	v_mfma_f32_16x16x32_bf16 v[92:95], v[154:157], v[202:205], v[92:95]
	v_mfma_f32_16x16x32_bf16 v[88:91], v[162:165], v[202:205], v[88:91]
	v_mfma_f32_16x16x32_bf16 v[76:79], v[154:157], v[210:213], v[76:79]
	v_mfma_f32_16x16x32_bf16 v[72:75], v[162:165], v[210:213], v[72:75]
	v_mfma_f32_16x16x32_bf16 v[116:119], v[166:169], v[182:185], v[116:119]
	v_mfma_f32_16x16x32_bf16 v[112:115], v[174:177], v[182:185], v[112:115]
	v_mfma_f32_16x16x32_bf16 v[100:103], v[166:169], v[190:193], v[100:103]
	v_mfma_f32_16x16x32_bf16 v[96:99], v[174:177], v[190:193], v[96:99]
	v_mfma_f32_16x16x32_bf16 v[84:87], v[166:169], v[198:201], v[84:87]
	v_mfma_f32_16x16x32_bf16 v[80:83], v[174:177], v[198:201], v[80:83]
	v_mfma_f32_16x16x32_bf16 v[68:71], v[166:169], v[206:209], v[68:71]
	v_mfma_f32_16x16x32_bf16 v[64:67], v[174:177], v[206:209], v[64:67]
	v_mfma_f32_16x16x32_bf16 v[116:119], v[170:173], v[186:189], v[116:119]
	v_mfma_f32_16x16x32_bf16 v[112:115], v[178:181], v[186:189], v[112:115]
	v_mfma_f32_16x16x32_bf16 v[100:103], v[170:173], v[194:197], v[100:103]
	v_mfma_f32_16x16x32_bf16 v[96:99], v[178:181], v[194:197], v[96:99]
	v_mfma_f32_16x16x32_bf16 v[84:87], v[170:173], v[202:205], v[84:87]
	v_mfma_f32_16x16x32_bf16 v[80:83], v[178:181], v[202:205], v[80:83]
	v_mfma_f32_16x16x32_bf16 v[68:71], v[170:173], v[210:213], v[68:71]
	v_mfma_f32_16x16x32_bf16 v[64:67], v[178:181], v[210:213], v[64:67]
	s_barrier
	s_add_i32 s28, s57, s34
	s_mov_b32 m0, s28
	ds_read_b128 v[182:185], v149 offset:49152
	global_load_lds_dwordx4 v132, s[98:99]
	s_add_i32 m0, s28, 0x2000
	s_add_u32 s26, s26, 0x40080
	s_addc_u32 s27, s27, 0
	s_add_i32 s28, s59, s34
	global_load_lds_dwordx4 v128, s[98:99]
	s_mov_b32 m0, s28
	ds_read_b128 v[186:189], v149 offset:50176
	global_load_lds_dwordx4 v132, s[26:27]
	s_add_i32 m0, s28, 0x2000
	ds_read_b128 v[190:193], v149 offset:51200
	global_load_lds_dwordx4 v128, s[26:27]
	s_mov_b32 m0, s44
	ds_read_b128 v[194:197], v149 offset:52224
	global_load_lds_dwordx4 v134, s[100:101]
	s_mov_b32 m0, s45
	ds_read_b128 v[198:201], v149 offset:53248
	global_load_lds_dwordx4 v130, s[100:101]
	ds_read_b128 v[202:205], v149 offset:54272
	ds_read_b128 v[206:209], v149 offset:55296
	ds_read_b128 v[210:213], v149 offset:56320
	s_waitcnt vmcnt(8)
	s_waitcnt lgkmcnt(0)
	s_barrier
	v_mfma_f32_16x16x32_bf16 v[60:63], v[150:153], v[182:185], v[60:63]
	v_mfma_f32_16x16x32_bf16 v[56:59], v[158:161], v[182:185], v[56:59]
	v_mfma_f32_16x16x32_bf16 v[44:47], v[150:153], v[190:193], v[44:47]
	v_mfma_f32_16x16x32_bf16 v[40:43], v[158:161], v[190:193], v[40:43]
	v_mfma_f32_16x16x32_bf16 v[28:31], v[150:153], v[198:201], v[28:31]
	v_mfma_f32_16x16x32_bf16 v[24:27], v[158:161], v[198:201], v[24:27]
	v_mfma_f32_16x16x32_bf16 v[12:15], v[150:153], v[206:209], v[12:15]
	v_mfma_f32_16x16x32_bf16 v[8:11], v[158:161], v[206:209], v[8:11]
	v_mfma_f32_16x16x32_bf16 v[60:63], v[154:157], v[186:189], v[60:63]
	v_mfma_f32_16x16x32_bf16 v[56:59], v[162:165], v[186:189], v[56:59]
	v_mfma_f32_16x16x32_bf16 v[44:47], v[154:157], v[194:197], v[44:47]
	v_mfma_f32_16x16x32_bf16 v[40:43], v[162:165], v[194:197], v[40:43]
	v_mfma_f32_16x16x32_bf16 v[28:31], v[154:157], v[202:205], v[28:31]
	v_mfma_f32_16x16x32_bf16 v[24:27], v[162:165], v[202:205], v[24:27]
	v_mfma_f32_16x16x32_bf16 v[12:15], v[154:157], v[210:213], v[12:15]
	v_mfma_f32_16x16x32_bf16 v[8:11], v[162:165], v[210:213], v[8:11]
	v_mfma_f32_16x16x32_bf16 v[52:55], v[166:169], v[182:185], v[52:55]
	v_mfma_f32_16x16x32_bf16 v[48:51], v[174:177], v[182:185], v[48:51]
	v_mfma_f32_16x16x32_bf16 v[36:39], v[166:169], v[190:193], v[36:39]
	v_mfma_f32_16x16x32_bf16 v[32:35], v[174:177], v[190:193], v[32:35]
	v_mfma_f32_16x16x32_bf16 v[20:23], v[166:169], v[198:201], v[20:23]
	v_mfma_f32_16x16x32_bf16 v[16:19], v[174:177], v[198:201], v[16:19]
	v_mfma_f32_16x16x32_bf16 v[4:7], v[166:169], v[206:209], v[4:7]
	v_mfma_f32_16x16x32_bf16 v[0:3], v[174:177], v[206:209], v[0:3]
	v_mfma_f32_16x16x32_bf16 v[52:55], v[170:173], v[186:189], v[52:55]
	v_mfma_f32_16x16x32_bf16 v[48:51], v[178:181], v[186:189], v[48:51]
	v_mfma_f32_16x16x32_bf16 v[36:39], v[170:173], v[194:197], v[36:39]
	v_mfma_f32_16x16x32_bf16 v[32:35], v[178:181], v[194:197], v[32:35]
	v_mfma_f32_16x16x32_bf16 v[20:23], v[170:173], v[202:205], v[20:23]
	v_mfma_f32_16x16x32_bf16 v[16:19], v[178:181], v[202:205], v[16:19]
	v_mfma_f32_16x16x32_bf16 v[4:7], v[170:173], v[210:213], v[4:7]
	v_mfma_f32_16x16x32_bf16 v[0:3], v[178:181], v[210:213], v[0:3]
	s_barrier
	s_add_i32 s56, s56, 2
	s_add_u32 s24, s24, 0x100
	s_addc_u32 s25, s25, 0
	s_add_u32 s54, s54, 0x100
	s_addc_u32 s55, s55, 0
	s_cmp_gt_u32 s56, 13
	s_cbranch_scc0 .Lasym_T_376
; __device__ __forceinline__ unsigned cvt_pk_bf16(float lo, float hi) { f32x2 v = {lo, hi}; bf16x2_t b = __builtin_convertvector(v, bf16x2_t); return __builtin_bit_cast(unsigned, b); }
; __device__ __forceinline__ float silu_f(float x) { return x * fast_sigmoid(x); }
; #define PG8_BAR __builtin_amdgcn_s_barrier()
;     __device__ __forceinline__ void operator()(const f32x4 (&acc)[2][2][4][2], const Unit& u, int wr, int wc, int fr, int fq) const {
;         const int row0 = u.pm * BM + wr * 64 + fr, col0 = u.pn * HALF + wc * 32 + 8 * fq;
;         float rsv[8];
; #pragma unroll
;         for (int q8 = 0; q8 < 8; ++q8) rsv[q8] = rt ? rt[u.ord * BM + (q8 >> 2) * HALF + wr * 64 + (q8 & 3) * 16 + fr] : 1.0f;
; #pragma unroll
;         for (int ai = 0; ai < 2; ++ai)
; #pragma unroll
;             for (int m = 0; m < 4; ++m) { const int row = row0 + ai * HALF + m * 16; const float rs = rsv[ai * 4 + m];
;                 float o[8];
; #pragma unroll
;                 for (int n = 0; n < 2; ++n)
; #pragma unroll
;                     for (int i = 0; i < 4; ++i) { const float g = acc[ai][0][m][n][i] * rs, up = acc[ai][1][m][n][i] * rs; o[4 * n + i] = silu_f(g) * up; }
;                 u32x4 w; w.x = cvt_pk_bf16(o[0], o[1]); w.y = cvt_pk_bf16(o[2], o[3]); w.z = cvt_pk_bf16(o[4], o[5]); w.w = cvt_pk_bf16(o[6], o[7]);
;                 *(u32x4*)(H + (size_t)row * ldh + col0) = w; }
; template <class Epi, class Sched, bool ALIGN_EPI = false, bool SP2 = false>
; __device__ __forceinline__ void gemm_phase(PG8_LAS unsigned char* lds, const Gemm g, const Sched& S, const Epi& E, int tid_in) {
;     ...
;         if constexpr (ALIGN_EPI) { if (wr == 0) PG8_BAR; }
.Lasym_J_376:
	s_and_b64 vcc, exec, s[12:13]
	s_cbranch_vccz .LBB0_379
	s_barrier
.LBB0_379:
	v_mul_f32_e32 v150, 0xbfb8aa3b, v124
	v_mul_f32_e32 v151, 0xbfb8aa3b, v125
	v_exp_f32_e32 v150, v150
	v_exp_f32_e32 v151, v151
	v_lshl_or_b32 v154, s51, 7, v146
	v_ashrrev_i32_e32 v155, 31, v154
	v_add_f32_e32 v150, 1.0, v150
	v_add_f32_e32 v151, 1.0, v151
	v_rcp_f32_e32 v152, v150
	v_rcp_f32_e32 v153, v151
	v_mul_f32_e32 v151, 0xbfb8aa3b, v126
	v_exp_f32_e32 v151, v151
	v_lshl_add_u32 v150, s22, 8, v144
	v_pk_mul_f32 v[124:125], v[124:125], v[152:153]
	v_mul_f32_e32 v152, 0xbfb8aa3b, v127
	v_exp_f32_e32 v152, v152
	v_pk_mul_f32 v[116:117], v[124:125], v[116:117]
	v_add_f32_e32 v124, 1.0, v151
	v_mul_f32_e32 v151, 0xbfb8aa3b, v120
	v_add_f32_e32 v125, 1.0, v152
	v_rcp_f32_e32 v124, v124
	v_rcp_f32_e32 v125, v125
	v_exp_f32_e32 v151, v151
	v_mul_f32_e32 v152, 0xbfb8aa3b, v121
	v_exp_f32_e32 v152, v152
	v_pk_mul_f32 v[124:125], v[126:127], v[124:125]
	v_add_f32_e32 v126, 1.0, v151
	v_mul_f32_e32 v151, 0xbfb8aa3b, v122
	v_add_f32_e32 v127, 1.0, v152
	v_exp_f32_e32 v151, v151
	v_mul_f32_e32 v152, 0xbfb8aa3b, v123
	v_exp_f32_e32 v153, v152
	v_rcp_f32_e32 v126, v126
	v_add_f32_e32 v151, 1.0, v151
	v_rcp_f32_e32 v127, v127
	v_rcp_f32_e32 v152, v151
	v_add_f32_e32 v151, 1.0, v153
	v_rcp_f32_e32 v153, v151
	v_pk_mul_f32 v[120:121], v[120:121], v[126:127]
	v_pk_mul_f32 v[118:119], v[124:125], v[118:119]
	v_pk_mul_f32 v[112:113], v[120:121], v[112:113]
	v_pk_mul_f32 v[120:121], v[122:123], v[152:153]
	v_cvt_pk_bf16_f32 v116, v116, v117
	v_pk_mul_f32 v[114:115], v[120:121], v[114:115]
	v_cvt_pk_bf16_f32 v117, v118, v119
	v_cvt_pk_bf16_f32 v119, v114, v115
	v_mul_f32_e32 v114, 0xbfb8aa3b, v108
	v_exp_f32_e32 v114, v114
	v_mul_f32_e32 v115, 0xbfb8aa3b, v109
	v_exp_f32_e32 v115, v115
	v_cvt_pk_bf16_f32 v118, v112, v113
	v_add_f32_e32 v114, 1.0, v114
	v_mov_b64_e32 v[112:113], s[8:9]
	v_rcp_f32_e32 v122, v114
	v_add_f32_e32 v114, 1.0, v115
	v_mad_i64_i32 v[120:121], s[24:25], v150, s50, v[112:113]
	v_rcp_f32_e32 v123, v114
	v_lshlrev_b64 v[114:115], 1, v[154:155]
	v_lshl_add_u64 v[120:121], v[120:121], 0, v[114:115]
	global_store_dwordx4 v[120:121], v[116:119], off
	v_pk_mul_f32 v[108:109], v[108:109], v[122:123]
	s_andn2_b64 vcc, exec, s[2:3]
	v_mul_f32_e32 v116, 0xbfb8aa3b, v110
	v_mul_f32_e32 v117, 0xbfb8aa3b, v111
	v_exp_f32_e32 v116, v116
	v_exp_f32_e32 v117, v117
	v_pk_mul_f32 v[100:101], v[108:109], v[100:101]
	s_mov_b64 s[2:3], -1
	v_add_f32_e32 v108, 1.0, v116
	v_add_f32_e32 v109, 1.0, v117
	v_mul_f32_e32 v116, 0xbfb8aa3b, v104
	v_mul_f32_e32 v117, 0xbfb8aa3b, v105
	v_rcp_f32_e32 v108, v108
	v_rcp_f32_e32 v109, v109
	v_exp_f32_e32 v116, v116
	v_exp_f32_e32 v117, v117
	v_pk_mul_f32 v[108:109], v[110:111], v[108:109]
	v_add_f32_e32 v110, 1.0, v116
	v_add_f32_e32 v111, 1.0, v117
	v_mul_f32_e32 v116, 0xbfb8aa3b, v106
	v_mul_f32_e32 v117, 0xbfb8aa3b, v107
	v_exp_f32_e32 v116, v116
	v_exp_f32_e32 v117, v117
	v_rcp_f32_e32 v110, v110
	v_rcp_f32_e32 v111, v111
	v_add_f32_e32 v116, 1.0, v116
	v_add_f32_e32 v117, 1.0, v117
	v_rcp_f32_e32 v116, v116
	v_rcp_f32_e32 v117, v117
	v_pk_mul_f32 v[104:105], v[104:105], v[110:111]
	v_pk_mul_f32 v[102:103], v[108:109], v[102:103]
	v_pk_mul_f32 v[104:105], v[104:105], v[96:97]
	v_pk_mul_f32 v[96:97], v[106:107], v[116:117]
	v_or_b32_e32 v108, 16, v150
	v_pk_mul_f32 v[106:107], v[96:97], v[98:99]
	v_mul_f32_e32 v99, 0xbfb8aa3b, v92
	v_cvt_pk_bf16_f32 v96, v100, v101
	v_exp_f32_e32 v100, v99
	v_mul_f32_e32 v99, 0xbfb8aa3b, v93
	v_exp_f32_e32 v101, v99
	v_cvt_pk_bf16_f32 v97, v102, v103
	v_mad_i64_i32 v[102:103], s[24:25], v108, s50, v[112:113]
	v_cvt_pk_bf16_f32 v98, v104, v105
	v_cvt_pk_bf16_f32 v99, v106, v107
	v_add_f32_e32 v100, 1.0, v100
	v_add_f32_e32 v101, 1.0, v101
	v_lshl_add_u64 v[102:103], v[102:103], 0, v[114:115]
	v_rcp_f32_e32 v100, v100
	v_rcp_f32_e32 v101, v101
	global_store_dwordx4 v[102:103], v[96:99], off
	v_pk_mul_f32 v[92:93], v[92:93], v[100:101]
	s_nop 0
	v_mul_f32_e32 v96, 0xbfb8aa3b, v94
	v_mul_f32_e32 v97, 0xbfb8aa3b, v95
	v_exp_f32_e32 v96, v96
	v_exp_f32_e32 v97, v97
	v_pk_mul_f32 v[84:85], v[92:93], v[84:85]
	v_add_f32_e32 v92, 1.0, v96
	v_add_f32_e32 v93, 1.0, v97
	v_mul_f32_e32 v96, 0xbfb8aa3b, v88
	v_mul_f32_e32 v97, 0xbfb8aa3b, v89
	v_rcp_f32_e32 v92, v92
	v_rcp_f32_e32 v93, v93
	v_exp_f32_e32 v96, v96
	v_exp_f32_e32 v97, v97
	v_pk_mul_f32 v[92:93], v[94:95], v[92:93]
	v_add_f32_e32 v94, 1.0, v96
	v_add_f32_e32 v95, 1.0, v97
	v_mul_f32_e32 v96, 0xbfb8aa3b, v90
	v_mul_f32_e32 v97, 0xbfb8aa3b, v91
	v_exp_f32_e32 v96, v96
	v_exp_f32_e32 v97, v97
	v_rcp_f32_e32 v94, v94
	v_rcp_f32_e32 v95, v95
	v_add_f32_e32 v96, 1.0, v96
	v_add_f32_e32 v97, 1.0, v97
	v_rcp_f32_e32 v96, v96
	v_rcp_f32_e32 v97, v97
	v_pk_mul_f32 v[88:89], v[88:89], v[94:95]
	v_pk_mul_f32 v[86:87], v[92:93], v[86:87]
	v_pk_mul_f32 v[88:89], v[88:89], v[80:81]
	v_pk_mul_f32 v[80:81], v[90:91], v[96:97]
	v_or_b32_e32 v92, 32, v150
	v_pk_mul_f32 v[90:91], v[80:81], v[82:83]
	v_mul_f32_e32 v83, 0xbfb8aa3b, v76
	v_cvt_pk_bf16_f32 v80, v84, v85
	v_exp_f32_e32 v84, v83
	v_mul_f32_e32 v83, 0xbfb8aa3b, v77
	v_exp_f32_e32 v85, v83
	v_cvt_pk_bf16_f32 v81, v86, v87
	v_mad_i64_i32 v[86:87], s[24:25], v92, s50, v[112:113]
	v_cvt_pk_bf16_f32 v82, v88, v89
	v_cvt_pk_bf16_f32 v83, v90, v91
	v_add_f32_e32 v84, 1.0, v84
	v_add_f32_e32 v85, 1.0, v85
	v_lshl_add_u64 v[86:87], v[86:87], 0, v[114:115]
	v_rcp_f32_e32 v84, v84
	v_rcp_f32_e32 v85, v85
	global_store_dwordx4 v[86:87], v[80:83], off
	v_pk_mul_f32 v[76:77], v[76:77], v[84:85]
	s_nop 0
	v_mul_f32_e32 v80, 0xbfb8aa3b, v78
	v_mul_f32_e32 v81, 0xbfb8aa3b, v79
	v_exp_f32_e32 v80, v80
; __device__ __forceinline__ unsigned cvt_pk_bf16(float lo, float hi) { f32x2 v = {lo, hi}; bf16x2_t b = __builtin_convertvector(v, bf16x2_t); return __builtin_bit_cast(unsigned, b); }
; __device__ __forceinline__ float silu_f(float x) { return x * fast_sigmoid(x); }
;     __device__ __forceinline__ void operator()(const f32x4 (&acc)[2][2][4][2], const Unit& u, int wr, int wc, int fr, int fq) const {
;     ...
;         for (int ai = 0; ai < 2; ++ai)
; #pragma unroll
;             for (int m = 0; m < 4; ++m) { const int row = row0 + ai * HALF + m * 16; const float rs = rsv[ai * 4 + m];
;                 float o[8];
; #pragma unroll
;                 for (int n = 0; n < 2; ++n)
; #pragma unroll
;                     for (int i = 0; i < 4; ++i) { const float g = acc[ai][0][m][n][i] * rs, up = acc[ai][1][m][n][i] * rs; o[4 * n + i] = silu_f(g) * up; }
;                 u32x4 w; w.x = cvt_pk_bf16(o[0], o[1]); w.y = cvt_pk_bf16(o[2], o[3]); w.z = cvt_pk_bf16(o[4], o[5]); w.w = cvt_pk_bf16(o[6], o[7]);
;                 *(u32x4*)(H + (size_t)row * ldh + col0) = w; }
	v_exp_f32_e32 v81, v81
	v_pk_mul_f32 v[68:69], v[76:77], v[68:69]
	v_add_f32_e32 v76, 1.0, v80
	v_add_f32_e32 v77, 1.0, v81
	v_mul_f32_e32 v80, 0xbfb8aa3b, v72
	v_mul_f32_e32 v81, 0xbfb8aa3b, v73
	v_rcp_f32_e32 v76, v76
	v_rcp_f32_e32 v77, v77
	v_exp_f32_e32 v80, v80
	v_exp_f32_e32 v81, v81
	v_pk_mul_f32 v[76:77], v[78:79], v[76:77]
	v_add_f32_e32 v78, 1.0, v80
	v_add_f32_e32 v79, 1.0, v81
	v_mul_f32_e32 v80, 0xbfb8aa3b, v74
	v_mul_f32_e32 v81, 0xbfb8aa3b, v75
	v_exp_f32_e32 v80, v80
	v_exp_f32_e32 v81, v81
	v_rcp_f32_e32 v78, v78
	v_rcp_f32_e32 v79, v79
	v_add_f32_e32 v80, 1.0, v80
	v_add_f32_e32 v81, 1.0, v81
	v_rcp_f32_e32 v80, v80
	v_rcp_f32_e32 v81, v81
	v_pk_mul_f32 v[72:73], v[72:73], v[78:79]
	v_pk_mul_f32 v[70:71], v[76:77], v[70:71]
	v_pk_mul_f32 v[72:73], v[72:73], v[64:65]
	v_pk_mul_f32 v[64:65], v[74:75], v[80:81]
	v_or_b32_e32 v76, 48, v150
	v_pk_mul_f32 v[74:75], v[64:65], v[66:67]
	v_cvt_pk_bf16_f32 v64, v68, v69
	v_mul_f32_e32 v68, 0xbfb8aa3b, v60
	v_cvt_pk_bf16_f32 v65, v70, v71
	v_exp_f32_e32 v70, v68
	v_mul_f32_e32 v68, 0xbfb8aa3b, v61
	v_exp_f32_e32 v71, v68
	v_mad_i64_i32 v[68:69], s[24:25], v76, s50, v[112:113]
	v_cvt_pk_bf16_f32 v66, v72, v73
	v_cvt_pk_bf16_f32 v67, v74, v75
	v_add_f32_e32 v70, 1.0, v70
	v_add_f32_e32 v71, 1.0, v71
	v_lshl_add_u64 v[68:69], v[68:69], 0, v[114:115]
	v_rcp_f32_e32 v70, v70
	v_rcp_f32_e32 v71, v71
	global_store_dwordx4 v[68:69], v[64:67], off
	v_pk_mul_f32 v[60:61], v[60:61], v[70:71]
	s_nop 0
	v_mul_f32_e32 v64, 0xbfb8aa3b, v62
	v_mul_f32_e32 v65, 0xbfb8aa3b, v63
	v_exp_f32_e32 v64, v64
	v_exp_f32_e32 v65, v65
	v_pk_mul_f32 v[52:53], v[60:61], v[52:53]
	v_add_u32_e32 v66, 0x80, v150
	v_add_f32_e32 v60, 1.0, v64
	v_add_f32_e32 v61, 1.0, v65
	v_mul_f32_e32 v64, 0xbfb8aa3b, v56
	v_mul_f32_e32 v65, 0xbfb8aa3b, v57
	v_rcp_f32_e32 v60, v60
	v_rcp_f32_e32 v61, v61
	v_exp_f32_e32 v64, v64
	v_exp_f32_e32 v65, v65
	v_pk_mul_f32 v[60:61], v[62:63], v[60:61]
	v_add_f32_e32 v62, 1.0, v64
	v_add_f32_e32 v63, 1.0, v65
	v_mul_f32_e32 v64, 0xbfb8aa3b, v58
	v_mul_f32_e32 v65, 0xbfb8aa3b, v59
	v_exp_f32_e32 v64, v64
	v_exp_f32_e32 v65, v65
	v_rcp_f32_e32 v62, v62
	v_rcp_f32_e32 v63, v63
	v_add_f32_e32 v64, 1.0, v64
	v_add_f32_e32 v65, 1.0, v65
	v_rcp_f32_e32 v64, v64
	v_rcp_f32_e32 v65, v65
	v_pk_mul_f32 v[56:57], v[56:57], v[62:63]
	v_pk_mul_f32 v[54:55], v[60:61], v[54:55]
	v_pk_mul_f32 v[56:57], v[56:57], v[48:49]
	v_pk_mul_f32 v[48:49], v[58:59], v[64:65]
	s_nop 0
	v_pk_mul_f32 v[58:59], v[48:49], v[50:51]
	v_mul_f32_e32 v51, 0xbfb8aa3b, v44
	v_cvt_pk_bf16_f32 v48, v52, v53
	v_exp_f32_e32 v52, v51
	v_mul_f32_e32 v51, 0xbfb8aa3b, v45
	v_exp_f32_e32 v53, v51
	v_cvt_pk_bf16_f32 v49, v54, v55
	v_mad_i64_i32 v[54:55], s[24:25], v66, s50, v[112:113]
	v_cvt_pk_bf16_f32 v50, v56, v57
	v_cvt_pk_bf16_f32 v51, v58, v59
	v_add_f32_e32 v52, 1.0, v52
	v_add_f32_e32 v53, 1.0, v53
	v_lshl_add_u64 v[54:55], v[54:55], 0, v[114:115]
	v_rcp_f32_e32 v52, v52
	v_rcp_f32_e32 v53, v53
	global_store_dwordx4 v[54:55], v[48:51], off
	v_pk_mul_f32 v[44:45], v[44:45], v[52:53]
	s_nop 0
	v_mul_f32_e32 v48, 0xbfb8aa3b, v46
	v_mul_f32_e32 v49, 0xbfb8aa3b, v47
	v_exp_f32_e32 v48, v48
	v_exp_f32_e32 v49, v49
	v_pk_mul_f32 v[36:37], v[44:45], v[36:37]
	v_add_f32_e32 v44, 1.0, v48
	v_add_f32_e32 v45, 1.0, v49
	v_mul_f32_e32 v48, 0xbfb8aa3b, v40
	v_mul_f32_e32 v49, 0xbfb8aa3b, v41
	v_rcp_f32_e32 v44, v44
	v_rcp_f32_e32 v45, v45
	v_exp_f32_e32 v48, v48
	v_exp_f32_e32 v49, v49
	v_pk_mul_f32 v[44:45], v[46:47], v[44:45]
	v_add_f32_e32 v46, 1.0, v48
	v_add_f32_e32 v47, 1.0, v49
	v_mul_f32_e32 v48, 0xbfb8aa3b, v42
	v_mul_f32_e32 v49, 0xbfb8aa3b, v43
	v_exp_f32_e32 v48, v48
	v_exp_f32_e32 v49, v49
	v_rcp_f32_e32 v46, v46
	v_rcp_f32_e32 v47, v47
	v_add_f32_e32 v48, 1.0, v48
	v_add_f32_e32 v49, 1.0, v49
; __device__ __forceinline__ unsigned cvt_pk_bf16(float lo, float hi) { f32x2 v = {lo, hi}; bf16x2_t b = __builtin_convertvector(v, bf16x2_t); return __builtin_bit_cast(unsigned, b); }
; __device__ __forceinline__ float silu_f(float x) { return x * fast_sigmoid(x); }
;     __device__ __forceinline__ void operator()(const f32x4 (&acc)[2][2][4][2], const Unit& u, int wr, int wc, int fr, int fq) const {
;     ...
;         for (int ai = 0; ai < 2; ++ai)
; #pragma unroll
;             for (int m = 0; m < 4; ++m) { const int row = row0 + ai * HALF + m * 16; const float rs = rsv[ai * 4 + m];
;                 float o[8];
; #pragma unroll
;                 for (int n = 0; n < 2; ++n)
; #pragma unroll
;                     for (int i = 0; i < 4; ++i) { const float g = acc[ai][0][m][n][i] * rs, up = acc[ai][1][m][n][i] * rs; o[4 * n + i] = silu_f(g) * up; }
;                 u32x4 w; w.x = cvt_pk_bf16(o[0], o[1]); w.y = cvt_pk_bf16(o[2], o[3]); w.z = cvt_pk_bf16(o[4], o[5]); w.w = cvt_pk_bf16(o[6], o[7]);
;                 *(u32x4*)(H + (size_t)row * ldh + col0) = w; }
	v_rcp_f32_e32 v48, v48
	v_rcp_f32_e32 v49, v49
	v_pk_mul_f32 v[40:41], v[40:41], v[46:47]
	v_pk_mul_f32 v[38:39], v[44:45], v[38:39]
	v_pk_mul_f32 v[40:41], v[40:41], v[32:33]
	v_pk_mul_f32 v[32:33], v[42:43], v[48:49]
	v_add_u32_e32 v44, 0x90, v150
	v_pk_mul_f32 v[42:43], v[32:33], v[34:35]
	v_mul_f32_e32 v35, 0xbfb8aa3b, v28
	v_cvt_pk_bf16_f32 v32, v36, v37
	v_exp_f32_e32 v36, v35
	v_mul_f32_e32 v35, 0xbfb8aa3b, v29
	v_exp_f32_e32 v37, v35
	v_cvt_pk_bf16_f32 v33, v38, v39
	v_mad_i64_i32 v[38:39], s[24:25], v44, s50, v[112:113]
	v_cvt_pk_bf16_f32 v34, v40, v41
	v_cvt_pk_bf16_f32 v35, v42, v43
	v_add_f32_e32 v36, 1.0, v36
	v_add_f32_e32 v37, 1.0, v37
	v_lshl_add_u64 v[38:39], v[38:39], 0, v[114:115]
	v_rcp_f32_e32 v36, v36
	v_rcp_f32_e32 v37, v37
	global_store_dwordx4 v[38:39], v[32:35], off
	v_pk_mul_f32 v[28:29], v[28:29], v[36:37]
	s_nop 0
	v_mul_f32_e32 v32, 0xbfb8aa3b, v30
	v_mul_f32_e32 v33, 0xbfb8aa3b, v31
	v_exp_f32_e32 v32, v32
	v_exp_f32_e32 v33, v33
	v_pk_mul_f32 v[20:21], v[28:29], v[20:21]
	v_add_f32_e32 v28, 1.0, v32
	v_add_f32_e32 v29, 1.0, v33
	v_mul_f32_e32 v32, 0xbfb8aa3b, v24
	v_mul_f32_e32 v33, 0xbfb8aa3b, v25
	v_rcp_f32_e32 v28, v28
	v_rcp_f32_e32 v29, v29
	v_exp_f32_e32 v32, v32
	v_exp_f32_e32 v33, v33
	v_pk_mul_f32 v[28:29], v[30:31], v[28:29]
	v_add_f32_e32 v30, 1.0, v32
	v_add_f32_e32 v31, 1.0, v33
	v_mul_f32_e32 v32, 0xbfb8aa3b, v26
	v_mul_f32_e32 v33, 0xbfb8aa3b, v27
	v_exp_f32_e32 v32, v32
	v_exp_f32_e32 v33, v33
	v_rcp_f32_e32 v30, v30
	v_rcp_f32_e32 v31, v31
	v_add_f32_e32 v32, 1.0, v32
	v_add_f32_e32 v33, 1.0, v33
	v_rcp_f32_e32 v32, v32
	v_rcp_f32_e32 v33, v33
	v_pk_mul_f32 v[24:25], v[24:25], v[30:31]
	v_pk_mul_f32 v[22:23], v[28:29], v[22:23]
	v_pk_mul_f32 v[24:25], v[24:25], v[16:17]
	v_pk_mul_f32 v[16:17], v[26:27], v[32:33]
	v_add_u32_e32 v28, 0xa0, v150
	v_pk_mul_f32 v[26:27], v[16:17], v[18:19]
	v_mul_f32_e32 v19, 0xbfb8aa3b, v12
	v_cvt_pk_bf16_f32 v16, v20, v21
	v_exp_f32_e32 v20, v19
	v_mul_f32_e32 v19, 0xbfb8aa3b, v13
	v_exp_f32_e32 v21, v19
	v_cvt_pk_bf16_f32 v17, v22, v23
	v_mad_i64_i32 v[22:23], s[24:25], v28, s50, v[112:113]
	v_cvt_pk_bf16_f32 v18, v24, v25
	v_cvt_pk_bf16_f32 v19, v26, v27
	v_add_f32_e32 v20, 1.0, v20
	v_add_f32_e32 v21, 1.0, v21
	v_lshl_add_u64 v[22:23], v[22:23], 0, v[114:115]
	v_rcp_f32_e32 v20, v20
	v_rcp_f32_e32 v21, v21
	global_store_dwordx4 v[22:23], v[16:19], off
	v_pk_mul_f32 v[12:13], v[12:13], v[20:21]
	s_nop 0
	v_mul_f32_e32 v16, 0xbfb8aa3b, v14
	v_mul_f32_e32 v17, 0xbfb8aa3b, v15
	v_exp_f32_e32 v16, v16
	v_exp_f32_e32 v17, v17
	v_pk_mul_f32 v[4:5], v[12:13], v[4:5]
	v_add_f32_e32 v12, 1.0, v16
	v_add_f32_e32 v13, 1.0, v17
	v_mul_f32_e32 v16, 0xbfb8aa3b, v8
	v_mul_f32_e32 v17, 0xbfb8aa3b, v9
	v_rcp_f32_e32 v12, v12
	v_rcp_f32_e32 v13, v13
	v_exp_f32_e32 v16, v16
	v_exp_f32_e32 v17, v17
	v_pk_mul_f32 v[12:13], v[14:15], v[12:13]
	v_add_f32_e32 v14, 1.0, v16
	v_add_f32_e32 v15, 1.0, v17
	v_mul_f32_e32 v16, 0xbfb8aa3b, v10
	v_mul_f32_e32 v17, 0xbfb8aa3b, v11
	v_exp_f32_e32 v16, v16
	v_exp_f32_e32 v17, v17
	v_rcp_f32_e32 v14, v14
	v_rcp_f32_e32 v15, v15
	v_add_f32_e32 v16, 1.0, v16
	v_add_f32_e32 v17, 1.0, v17
	v_rcp_f32_e32 v16, v16
	v_rcp_f32_e32 v17, v17
	v_pk_mul_f32 v[8:9], v[8:9], v[14:15]
	v_pk_mul_f32 v[6:7], v[12:13], v[6:7]
	v_pk_mul_f32 v[8:9], v[8:9], v[0:1]
	v_pk_mul_f32 v[0:1], v[10:11], v[16:17]
	v_add_u32_e32 v12, 0xb0, v150
	v_pk_mul_f32 v[10:11], v[0:1], v[2:3]
	v_cvt_pk_bf16_f32 v0, v4, v5
	v_mad_i64_i32 v[4:5], s[24:25], v12, s50, v[112:113]
	v_cvt_pk_bf16_f32 v1, v6, v7
	v_cvt_pk_bf16_f32 v2, v8, v9
	v_cvt_pk_bf16_f32 v3, v10, v11
	v_lshl_add_u64 v[4:5], v[4:5], 0, v[114:115]
	global_store_dwordx4 v[4:5], v[0:3], off
	s_cbranch_vccnz .LBB0_372
	s_andn2_b64 vcc, exec, s[6:7]
	s_cbranch_vccnz .LBB0_371
	s_barrier
	s_branch .LBB0_371

; #define PG8_STAGE(bufoff, gbase, voff) do { _Pragma("unroll") for (int _i = 0; _i < 2; ++_i) \
;         __builtin_amdgcn_global_load_lds((const unsigned*)((const char*)(gbase) + (voff)[_i]), (PG8_LAS unsigned*)(lds + (bufoff) + ldsw + _i * 8192), 16, 0, 0); } while (0)
; #define PG8_LDA(dst, b, h) do { _Pragma("unroll") for (int m = 0; m < 4; ++m) _Pragma("unroll") for (int k = 0; k < 2; ++k) dst[m][k] = *(const PG8_LAS bf16x8*)(lds + PG8_SA(b, h) + aoff + m * 2048 + k * 1024); } while (0)
; #define PG8_LDB(dst, b, h) do { _Pragma("unroll") for (int n = 0; n < 2; ++n) _Pragma("unroll") for (int k = 0; k < 2; ++k) dst[n][k] = *(const PG8_LAS bf16x8*)(lds + PG8_SB(b, h) + boff + n * 2048 + k * 1024); } while (0)
; #define PG8_MMA(ai, bj, At, Bt) do { __builtin_amdgcn_s_setprio(1); _Pragma("unroll") for (int m = 0; m < 4; ++m) _Pragma("unroll") for (int n = 0; n < 2; ++n) _Pragma("unroll") for (int k = 0; k < 2; ++k) \
;         acc[ai][bj][m][n] = __builtin_amdgcn_mfma_f32_16x16x32_bf16(Bt[n][k], At[m][k], acc[ai][bj][m][n], 0, 0, 0); __builtin_amdgcn_s_setprio(0); } while (0)
; #define PG8_WAIT_V(n) asm volatile("s_waitcnt vmcnt(" #n ")" ::: "memory")
; #define PG8_WAIT_L(n) asm volatile("s_waitcnt lgkmcnt(" #n ")" ::: "memory")
; template <class Epi, class Sched, bool ALIGN_EPI = false, bool SP2 = false>
; __device__ __forceinline__ void gemm_phase(PG8_LAS unsigned char* lds, const Gemm g, const Sched& S, const Epi& E, int tid_in) {
;     ...
;             const bool last = (t == nt - 2);
;             const char* a1 = cA + (size_t)(t + 1) * kstep;
;             const char* a2 = last ? nA : cA + (size_t)(t + 2) * kstep; const char* b2 = last ? nB : cB + (size_t)(t + 2) * kstep;
;             const char* a3 = a2 + kstep; const char* b3 = b2 + kstep;
;             if (last && has_next) S.a_ready(nxt);
;             if constexpr (SP2) {
;             PG8_LDB(B0, 0, 0); PG8_LDB(B1, 0, 1); PG8_SCHED; PG8_LDA(At, 0, 0); PG8_STAGE(PG8_SA(1, 1), a1 + hstep, voffA);
;             PG8_WAIT_V(8); PG8_WAIT_L(0); PG8_BAR; PG8_MMA(0, 0, At, B0); PG8_MMA(0, 1, At, B1); PG8_BAR; PG8_SCHED;
;     ...
;         for (int a = 0; a < 2; ++a)
; #pragma unroll
;             for (int b = 0; b < 2; ++b)
; #pragma unroll
;                 for (int m = 0; m < 4; ++m)
; #pragma unroll
;                     for (int n = 0; n < 2; ++n) acc[a][b][m][n] = (f32x4){0.f, 0.f, 0.f, 0.f};
.LBB0_460:
	s_add_u32 s12, s50, 0x100
	v_mov_b32_e32 v0, 0
	s_addc_u32 s75, s51, 0
	s_mov_b32 s76, -2
	s_waitcnt lgkmcnt(0)
	v_mov_b32_e32 v1, v0
	v_mov_b32_e32 v2, v0
	v_mov_b32_e32 v3, v0
	v_mov_b32_e32 v4, v0
	v_mov_b32_e32 v5, v0
	v_mov_b32_e32 v6, v0
	v_mov_b32_e32 v7, v0
	v_mov_b32_e32 v16, v0
	v_mov_b32_e32 v17, v0
	v_mov_b32_e32 v18, v0
	v_mov_b32_e32 v19, v0
	v_mov_b32_e32 v20, v0
	v_mov_b32_e32 v21, v0
	v_mov_b32_e32 v22, v0
	v_mov_b32_e32 v23, v0
	v_mov_b32_e32 v32, v0
	v_mov_b32_e32 v33, v0
	v_mov_b32_e32 v34, v0
	v_mov_b32_e32 v35, v0
	v_mov_b32_e32 v36, v0
	v_mov_b32_e32 v37, v0
	v_mov_b32_e32 v38, v0
	v_mov_b32_e32 v39, v0
	v_mov_b32_e32 v48, v0
	v_mov_b32_e32 v49, v0
	v_mov_b32_e32 v50, v0
	v_mov_b32_e32 v51, v0
	v_mov_b32_e32 v52, v0
	v_mov_b32_e32 v53, v0
	v_mov_b32_e32 v54, v0
	v_mov_b32_e32 v55, v0
	v_mov_b32_e32 v8, v0
	v_mov_b32_e32 v9, v0
	v_mov_b32_e32 v10, v0
	v_mov_b32_e32 v11, v0
	v_mov_b32_e32 v12, v0
	v_mov_b32_e32 v13, v0
	v_mov_b32_e32 v14, v0
	v_mov_b32_e32 v15, v0
	v_mov_b32_e32 v24, v0
	v_mov_b32_e32 v25, v0
	v_mov_b32_e32 v26, v0
	v_mov_b32_e32 v27, v0
	v_mov_b32_e32 v28, v0
	v_mov_b32_e32 v29, v0
	v_mov_b32_e32 v30, v0
	v_mov_b32_e32 v31, v0
	v_mov_b32_e32 v40, v0
	v_mov_b32_e32 v41, v0
	v_mov_b32_e32 v42, v0
	v_mov_b32_e32 v43, v0
	v_mov_b32_e32 v44, v0
	v_mov_b32_e32 v45, v0
	v_mov_b32_e32 v46, v0
	v_mov_b32_e32 v47, v0
	v_mov_b32_e32 v56, v0
	v_mov_b32_e32 v57, v0
	v_mov_b32_e32 v58, v0
	v_mov_b32_e32 v59, v0
	v_mov_b32_e32 v60, v0
	v_mov_b32_e32 v61, v0
	v_mov_b32_e32 v62, v0
	v_mov_b32_e32 v63, v0
	v_mov_b32_e32 v64, v0
	v_mov_b32_e32 v65, v0
	v_mov_b32_e32 v66, v0
	v_mov_b32_e32 v67, v0
	v_mov_b32_e32 v68, v0
	v_mov_b32_e32 v69, v0
	v_mov_b32_e32 v70, v0
	v_mov_b32_e32 v71, v0
	v_mov_b32_e32 v80, v0
	v_mov_b32_e32 v81, v0
	v_mov_b32_e32 v82, v0
	v_mov_b32_e32 v83, v0
	v_mov_b32_e32 v84, v0
	v_mov_b32_e32 v85, v0
	v_mov_b32_e32 v86, v0
	v_mov_b32_e32 v87, v0
	v_mov_b32_e32 v96, v0
	v_mov_b32_e32 v97, v0
	v_mov_b32_e32 v98, v0
	v_mov_b32_e32 v99, v0
	v_mov_b32_e32 v100, v0
	v_mov_b32_e32 v101, v0
	v_mov_b32_e32 v102, v0
	v_mov_b32_e32 v103, v0
	v_mov_b32_e32 v112, v0
	v_mov_b32_e32 v113, v0
	v_mov_b32_e32 v114, v0
	v_mov_b32_e32 v115, v0
	v_mov_b32_e32 v116, v0
	v_mov_b32_e32 v117, v0
	v_mov_b32_e32 v118, v0
	v_mov_b32_e32 v119, v0
	v_mov_b32_e32 v72, v0
	v_mov_b32_e32 v73, v0
	v_mov_b32_e32 v74, v0
	v_mov_b32_e32 v75, v0
	v_mov_b32_e32 v76, v0
	v_mov_b32_e32 v77, v0
	v_mov_b32_e32 v78, v0
	v_mov_b32_e32 v79, v0
	v_mov_b32_e32 v88, v0
	v_mov_b32_e32 v89, v0
	v_mov_b32_e32 v90, v0
	v_mov_b32_e32 v91, v0
	v_mov_b32_e32 v92, v0
	v_mov_b32_e32 v93, v0
	v_mov_b32_e32 v94, v0
	v_mov_b32_e32 v95, v0
	v_mov_b32_e32 v104, v0
	v_mov_b32_e32 v105, v0
	v_mov_b32_e32 v106, v0
	v_mov_b32_e32 v107, v0
	v_mov_b32_e32 v108, v0
	v_mov_b32_e32 v109, v0
	v_mov_b32_e32 v110, v0
	v_mov_b32_e32 v111, v0
	v_mov_b32_e32 v120, v0
	v_mov_b32_e32 v121, v0
	v_mov_b32_e32 v122, v0
	v_mov_b32_e32 v123, v0
	v_mov_b32_e32 v124, v0
	v_mov_b32_e32 v125, v0
	v_mov_b32_e32 v126, v0
	v_mov_b32_e32 v127, v0
	s_cmp_lg_u64 s[24:25], 0
	s_cbranch_scc0 .Lasym_T_461
.LBB0_461:
	s_add_u32 s6, s48, 0x100
	s_addc_u32 s7, s49, 0
	s_cmp_eq_u32 s76, 40
	s_cselect_b32 s53, s45, s7
	s_cselect_b32 s52, s44, s6
	s_cselect_b32 s51, s47, s75
	s_cselect_b32 s50, s46, s12
	s_add_i32 m0, s60, 0xc000
	ds_read_b128 v[128:131], v236
	global_load_lds_dwordx4 v200, s[48:49]
	s_add_i32 m0, s60, 0xe000
	ds_read_b128 v[132:135], v236 offset:1024
	global_load_lds_dwordx4 v202, s[48:49]
	ds_read_b128 v[136:139], v236 offset:2048
	ds_read_b128 v[140:143], v236 offset:3072
	ds_read_b128 v[144:147], v237
	ds_read_b128 v[148:151], v237 offset:1024
	ds_read_b128 v[152:155], v237 offset:2048
	ds_read_b128 v[156:159], v237 offset:3072
	ds_read_b128 v[160:163], v238
	ds_read_b128 v[164:167], v238 offset:1024
	ds_read_b128 v[168:171], v238 offset:2048
	ds_read_b128 v[172:175], v238 offset:3072
	ds_read_b128 v[176:179], v238 offset:4096
	ds_read_b128 v[180:183], v238 offset:5120
	ds_read_b128 v[184:187], v238 offset:6144
	ds_read_b128 v[188:191], v238 offset:7168
	s_waitcnt lgkmcnt(0)
	s_barrier
	v_mfma_f32_16x16x32_bf16 v[124:127], v[128:131], v[160:163], v[124:127]
	v_mfma_f32_16x16x32_bf16 v[120:123], v[136:139], v[160:163], v[120:123]
	v_mfma_f32_16x16x32_bf16 v[108:111], v[128:131], v[168:171], v[108:111]
	v_mfma_f32_16x16x32_bf16 v[104:107], v[136:139], v[168:171], v[104:107]
	v_mfma_f32_16x16x32_bf16 v[92:95], v[128:131], v[176:179], v[92:95]
	v_mfma_f32_16x16x32_bf16 v[88:91], v[136:139], v[176:179], v[88:91]
	v_mfma_f32_16x16x32_bf16 v[76:79], v[128:131], v[184:187], v[76:79]
	v_mfma_f32_16x16x32_bf16 v[72:75], v[136:139], v[184:187], v[72:75]
	v_mfma_f32_16x16x32_bf16 v[124:127], v[132:135], v[164:167], v[124:127]
	v_mfma_f32_16x16x32_bf16 v[120:123], v[140:143], v[164:167], v[120:123]
	v_mfma_f32_16x16x32_bf16 v[108:111], v[132:135], v[172:175], v[108:111]
	v_mfma_f32_16x16x32_bf16 v[104:107], v[140:143], v[172:175], v[104:107]
	v_mfma_f32_16x16x32_bf16 v[92:95], v[132:135], v[180:183], v[92:95]
	v_mfma_f32_16x16x32_bf16 v[88:91], v[140:143], v[180:183], v[88:91]
	v_mfma_f32_16x16x32_bf16 v[76:79], v[132:135], v[188:191], v[76:79]
	v_mfma_f32_16x16x32_bf16 v[72:75], v[140:143], v[188:191], v[72:75]
	v_mfma_f32_16x16x32_bf16 v[116:119], v[144:147], v[160:163], v[116:119]
	v_mfma_f32_16x16x32_bf16 v[112:115], v[152:155], v[160:163], v[112:115]
	v_mfma_f32_16x16x32_bf16 v[100:103], v[144:147], v[168:171], v[100:103]
	v_mfma_f32_16x16x32_bf16 v[96:99], v[152:155], v[168:171], v[96:99]
	v_mfma_f32_16x16x32_bf16 v[84:87], v[144:147], v[176:179], v[84:87]
	v_mfma_f32_16x16x32_bf16 v[80:83], v[152:155], v[176:179], v[80:83]
	v_mfma_f32_16x16x32_bf16 v[68:71], v[144:147], v[184:187], v[68:71]
	v_mfma_f32_16x16x32_bf16 v[64:67], v[152:155], v[184:187], v[64:67]
	v_mfma_f32_16x16x32_bf16 v[116:119], v[148:151], v[164:167], v[116:119]
	v_mfma_f32_16x16x32_bf16 v[112:115], v[156:159], v[164:167], v[112:115]
	v_mfma_f32_16x16x32_bf16 v[100:103], v[148:151], v[172:175], v[100:103]
	v_mfma_f32_16x16x32_bf16 v[96:99], v[156:159], v[172:175], v[96:99]
	v_mfma_f32_16x16x32_bf16 v[84:87], v[148:151], v[180:183], v[84:87]
	v_mfma_f32_16x16x32_bf16 v[80:83], v[156:159], v[180:183], v[80:83]
	v_mfma_f32_16x16x32_bf16 v[68:71], v[148:151], v[188:191], v[68:71]
	v_mfma_f32_16x16x32_bf16 v[64:67], v[156:159], v[188:191], v[64:67]
	s_waitcnt vmcnt(8)
	s_barrier
; #define PG8_STAGE(bufoff, gbase, voff) do { _Pragma("unroll") for (int _i = 0; _i < 2; ++_i) \
;         __builtin_amdgcn_global_load_lds((const unsigned*)((const char*)(gbase) + (voff)[_i]), (PG8_LAS unsigned*)(lds + (bufoff) + ldsw + _i * 8192), 16, 0, 0); } while (0)
; #define PG8_LDA(dst, b, h) do { _Pragma("unroll") for (int m = 0; m < 4; ++m) _Pragma("unroll") for (int k = 0; k < 2; ++k) dst[m][k] = *(const PG8_LAS bf16x8*)(lds + PG8_SA(b, h) + aoff + m * 2048 + k * 1024); } while (0)
; #define PG8_LDB(dst, b, h) do { _Pragma("unroll") for (int n = 0; n < 2; ++n) _Pragma("unroll") for (int k = 0; k < 2; ++k) dst[n][k] = *(const PG8_LAS bf16x8*)(lds + PG8_SB(b, h) + boff + n * 2048 + k * 1024); } while (0)
; #define PG8_MMA(ai, bj, At, Bt) do { __builtin_amdgcn_s_setprio(1); _Pragma("unroll") for (int m = 0; m < 4; ++m) _Pragma("unroll") for (int n = 0; n < 2; ++n) _Pragma("unroll") for (int k = 0; k < 2; ++k) \
;         acc[ai][bj][m][n] = __builtin_amdgcn_mfma_f32_16x16x32_bf16(Bt[n][k], At[m][k], acc[ai][bj][m][n], 0, 0, 0); __builtin_amdgcn_s_setprio(0); } while (0)
; #define PG8_WAIT_V(n) asm volatile("s_waitcnt vmcnt(" #n ")" ::: "memory")
; #define PG8_WAIT_L(n) asm volatile("s_waitcnt lgkmcnt(" #n ")" ::: "memory")
; #define PG8_BAR __builtin_amdgcn_s_barrier()
; #define PG8_SCHED __builtin_amdgcn_sched_barrier(0)
; template <class Epi, class Sched, bool ALIGN_EPI = false, bool SP2 = false>
; __device__ __forceinline__ void gemm_phase(PG8_LAS unsigned char* lds, const Gemm g, const Sched& S, const Epi& E, int tid_in) {
;     ...
;             PG8_WAIT_V(8); PG8_WAIT_L(0); PG8_BAR; PG8_MMA(0, 0, At, B0); PG8_MMA(0, 1, At, B1); PG8_BAR; PG8_SCHED;
;             PG8_LDA(At, 0, 1); PG8_STAGE(PG8_SB(0, 0), b2, voffB); PG8_STAGE(PG8_SB(0, 1), b2 + hstep, voffB); PG8_STAGE(PG8_SA(0, 0), a2, voffA);
;             PG8_WAIT_V(8); PG8_WAIT_L(0); PG8_BAR; PG8_MMA(1, 0, At, B0); PG8_MMA(1, 1, At, B1); PG8_BAR; PG8_SCHED;
;             PG8_LDB(B0, 1, 0); PG8_LDB(B1, 1, 1); PG8_SCHED; PG8_LDA(At, 1, 0); PG8_STAGE(PG8_SA(0, 1), a2 + hstep, voffA);
;             PG8_WAIT_V(8); PG8_WAIT_L(0); PG8_BAR; PG8_MMA(0, 0, At, B0); PG8_MMA(0, 1, At, B1); PG8_BAR; PG8_SCHED;
	s_add_u32 s98, s50, s22
	s_addc_u32 s99, s51, s23
	s_add_u32 s100, s52, s22
	s_addc_u32 s101, s53, s23
	s_add_i32 s48, s70, s59
	s_mov_b32 m0, s48
	ds_read_b128 v[160:163], v238 offset:16384
	global_load_lds_dwordx4 v194, s[50:51]
	s_add_i32 m0, s48, 0x2000
	s_add_u32 s48, s50, 0xb0000
	s_addc_u32 s49, s51, 0
	s_add_i32 s77, s71, s59
	global_load_lds_dwordx4 v198, s[50:51]
	s_mov_b32 m0, s77
	ds_read_b128 v[164:167], v238 offset:17408
	global_load_lds_dwordx4 v194, s[48:49]
	s_add_i32 m0, s77, 0x2000
	ds_read_b128 v[168:171], v238 offset:18432
	global_load_lds_dwordx4 v198, s[48:49]
	s_mov_b32 m0, s60
	ds_read_b128 v[172:175], v238 offset:19456
	global_load_lds_dwordx4 v192, s[52:53]
	s_mov_b32 m0, s61
	ds_read_b128 v[176:179], v238 offset:20480
	global_load_lds_dwordx4 v196, s[52:53]
	ds_read_b128 v[180:183], v238 offset:21504
	ds_read_b128 v[184:187], v238 offset:22528
	ds_read_b128 v[188:191], v238 offset:23552
	s_waitcnt lgkmcnt(0)
	s_barrier
	v_mfma_f32_16x16x32_bf16 v[60:63], v[128:131], v[160:163], v[60:63]
	v_mfma_f32_16x16x32_bf16 v[56:59], v[136:139], v[160:163], v[56:59]
	v_mfma_f32_16x16x32_bf16 v[44:47], v[128:131], v[168:171], v[44:47]
	v_mfma_f32_16x16x32_bf16 v[40:43], v[136:139], v[168:171], v[40:43]
	v_mfma_f32_16x16x32_bf16 v[28:31], v[128:131], v[176:179], v[28:31]
	v_mfma_f32_16x16x32_bf16 v[24:27], v[136:139], v[176:179], v[24:27]
	v_mfma_f32_16x16x32_bf16 v[12:15], v[128:131], v[184:187], v[12:15]
	v_mfma_f32_16x16x32_bf16 v[8:11], v[136:139], v[184:187], v[8:11]
	v_mfma_f32_16x16x32_bf16 v[60:63], v[132:135], v[164:167], v[60:63]
	v_mfma_f32_16x16x32_bf16 v[56:59], v[140:143], v[164:167], v[56:59]
	v_mfma_f32_16x16x32_bf16 v[44:47], v[132:135], v[172:175], v[44:47]
	v_mfma_f32_16x16x32_bf16 v[40:43], v[140:143], v[172:175], v[40:43]
	v_mfma_f32_16x16x32_bf16 v[28:31], v[132:135], v[180:183], v[28:31]
	v_mfma_f32_16x16x32_bf16 v[24:27], v[140:143], v[180:183], v[24:27]
	v_mfma_f32_16x16x32_bf16 v[12:15], v[132:135], v[188:191], v[12:15]
	v_mfma_f32_16x16x32_bf16 v[8:11], v[140:143], v[188:191], v[8:11]
	v_mfma_f32_16x16x32_bf16 v[52:55], v[144:147], v[160:163], v[52:55]
	v_mfma_f32_16x16x32_bf16 v[48:51], v[152:155], v[160:163], v[48:51]
	v_mfma_f32_16x16x32_bf16 v[36:39], v[144:147], v[168:171], v[36:39]
	v_mfma_f32_16x16x32_bf16 v[32:35], v[152:155], v[168:171], v[32:35]
	v_mfma_f32_16x16x32_bf16 v[20:23], v[144:147], v[176:179], v[20:23]
	v_mfma_f32_16x16x32_bf16 v[16:19], v[152:155], v[176:179], v[16:19]
	v_mfma_f32_16x16x32_bf16 v[4:7], v[144:147], v[184:187], v[4:7]
	v_mfma_f32_16x16x32_bf16 v[0:3], v[152:155], v[184:187], v[0:3]
	v_mfma_f32_16x16x32_bf16 v[52:55], v[148:151], v[164:167], v[52:55]
	v_mfma_f32_16x16x32_bf16 v[48:51], v[156:159], v[164:167], v[48:51]
	v_mfma_f32_16x16x32_bf16 v[36:39], v[148:151], v[172:175], v[36:39]
	v_mfma_f32_16x16x32_bf16 v[32:35], v[156:159], v[172:175], v[32:35]
	v_mfma_f32_16x16x32_bf16 v[20:23], v[148:151], v[180:183], v[20:23]
	v_mfma_f32_16x16x32_bf16 v[16:19], v[156:159], v[180:183], v[16:19]
	v_mfma_f32_16x16x32_bf16 v[4:7], v[148:151], v[188:191], v[4:7]
	v_mfma_f32_16x16x32_bf16 v[0:3], v[156:159], v[188:191], v[0:3]
	s_waitcnt vmcnt(8)
	s_barrier
	s_add_i32 s77, 0, 0x18000
	s_add_i32 s78, 0, 0x1c000
	s_add_u32 s48, s52, 0xb0000
	s_addc_u32 s49, s53, 0
	s_mov_b32 m0, s62
	s_nop 0
	global_load_lds_dwordx4 v192, s[48:49]
	s_mov_b32 m0, s63
	s_nop 0
	global_load_lds_dwordx4 v196, s[48:49]
	v_add_u32_e32 v140, s77, v232
	v_add_u32_e32 v156, s78, v232
	ds_read_b128 v[128:131], v140
	ds_read_b128 v[132:135], v140 offset:1024
	ds_read_b128 v[136:139], v140 offset:2048
	ds_read_b128 v[140:143], v140 offset:3072
	ds_read_b128 v[144:147], v156
	ds_read_b128 v[148:151], v156 offset:1024
	ds_read_b128 v[152:155], v156 offset:2048
	ds_read_b128 v[156:159], v156 offset:3072
	ds_read_b128 v[160:163], v238 offset:32768
	ds_read_b128 v[164:167], v238 offset:33792
	ds_read_b128 v[168:171], v238 offset:34816
	ds_read_b128 v[172:175], v238 offset:35840
	ds_read_b128 v[176:179], v238 offset:36864
	ds_read_b128 v[180:183], v238 offset:37888
	ds_read_b128 v[184:187], v238 offset:38912
	ds_read_b128 v[188:191], v238 offset:39936
	s_waitcnt lgkmcnt(0)
	s_barrier
; #define PG8_STAGE(bufoff, gbase, voff) do { _Pragma("unroll") for (int _i = 0; _i < 2; ++_i) \
;         __builtin_amdgcn_global_load_lds((const unsigned*)((const char*)(gbase) + (voff)[_i]), (PG8_LAS unsigned*)(lds + (bufoff) + ldsw + _i * 8192), 16, 0, 0); } while (0)
; #define PG8_LDA(dst, b, h) do { _Pragma("unroll") for (int m = 0; m < 4; ++m) _Pragma("unroll") for (int k = 0; k < 2; ++k) dst[m][k] = *(const PG8_LAS bf16x8*)(lds + PG8_SA(b, h) + aoff + m * 2048 + k * 1024); } while (0)
; #define PG8_MMA(ai, bj, At, Bt) do { __builtin_amdgcn_s_setprio(1); _Pragma("unroll") for (int m = 0; m < 4; ++m) _Pragma("unroll") for (int n = 0; n < 2; ++n) _Pragma("unroll") for (int k = 0; k < 2; ++k) \
;         acc[ai][bj][m][n] = __builtin_amdgcn_mfma_f32_16x16x32_bf16(Bt[n][k], At[m][k], acc[ai][bj][m][n], 0, 0, 0); __builtin_amdgcn_s_setprio(0); } while (0)
; #define PG8_WAIT_V(n) asm volatile("s_waitcnt vmcnt(" #n ")" ::: "memory")
; #define PG8_WAIT_L(n) asm volatile("s_waitcnt lgkmcnt(" #n ")" ::: "memory")
; #define PG8_BAR __builtin_amdgcn_s_barrier()
; #define PG8_SCHED __builtin_amdgcn_sched_barrier(0)
; template <class Epi, class Sched, bool ALIGN_EPI = false, bool SP2 = false>
; __device__ __forceinline__ void gemm_phase(PG8_LAS unsigned char* lds, const Gemm g, const Sched& S, const Epi& E, int tid_in) {
;     ...
;             PG8_WAIT_V(8); PG8_WAIT_L(0); PG8_BAR; PG8_MMA(0, 0, At, B0); PG8_MMA(0, 1, At, B1); PG8_BAR; PG8_SCHED;
;             PG8_LDA(At, 1, 1); PG8_STAGE(PG8_SB(1, 0), b3, voffB); PG8_STAGE(PG8_SB(1, 1), b3 + hstep, voffB); PG8_STAGE(PG8_SA(1, 0), a3, voffA);
;             PG8_WAIT_V(8); PG8_WAIT_L(0); PG8_BAR; PG8_MMA(1, 0, At, B0); PG8_MMA(1, 1, At, B1); PG8_BAR; PG8_SCHED;
	v_mfma_f32_16x16x32_bf16 v[124:127], v[128:131], v[160:163], v[124:127]
	v_mfma_f32_16x16x32_bf16 v[120:123], v[136:139], v[160:163], v[120:123]
	v_mfma_f32_16x16x32_bf16 v[108:111], v[128:131], v[168:171], v[108:111]
	v_mfma_f32_16x16x32_bf16 v[104:107], v[136:139], v[168:171], v[104:107]
	v_mfma_f32_16x16x32_bf16 v[92:95], v[128:131], v[176:179], v[92:95]
	v_mfma_f32_16x16x32_bf16 v[88:91], v[136:139], v[176:179], v[88:91]
	v_mfma_f32_16x16x32_bf16 v[76:79], v[128:131], v[184:187], v[76:79]
	v_mfma_f32_16x16x32_bf16 v[72:75], v[136:139], v[184:187], v[72:75]
	v_mfma_f32_16x16x32_bf16 v[124:127], v[132:135], v[164:167], v[124:127]
	v_mfma_f32_16x16x32_bf16 v[120:123], v[140:143], v[164:167], v[120:123]
	v_mfma_f32_16x16x32_bf16 v[108:111], v[132:135], v[172:175], v[108:111]
	v_mfma_f32_16x16x32_bf16 v[104:107], v[140:143], v[172:175], v[104:107]
	v_mfma_f32_16x16x32_bf16 v[92:95], v[132:135], v[180:183], v[92:95]
	v_mfma_f32_16x16x32_bf16 v[88:91], v[140:143], v[180:183], v[88:91]
	v_mfma_f32_16x16x32_bf16 v[76:79], v[132:135], v[188:191], v[76:79]
	v_mfma_f32_16x16x32_bf16 v[72:75], v[140:143], v[188:191], v[72:75]
	v_mfma_f32_16x16x32_bf16 v[116:119], v[144:147], v[160:163], v[116:119]
	v_mfma_f32_16x16x32_bf16 v[112:115], v[152:155], v[160:163], v[112:115]
	v_mfma_f32_16x16x32_bf16 v[100:103], v[144:147], v[168:171], v[100:103]
	v_mfma_f32_16x16x32_bf16 v[96:99], v[152:155], v[168:171], v[96:99]
	v_mfma_f32_16x16x32_bf16 v[84:87], v[144:147], v[176:179], v[84:87]
	v_mfma_f32_16x16x32_bf16 v[80:83], v[152:155], v[176:179], v[80:83]
	v_mfma_f32_16x16x32_bf16 v[68:71], v[144:147], v[184:187], v[68:71]
	v_mfma_f32_16x16x32_bf16 v[64:67], v[152:155], v[184:187], v[64:67]
	v_mfma_f32_16x16x32_bf16 v[116:119], v[148:151], v[164:167], v[116:119]
	v_mfma_f32_16x16x32_bf16 v[112:115], v[156:159], v[164:167], v[112:115]
	v_mfma_f32_16x16x32_bf16 v[100:103], v[148:151], v[172:175], v[100:103]
	v_mfma_f32_16x16x32_bf16 v[96:99], v[156:159], v[172:175], v[96:99]
	v_mfma_f32_16x16x32_bf16 v[84:87], v[148:151], v[180:183], v[84:87]
	v_mfma_f32_16x16x32_bf16 v[80:83], v[156:159], v[180:183], v[80:83]
	v_mfma_f32_16x16x32_bf16 v[68:71], v[148:151], v[188:191], v[68:71]
	v_mfma_f32_16x16x32_bf16 v[64:67], v[156:159], v[188:191], v[64:67]
	s_waitcnt vmcnt(8)
	s_barrier
	s_add_i32 s48, s77, s59
	s_mov_b32 m0, s48
	ds_read_b128 v[160:163], v238 offset:49152
	global_load_lds_dwordx4 v194, s[98:99]
	s_add_i32 m0, s48, 0x2000
	s_add_u32 s48, s50, 0xb0080
	s_addc_u32 s49, s51, 0
	s_add_i32 s50, s78, s59
	global_load_lds_dwordx4 v198, s[98:99]
	s_mov_b32 m0, s50
	ds_read_b128 v[164:167], v238 offset:50176
	global_load_lds_dwordx4 v194, s[48:49]
	s_add_i32 m0, s50, 0x2000
	ds_read_b128 v[168:171], v238 offset:51200
	global_load_lds_dwordx4 v198, s[48:49]
	s_mov_b32 m0, s65
	ds_read_b128 v[172:175], v238 offset:52224
	global_load_lds_dwordx4 v192, s[100:101]
	s_mov_b32 m0, s67
	ds_read_b128 v[176:179], v238 offset:53248
	global_load_lds_dwordx4 v196, s[100:101]
	ds_read_b128 v[180:183], v238 offset:54272
	ds_read_b128 v[184:187], v238 offset:55296
	ds_read_b128 v[188:191], v238 offset:56320
	s_waitcnt lgkmcnt(0)
	s_barrier
	v_mfma_f32_16x16x32_bf16 v[60:63], v[128:131], v[160:163], v[60:63]
	v_mfma_f32_16x16x32_bf16 v[56:59], v[136:139], v[160:163], v[56:59]
	v_mfma_f32_16x16x32_bf16 v[44:47], v[128:131], v[168:171], v[44:47]
	v_mfma_f32_16x16x32_bf16 v[40:43], v[136:139], v[168:171], v[40:43]
	v_mfma_f32_16x16x32_bf16 v[28:31], v[128:131], v[176:179], v[28:31]
	v_mfma_f32_16x16x32_bf16 v[24:27], v[136:139], v[176:179], v[24:27]
	v_mfma_f32_16x16x32_bf16 v[12:15], v[128:131], v[184:187], v[12:15]
	v_mfma_f32_16x16x32_bf16 v[8:11], v[136:139], v[184:187], v[8:11]
	v_mfma_f32_16x16x32_bf16 v[60:63], v[132:135], v[164:167], v[60:63]
	v_mfma_f32_16x16x32_bf16 v[56:59], v[140:143], v[164:167], v[56:59]
	v_mfma_f32_16x16x32_bf16 v[44:47], v[132:135], v[172:175], v[44:47]
	v_mfma_f32_16x16x32_bf16 v[40:43], v[140:143], v[172:175], v[40:43]
	v_mfma_f32_16x16x32_bf16 v[28:31], v[132:135], v[180:183], v[28:31]
	v_mfma_f32_16x16x32_bf16 v[24:27], v[140:143], v[180:183], v[24:27]
	v_mfma_f32_16x16x32_bf16 v[12:15], v[132:135], v[188:191], v[12:15]
	v_mfma_f32_16x16x32_bf16 v[8:11], v[140:143], v[188:191], v[8:11]
	v_mfma_f32_16x16x32_bf16 v[52:55], v[144:147], v[160:163], v[52:55]
	v_mfma_f32_16x16x32_bf16 v[48:51], v[152:155], v[160:163], v[48:51]
	v_mfma_f32_16x16x32_bf16 v[36:39], v[144:147], v[168:171], v[36:39]
	v_mfma_f32_16x16x32_bf16 v[32:35], v[152:155], v[168:171], v[32:35]
	v_mfma_f32_16x16x32_bf16 v[20:23], v[144:147], v[176:179], v[20:23]
	v_mfma_f32_16x16x32_bf16 v[16:19], v[152:155], v[176:179], v[16:19]
	v_mfma_f32_16x16x32_bf16 v[4:7], v[144:147], v[184:187], v[4:7]
	v_mfma_f32_16x16x32_bf16 v[0:3], v[152:155], v[184:187], v[0:3]
	v_mfma_f32_16x16x32_bf16 v[52:55], v[148:151], v[164:167], v[52:55]
	v_mfma_f32_16x16x32_bf16 v[48:51], v[156:159], v[164:167], v[48:51]
	v_mfma_f32_16x16x32_bf16 v[36:39], v[148:151], v[172:175], v[36:39]
	v_mfma_f32_16x16x32_bf16 v[32:35], v[156:159], v[172:175], v[32:35]
	v_mfma_f32_16x16x32_bf16 v[20:23], v[148:151], v[180:183], v[20:23]
	v_mfma_f32_16x16x32_bf16 v[16:19], v[156:159], v[180:183], v[16:19]
	v_mfma_f32_16x16x32_bf16 v[4:7], v[148:151], v[188:191], v[4:7]
	v_mfma_f32_16x16x32_bf16 v[0:3], v[156:159], v[188:191], v[0:3]
	s_waitcnt vmcnt(8)
	s_barrier
	s_add_i32 s76, s76, 2
	s_add_u32 s12, s12, 0x100
	s_addc_u32 s75, s75, 0
	s_cmp_gt_u32 s76, 41
	s_mov_b64 s[48:49], s[6:7]
	s_cbranch_scc0 .LBB0_461
	s_branch .Lasym_J_461

; #define PG8_BAR __builtin_amdgcn_s_barrier()
; template <class Epi, class Sched, bool ALIGN_EPI = false, bool SP2 = false>
; __device__ __forceinline__ void gemm_phase(PG8_LAS unsigned char* lds, const Gemm g, const Sched& S, const Epi& E, int tid_in) {
;     ...
;         if constexpr (ALIGN_EPI) { if (wr == 0) PG8_BAR; }
.Lasym_J_461:
	s_and_b64 vcc, exec, s[24:25]
	s_cbranch_vccz .LBB0_464
	s_barrier

; #define PG8_STAGE(bufoff, gbase, voff) do { _Pragma("unroll") for (int _i = 0; _i < 2; ++_i) \
;         __builtin_amdgcn_global_load_lds((const unsigned*)((const char*)(gbase) + (voff)[_i]), (PG8_LAS unsigned*)(lds + (bufoff) + ldsw + _i * 8192), 16, 0, 0); } while (0)
; #define PG8_LDA(dst, b, h) do { _Pragma("unroll") for (int m = 0; m < 4; ++m) _Pragma("unroll") for (int k = 0; k < 2; ++k) dst[m][k] = *(const PG8_LAS bf16x8*)(lds + PG8_SA(b, h) + aoff + m * 2048 + k * 1024); } while (0)
; #define PG8_LDB(dst, b, h) do { _Pragma("unroll") for (int n = 0; n < 2; ++n) _Pragma("unroll") for (int k = 0; k < 2; ++k) dst[n][k] = *(const PG8_LAS bf16x8*)(lds + PG8_SB(b, h) + boff + n * 2048 + k * 1024); } while (0)
; #define PG8_SCHED __builtin_amdgcn_sched_barrier(0)
; template <class Epi, class Sched, bool ALIGN_EPI = false, bool SP2 = false>
; __device__ __forceinline__ void gemm_phase(PG8_LAS unsigned char* lds, const Gemm g, const Sched& S, const Epi& E, int tid_in) {
;     ...
;             const bool last = (t == nt - 2);
;             const char* a1 = cA + (size_t)(t + 1) * kstep;
;             const char* a2 = last ? nA : cA + (size_t)(t + 2) * kstep; const char* b2 = last ? nB : cB + (size_t)(t + 2) * kstep;
;             const char* a3 = a2 + kstep; const char* b3 = b2 + kstep;
;             if (last && has_next) S.a_ready(nxt);
;             if constexpr (SP2) {
;             PG8_LDB(B0, 0, 0); PG8_LDB(B1, 0, 1); PG8_SCHED; PG8_LDA(At, 0, 0); PG8_STAGE(PG8_SA(1, 1), a1 + hstep, voffA);
;     ...
;         for (int a = 0; a < 2; ++a)
; #pragma unroll
;             for (int b = 0; b < 2; ++b)
; #pragma unroll
;                 for (int m = 0; m < 4; ++m)
; #pragma unroll
;                     for (int n = 0; n < 2; ++n) acc[a][b][m][n] = (f32x4){0.f, 0.f, 0.f, 0.f};
.LBB0_563:
	s_ashr_i32 s35, s34, 31
	s_lshl_b64 s[0:1], s[34:35], 19
	s_add_u32 s36, s54, s0
	s_addc_u32 s37, s55, s1
	s_and_b64 s[0:1], s[4:5], exec
	s_cselect_b32 s0, s37, s47
	s_cselect_b32 s1, s36, s46
	s_ashr_i32 s31, s30, 31
	s_lshl_b64 s[38:39], s[30:31], 19
	s_add_u32 s38, s56, s38
	s_addc_u32 s39, s57, s39
	s_and_b64 s[50:51], s[4:5], exec
	s_cselect_b32 s7, s39, s49
	s_cselect_b32 s31, s38, s48
	s_add_u32 s46, s46, 0x40080
	s_addc_u32 s47, s47, 0
	s_add_u32 s35, s48, 0x100
	v_mov_b32_e32 v60, 0
	s_addc_u32 s45, s49, 0
	s_mov_b32 s52, -2
	v_mov_b32_e32 v61, v60
	v_mov_b32_e32 v62, v60
	v_mov_b32_e32 v63, v60
	v_mov_b32_e32 v64, v60
	v_mov_b32_e32 v65, v60
	v_mov_b32_e32 v66, v60
	v_mov_b32_e32 v67, v60
	v_mov_b32_e32 v72, v60
	v_mov_b32_e32 v73, v60
	v_mov_b32_e32 v74, v60
	v_mov_b32_e32 v75, v60
	v_mov_b32_e32 v76, v60
	v_mov_b32_e32 v77, v60
	v_mov_b32_e32 v78, v60
	v_mov_b32_e32 v79, v60
	v_mov_b32_e32 v80, v60
	v_mov_b32_e32 v81, v60
	v_mov_b32_e32 v82, v60
	v_mov_b32_e32 v83, v60
	v_mov_b32_e32 v84, v60
	v_mov_b32_e32 v85, v60
	v_mov_b32_e32 v86, v60
	v_mov_b32_e32 v87, v60
	v_mov_b32_e32 v88, v60
	v_mov_b32_e32 v89, v60
	v_mov_b32_e32 v90, v60
	v_mov_b32_e32 v91, v60
	v_mov_b32_e32 v92, v60
	v_mov_b32_e32 v93, v60
	v_mov_b32_e32 v94, v60
	v_mov_b32_e32 v95, v60
	v_mov_b32_e32 v0, v60
	v_mov_b32_e32 v1, v60
	v_mov_b32_e32 v2, v60
	v_mov_b32_e32 v3, v60
	v_mov_b32_e32 v4, v60
	v_mov_b32_e32 v5, v60
	v_mov_b32_e32 v6, v60
	v_mov_b32_e32 v7, v60
	v_mov_b32_e32 v8, v60
	v_mov_b32_e32 v9, v60
	v_mov_b32_e32 v10, v60
	v_mov_b32_e32 v11, v60
	v_mov_b32_e32 v12, v60
	v_mov_b32_e32 v13, v60
	v_mov_b32_e32 v14, v60
	v_mov_b32_e32 v15, v60
	v_mov_b32_e32 v16, v60
	v_mov_b32_e32 v17, v60
	v_mov_b32_e32 v18, v60
	v_mov_b32_e32 v19, v60
	v_mov_b32_e32 v20, v60
	v_mov_b32_e32 v21, v60
	v_mov_b32_e32 v22, v60
	v_mov_b32_e32 v23, v60
	v_mov_b32_e32 v24, v60
	v_mov_b32_e32 v25, v60
	v_mov_b32_e32 v26, v60
	v_mov_b32_e32 v27, v60
	v_mov_b32_e32 v28, v60
	v_mov_b32_e32 v29, v60
	v_mov_b32_e32 v30, v60
	v_mov_b32_e32 v31, v60
	v_mov_b32_e32 v96, v60
	v_mov_b32_e32 v97, v60
	v_mov_b32_e32 v98, v60
	v_mov_b32_e32 v99, v60
	v_mov_b32_e32 v100, v60
	v_mov_b32_e32 v101, v60
	v_mov_b32_e32 v102, v60
	v_mov_b32_e32 v103, v60
	v_mov_b32_e32 v104, v60
	v_mov_b32_e32 v105, v60
	v_mov_b32_e32 v106, v60
	v_mov_b32_e32 v107, v60
	v_mov_b32_e32 v108, v60
	v_mov_b32_e32 v109, v60
	v_mov_b32_e32 v110, v60
	v_mov_b32_e32 v111, v60
	v_mov_b32_e32 v112, v60
	v_mov_b32_e32 v113, v60
	v_mov_b32_e32 v114, v60
	v_mov_b32_e32 v115, v60
	v_mov_b32_e32 v116, v60
	v_mov_b32_e32 v117, v60
	v_mov_b32_e32 v118, v60
	v_mov_b32_e32 v119, v60
	v_mov_b32_e32 v120, v60
	v_mov_b32_e32 v121, v60
	v_mov_b32_e32 v122, v60
	v_mov_b32_e32 v123, v60
	v_mov_b32_e32 v124, v60
	v_mov_b32_e32 v125, v60
	v_mov_b32_e32 v126, v60
	v_mov_b32_e32 v127, v60
	v_mov_b32_e32 v32, v60
	v_mov_b32_e32 v33, v60
	v_mov_b32_e32 v34, v60
	v_mov_b32_e32 v35, v60
	v_mov_b32_e32 v36, v60
	v_mov_b32_e32 v37, v60
	v_mov_b32_e32 v38, v60
	v_mov_b32_e32 v39, v60
	v_mov_b32_e32 v40, v60
	v_mov_b32_e32 v41, v60
	v_mov_b32_e32 v42, v60
	v_mov_b32_e32 v43, v60
	v_mov_b32_e32 v44, v60
	v_mov_b32_e32 v45, v60
	v_mov_b32_e32 v46, v60
	v_mov_b32_e32 v47, v60
	v_mov_b32_e32 v48, v60
	v_mov_b32_e32 v49, v60
	v_mov_b32_e32 v50, v60
	v_mov_b32_e32 v51, v60
	v_mov_b32_e32 v52, v60
	v_mov_b32_e32 v53, v60
	v_mov_b32_e32 v54, v60
	v_mov_b32_e32 v55, v60
	v_mov_b32_e32 v56, v60
	v_mov_b32_e32 v57, v60
	v_mov_b32_e32 v58, v60
	v_mov_b32_e32 v59, v60
	v_mov_b32_e32 v68, v60
	v_mov_b32_e32 v69, v60
	v_mov_b32_e32 v70, v60
	v_mov_b32_e32 v71, v60
	s_cmp_lg_u64 s[16:17], 0
	s_cbranch_scc0 .Lasym_T_564
.LBB0_564:
	s_add_u32 s48, s46, 0xfffc0080
	s_addc_u32 s49, s47, -1
	s_cmp_eq_u32 s52, 12
	s_cselect_b32 s51, s0, s49
	s_cselect_b32 s50, s1, s48
	s_cselect_b32 s49, s7, s45
	s_cselect_b32 s48, s31, s35
	s_add_i32 m0, s59, 0xc000
	ds_read_b128 v[128:131], v180
	global_load_lds_dwordx4 v158, s[46:47]
	s_add_i32 m0, s59, 0xe000
	ds_read_b128 v[132:135], v180 offset:1024
	global_load_lds_dwordx4 v160, s[46:47]
	ds_read_b128 v[136:139], v180 offset:2048
	ds_read_b128 v[140:143], v180 offset:3072
	ds_read_b128 v[166:169], v181
	ds_read_b128 v[170:173], v181 offset:1024
	ds_read_b128 v[174:177], v181 offset:2048
	ds_read_b128 v[184:187], v181 offset:3072
	ds_read_b128 v[188:191], v182
	ds_read_b128 v[192:195], v182 offset:1024
	ds_read_b128 v[196:199], v182 offset:2048
	ds_read_b128 v[200:203], v182 offset:3072
	ds_read_b128 v[204:207], v182 offset:4096
	ds_read_b128 v[208:211], v182 offset:5120
	ds_read_b128 v[212:215], v182 offset:6144
	ds_read_b128 v[216:219], v182 offset:7168
	s_waitcnt lgkmcnt(0)
	s_barrier
; #define PG8_STAGE(bufoff, gbase, voff) do { _Pragma("unroll") for (int _i = 0; _i < 2; ++_i) \
;         __builtin_amdgcn_global_load_lds((const unsigned*)((const char*)(gbase) + (voff)[_i]), (PG8_LAS unsigned*)(lds + (bufoff) + ldsw + _i * 8192), 16, 0, 0); } while (0)
; #define PG8_LDA(dst, b, h) do { _Pragma("unroll") for (int m = 0; m < 4; ++m) _Pragma("unroll") for (int k = 0; k < 2; ++k) dst[m][k] = *(const PG8_LAS bf16x8*)(lds + PG8_SA(b, h) + aoff + m * 2048 + k * 1024); } while (0)
; #define PG8_MMA(ai, bj, At, Bt) do { __builtin_amdgcn_s_setprio(1); _Pragma("unroll") for (int m = 0; m < 4; ++m) _Pragma("unroll") for (int n = 0; n < 2; ++n) _Pragma("unroll") for (int k = 0; k < 2; ++k) \
;         acc[ai][bj][m][n] = __builtin_amdgcn_mfma_f32_16x16x32_bf16(Bt[n][k], At[m][k], acc[ai][bj][m][n], 0, 0, 0); __builtin_amdgcn_s_setprio(0); } while (0)
; #define PG8_WAIT_V(n) asm volatile("s_waitcnt vmcnt(" #n ")" ::: "memory")
; #define PG8_WAIT_L(n) asm volatile("s_waitcnt lgkmcnt(" #n ")" ::: "memory")
; #define PG8_BAR __builtin_amdgcn_s_barrier()
; #define PG8_SCHED __builtin_amdgcn_sched_barrier(0)
; template <class Epi, class Sched, bool ALIGN_EPI = false, bool SP2 = false>
; __device__ __forceinline__ void gemm_phase(PG8_LAS unsigned char* lds, const Gemm g, const Sched& S, const Epi& E, int tid_in) {
;     ...
;             PG8_WAIT_V(8); PG8_WAIT_L(0); PG8_BAR; PG8_MMA(0, 0, At, B0); PG8_MMA(0, 1, At, B1); PG8_BAR; PG8_SCHED;
;             PG8_LDA(At, 0, 1); PG8_STAGE(PG8_SB(0, 0), b2, voffB); PG8_STAGE(PG8_SB(0, 1), b2 + hstep, voffB); PG8_STAGE(PG8_SA(0, 0), a2, voffA);
;             PG8_WAIT_V(8); PG8_WAIT_L(0); PG8_BAR; PG8_MMA(1, 0, At, B0); PG8_MMA(1, 1, At, B1); PG8_BAR; PG8_SCHED;
	v_mfma_f32_16x16x32_bf16 v[68:71], v[128:131], v[188:191], v[68:71]
	v_mfma_f32_16x16x32_bf16 v[56:59], v[136:139], v[188:191], v[56:59]
	v_mfma_f32_16x16x32_bf16 v[52:55], v[128:131], v[196:199], v[52:55]
	v_mfma_f32_16x16x32_bf16 v[48:51], v[136:139], v[196:199], v[48:51]
	v_mfma_f32_16x16x32_bf16 v[44:47], v[128:131], v[204:207], v[44:47]
	v_mfma_f32_16x16x32_bf16 v[40:43], v[136:139], v[204:207], v[40:43]
	v_mfma_f32_16x16x32_bf16 v[36:39], v[128:131], v[212:215], v[36:39]
	v_mfma_f32_16x16x32_bf16 v[32:35], v[136:139], v[212:215], v[32:35]
	v_mfma_f32_16x16x32_bf16 v[68:71], v[132:135], v[192:195], v[68:71]
	v_mfma_f32_16x16x32_bf16 v[56:59], v[140:143], v[192:195], v[56:59]
	v_mfma_f32_16x16x32_bf16 v[52:55], v[132:135], v[200:203], v[52:55]
	v_mfma_f32_16x16x32_bf16 v[48:51], v[140:143], v[200:203], v[48:51]
	v_mfma_f32_16x16x32_bf16 v[44:47], v[132:135], v[208:211], v[44:47]
	v_mfma_f32_16x16x32_bf16 v[40:43], v[140:143], v[208:211], v[40:43]
	v_mfma_f32_16x16x32_bf16 v[36:39], v[132:135], v[216:219], v[36:39]
	v_mfma_f32_16x16x32_bf16 v[32:35], v[140:143], v[216:219], v[32:35]
	v_mfma_f32_16x16x32_bf16 v[124:127], v[166:169], v[188:191], v[124:127]
	v_mfma_f32_16x16x32_bf16 v[120:123], v[174:177], v[188:191], v[120:123]
	v_mfma_f32_16x16x32_bf16 v[116:119], v[166:169], v[196:199], v[116:119]
	v_mfma_f32_16x16x32_bf16 v[112:115], v[174:177], v[196:199], v[112:115]
	v_mfma_f32_16x16x32_bf16 v[108:111], v[166:169], v[204:207], v[108:111]
	v_mfma_f32_16x16x32_bf16 v[104:107], v[174:177], v[204:207], v[104:107]
	v_mfma_f32_16x16x32_bf16 v[100:103], v[166:169], v[212:215], v[100:103]
	v_mfma_f32_16x16x32_bf16 v[96:99], v[174:177], v[212:215], v[96:99]
	v_mfma_f32_16x16x32_bf16 v[124:127], v[170:173], v[192:195], v[124:127]
	v_mfma_f32_16x16x32_bf16 v[120:123], v[184:187], v[192:195], v[120:123]
	v_mfma_f32_16x16x32_bf16 v[116:119], v[170:173], v[200:203], v[116:119]
	v_mfma_f32_16x16x32_bf16 v[112:115], v[184:187], v[200:203], v[112:115]
	v_mfma_f32_16x16x32_bf16 v[108:111], v[170:173], v[208:211], v[108:111]
	v_mfma_f32_16x16x32_bf16 v[104:107], v[184:187], v[208:211], v[104:107]
	v_mfma_f32_16x16x32_bf16 v[100:103], v[170:173], v[216:219], v[100:103]
	v_mfma_f32_16x16x32_bf16 v[96:99], v[184:187], v[216:219], v[96:99]
	s_waitcnt vmcnt(8)
	s_barrier
	s_add_u32 s98, s48, s14
	s_addc_u32 s99, s49, s15
	s_add_u32 s100, s50, s14
	s_addc_u32 s101, s51, s15
	s_add_i32 s53, s77, s29
	s_mov_b32 m0, s53
	ds_read_b128 v[188:191], v182 offset:16384
	global_load_lds_dwordx4 v146, s[48:49]
	s_add_i32 m0, s53, 0x2000
	s_add_u32 s88, s48, 0x40000
	s_addc_u32 s89, s49, 0
	s_add_i32 s53, s78, s29
	global_load_lds_dwordx4 v150, s[48:49]
	s_mov_b32 m0, s53
	ds_read_b128 v[192:195], v182 offset:17408
	global_load_lds_dwordx4 v146, s[88:89]
	s_add_i32 m0, s53, 0x2000
	ds_read_b128 v[196:199], v182 offset:18432
	global_load_lds_dwordx4 v150, s[88:89]
	s_mov_b32 m0, s59
	ds_read_b128 v[200:203], v182 offset:19456
	global_load_lds_dwordx4 v144, s[50:51]
	s_mov_b32 m0, s60
	ds_read_b128 v[204:207], v182 offset:20480
	global_load_lds_dwordx4 v148, s[50:51]
	ds_read_b128 v[208:211], v182 offset:21504
	ds_read_b128 v[212:215], v182 offset:22528
	ds_read_b128 v[216:219], v182 offset:23552
	s_waitcnt lgkmcnt(0)
	s_barrier
	v_mfma_f32_16x16x32_bf16 v[28:31], v[128:131], v[188:191], v[28:31]
	v_mfma_f32_16x16x32_bf16 v[24:27], v[136:139], v[188:191], v[24:27]
	v_mfma_f32_16x16x32_bf16 v[20:23], v[128:131], v[196:199], v[20:23]
	v_mfma_f32_16x16x32_bf16 v[16:19], v[136:139], v[196:199], v[16:19]
	v_mfma_f32_16x16x32_bf16 v[12:15], v[128:131], v[204:207], v[12:15]
	v_mfma_f32_16x16x32_bf16 v[8:11], v[136:139], v[204:207], v[8:11]
	v_mfma_f32_16x16x32_bf16 v[4:7], v[128:131], v[212:215], v[4:7]
	v_mfma_f32_16x16x32_bf16 v[0:3], v[136:139], v[212:215], v[0:3]
	v_mfma_f32_16x16x32_bf16 v[28:31], v[132:135], v[192:195], v[28:31]
	v_mfma_f32_16x16x32_bf16 v[24:27], v[140:143], v[192:195], v[24:27]
	v_mfma_f32_16x16x32_bf16 v[20:23], v[132:135], v[200:203], v[20:23]
	v_mfma_f32_16x16x32_bf16 v[16:19], v[140:143], v[200:203], v[16:19]
	v_mfma_f32_16x16x32_bf16 v[12:15], v[132:135], v[208:211], v[12:15]
	v_mfma_f32_16x16x32_bf16 v[8:11], v[140:143], v[208:211], v[8:11]
	v_mfma_f32_16x16x32_bf16 v[4:7], v[132:135], v[216:219], v[4:7]
	v_mfma_f32_16x16x32_bf16 v[0:3], v[140:143], v[216:219], v[0:3]
	v_mfma_f32_16x16x32_bf16 v[92:95], v[166:169], v[188:191], v[92:95]
	v_mfma_f32_16x16x32_bf16 v[88:91], v[174:177], v[188:191], v[88:91]
	v_mfma_f32_16x16x32_bf16 v[84:87], v[166:169], v[196:199], v[84:87]
	v_mfma_f32_16x16x32_bf16 v[80:83], v[174:177], v[196:199], v[80:83]
	v_mfma_f32_16x16x32_bf16 v[76:79], v[166:169], v[204:207], v[76:79]
	v_mfma_f32_16x16x32_bf16 v[72:75], v[174:177], v[204:207], v[72:75]
	v_mfma_f32_16x16x32_bf16 v[64:67], v[166:169], v[212:215], v[64:67]
	v_mfma_f32_16x16x32_bf16 v[60:63], v[174:177], v[212:215], v[60:63]
	v_mfma_f32_16x16x32_bf16 v[92:95], v[170:173], v[192:195], v[92:95]
	v_mfma_f32_16x16x32_bf16 v[88:91], v[184:187], v[192:195], v[88:91]
	v_mfma_f32_16x16x32_bf16 v[84:87], v[170:173], v[200:203], v[84:87]
	v_mfma_f32_16x16x32_bf16 v[80:83], v[184:187], v[200:203], v[80:83]
	v_mfma_f32_16x16x32_bf16 v[76:79], v[170:173], v[208:211], v[76:79]
	v_mfma_f32_16x16x32_bf16 v[72:75], v[184:187], v[208:211], v[72:75]
	v_mfma_f32_16x16x32_bf16 v[64:67], v[170:173], v[216:219], v[64:67]
	v_mfma_f32_16x16x32_bf16 v[60:63], v[184:187], v[216:219], v[60:63]
	s_waitcnt vmcnt(8)
	s_barrier
; #define PG8_STAGE(bufoff, gbase, voff) do { _Pragma("unroll") for (int _i = 0; _i < 2; ++_i) \
;         __builtin_amdgcn_global_load_lds((const unsigned*)((const char*)(gbase) + (voff)[_i]), (PG8_LAS unsigned*)(lds + (bufoff) + ldsw + _i * 8192), 16, 0, 0); } while (0)
; #define PG8_LDA(dst, b, h) do { _Pragma("unroll") for (int m = 0; m < 4; ++m) _Pragma("unroll") for (int k = 0; k < 2; ++k) dst[m][k] = *(const PG8_LAS bf16x8*)(lds + PG8_SA(b, h) + aoff + m * 2048 + k * 1024); } while (0)
; #define PG8_LDB(dst, b, h) do { _Pragma("unroll") for (int n = 0; n < 2; ++n) _Pragma("unroll") for (int k = 0; k < 2; ++k) dst[n][k] = *(const PG8_LAS bf16x8*)(lds + PG8_SB(b, h) + boff + n * 2048 + k * 1024); } while (0)
; #define PG8_MMA(ai, bj, At, Bt) do { __builtin_amdgcn_s_setprio(1); _Pragma("unroll") for (int m = 0; m < 4; ++m) _Pragma("unroll") for (int n = 0; n < 2; ++n) _Pragma("unroll") for (int k = 0; k < 2; ++k) \
;         acc[ai][bj][m][n] = __builtin_amdgcn_mfma_f32_16x16x32_bf16(Bt[n][k], At[m][k], acc[ai][bj][m][n], 0, 0, 0); __builtin_amdgcn_s_setprio(0); } while (0)
; #define PG8_WAIT_V(n) asm volatile("s_waitcnt vmcnt(" #n ")" ::: "memory")
; #define PG8_WAIT_L(n) asm volatile("s_waitcnt lgkmcnt(" #n ")" ::: "memory")
; #define PG8_BAR __builtin_amdgcn_s_barrier()
; #define PG8_SCHED __builtin_amdgcn_sched_barrier(0)
; template <class Epi, class Sched, bool ALIGN_EPI = false, bool SP2 = false>
; __device__ __forceinline__ void gemm_phase(PG8_LAS unsigned char* lds, const Gemm g, const Sched& S, const Epi& E, int tid_in) {
;     ...
;             PG8_LDB(B0, 1, 0); PG8_LDB(B1, 1, 1); PG8_SCHED; PG8_LDA(At, 1, 0); PG8_STAGE(PG8_SA(0, 1), a2 + hstep, voffA);
;             PG8_WAIT_V(8); PG8_WAIT_L(0); PG8_BAR; PG8_MMA(0, 0, At, B0); PG8_MMA(0, 1, At, B1); PG8_BAR; PG8_SCHED;
;             PG8_LDA(At, 1, 1); PG8_STAGE(PG8_SB(1, 0), b3, voffB); PG8_STAGE(PG8_SB(1, 1), b3 + hstep, voffB); PG8_STAGE(PG8_SA(1, 0), a3, voffA);
;             PG8_WAIT_V(8); PG8_WAIT_L(0); PG8_BAR; PG8_MMA(1, 0, At, B0); PG8_MMA(1, 1, At, B1); PG8_BAR; PG8_SCHED;
	s_add_i32 s53, 0, 0x18000
	s_add_i32 s88, 0, 0x1c000
	s_add_u32 s50, s50, 0x40000
	s_addc_u32 s51, s51, 0
	s_mov_b32 m0, s61
	s_nop 0
	global_load_lds_dwordx4 v144, s[50:51]
	s_mov_b32 m0, s62
	s_nop 0
	global_load_lds_dwordx4 v148, s[50:51]
	v_add_u32_e32 v140, s53, v179
	v_add_u32_e32 v184, s88, v179
	ds_read_b128 v[128:131], v140
	ds_read_b128 v[132:135], v140 offset:1024
	ds_read_b128 v[136:139], v140 offset:2048
	ds_read_b128 v[140:143], v140 offset:3072
	ds_read_b128 v[166:169], v184
	ds_read_b128 v[170:173], v184 offset:1024
	ds_read_b128 v[174:177], v184 offset:2048
	ds_read_b128 v[184:187], v184 offset:3072
	ds_read_b128 v[188:191], v182 offset:32768
	ds_read_b128 v[192:195], v182 offset:33792
	ds_read_b128 v[196:199], v182 offset:34816
	ds_read_b128 v[200:203], v182 offset:35840
	ds_read_b128 v[204:207], v182 offset:36864
	ds_read_b128 v[208:211], v182 offset:37888
	ds_read_b128 v[212:215], v182 offset:38912
	ds_read_b128 v[216:219], v182 offset:39936
	s_waitcnt lgkmcnt(0)
	s_barrier
	v_mfma_f32_16x16x32_bf16 v[68:71], v[128:131], v[188:191], v[68:71]
	v_mfma_f32_16x16x32_bf16 v[56:59], v[136:139], v[188:191], v[56:59]
	v_mfma_f32_16x16x32_bf16 v[52:55], v[128:131], v[196:199], v[52:55]
	v_mfma_f32_16x16x32_bf16 v[48:51], v[136:139], v[196:199], v[48:51]
	v_mfma_f32_16x16x32_bf16 v[44:47], v[128:131], v[204:207], v[44:47]
	v_mfma_f32_16x16x32_bf16 v[40:43], v[136:139], v[204:207], v[40:43]
	v_mfma_f32_16x16x32_bf16 v[36:39], v[128:131], v[212:215], v[36:39]
	v_mfma_f32_16x16x32_bf16 v[32:35], v[136:139], v[212:215], v[32:35]
	v_mfma_f32_16x16x32_bf16 v[68:71], v[132:135], v[192:195], v[68:71]
	v_mfma_f32_16x16x32_bf16 v[56:59], v[140:143], v[192:195], v[56:59]
	v_mfma_f32_16x16x32_bf16 v[52:55], v[132:135], v[200:203], v[52:55]
	v_mfma_f32_16x16x32_bf16 v[48:51], v[140:143], v[200:203], v[48:51]
	v_mfma_f32_16x16x32_bf16 v[44:47], v[132:135], v[208:211], v[44:47]
	v_mfma_f32_16x16x32_bf16 v[40:43], v[140:143], v[208:211], v[40:43]
	v_mfma_f32_16x16x32_bf16 v[36:39], v[132:135], v[216:219], v[36:39]
	v_mfma_f32_16x16x32_bf16 v[32:35], v[140:143], v[216:219], v[32:35]
	v_mfma_f32_16x16x32_bf16 v[124:127], v[166:169], v[188:191], v[124:127]
	v_mfma_f32_16x16x32_bf16 v[120:123], v[174:177], v[188:191], v[120:123]
	v_mfma_f32_16x16x32_bf16 v[116:119], v[166:169], v[196:199], v[116:119]
	v_mfma_f32_16x16x32_bf16 v[112:115], v[174:177], v[196:199], v[112:115]
	v_mfma_f32_16x16x32_bf16 v[108:111], v[166:169], v[204:207], v[108:111]
	v_mfma_f32_16x16x32_bf16 v[104:107], v[174:177], v[204:207], v[104:107]
	v_mfma_f32_16x16x32_bf16 v[100:103], v[166:169], v[212:215], v[100:103]
	v_mfma_f32_16x16x32_bf16 v[96:99], v[174:177], v[212:215], v[96:99]
	v_mfma_f32_16x16x32_bf16 v[124:127], v[170:173], v[192:195], v[124:127]
	v_mfma_f32_16x16x32_bf16 v[120:123], v[184:187], v[192:195], v[120:123]
	v_mfma_f32_16x16x32_bf16 v[116:119], v[170:173], v[200:203], v[116:119]
	v_mfma_f32_16x16x32_bf16 v[112:115], v[184:187], v[200:203], v[112:115]
	v_mfma_f32_16x16x32_bf16 v[108:111], v[170:173], v[208:211], v[108:111]
	v_mfma_f32_16x16x32_bf16 v[104:107], v[184:187], v[208:211], v[104:107]
	v_mfma_f32_16x16x32_bf16 v[100:103], v[170:173], v[216:219], v[100:103]
	v_mfma_f32_16x16x32_bf16 v[96:99], v[184:187], v[216:219], v[96:99]
	s_waitcnt vmcnt(8)
	s_barrier
	s_add_i32 s50, s53, s29
	s_mov_b32 m0, s50
	ds_read_b128 v[188:191], v182 offset:49152
	global_load_lds_dwordx4 v146, s[98:99]
	s_add_i32 m0, s50, 0x2000
	s_add_u32 s48, s48, 0x40080
	s_addc_u32 s49, s49, 0
	s_add_i32 s50, s88, s29
	global_load_lds_dwordx4 v150, s[98:99]
	s_mov_b32 m0, s50
	ds_read_b128 v[192:195], v182 offset:50176
	global_load_lds_dwordx4 v146, s[48:49]
	s_add_i32 m0, s50, 0x2000
	ds_read_b128 v[196:199], v182 offset:51200
	global_load_lds_dwordx4 v150, s[48:49]
	s_mov_b32 m0, s63
	ds_read_b128 v[200:203], v182 offset:52224
	global_load_lds_dwordx4 v144, s[100:101]
	s_mov_b32 m0, s64
	ds_read_b128 v[204:207], v182 offset:53248
	global_load_lds_dwordx4 v148, s[100:101]
	ds_read_b128 v[208:211], v182 offset:54272
	ds_read_b128 v[212:215], v182 offset:55296
	ds_read_b128 v[216:219], v182 offset:56320
	s_waitcnt lgkmcnt(0)
	s_barrier
	v_mfma_f32_16x16x32_bf16 v[28:31], v[128:131], v[188:191], v[28:31]
	v_mfma_f32_16x16x32_bf16 v[24:27], v[136:139], v[188:191], v[24:27]
	v_mfma_f32_16x16x32_bf16 v[20:23], v[128:131], v[196:199], v[20:23]
	v_mfma_f32_16x16x32_bf16 v[16:19], v[136:139], v[196:199], v[16:19]
	v_mfma_f32_16x16x32_bf16 v[12:15], v[128:131], v[204:207], v[12:15]
	v_mfma_f32_16x16x32_bf16 v[8:11], v[136:139], v[204:207], v[8:11]
	v_mfma_f32_16x16x32_bf16 v[4:7], v[128:131], v[212:215], v[4:7]
	v_mfma_f32_16x16x32_bf16 v[0:3], v[136:139], v[212:215], v[0:3]
	v_mfma_f32_16x16x32_bf16 v[28:31], v[132:135], v[192:195], v[28:31]
	v_mfma_f32_16x16x32_bf16 v[24:27], v[140:143], v[192:195], v[24:27]
	v_mfma_f32_16x16x32_bf16 v[20:23], v[132:135], v[200:203], v[20:23]
	v_mfma_f32_16x16x32_bf16 v[16:19], v[140:143], v[200:203], v[16:19]
	v_mfma_f32_16x16x32_bf16 v[12:15], v[132:135], v[208:211], v[12:15]
	v_mfma_f32_16x16x32_bf16 v[8:11], v[140:143], v[208:211], v[8:11]
	v_mfma_f32_16x16x32_bf16 v[4:7], v[132:135], v[216:219], v[4:7]
	v_mfma_f32_16x16x32_bf16 v[0:3], v[140:143], v[216:219], v[0:3]
	v_mfma_f32_16x16x32_bf16 v[92:95], v[166:169], v[188:191], v[92:95]
	v_mfma_f32_16x16x32_bf16 v[88:91], v[174:177], v[188:191], v[88:91]
	v_mfma_f32_16x16x32_bf16 v[84:87], v[166:169], v[196:199], v[84:87]
	v_mfma_f32_16x16x32_bf16 v[80:83], v[174:177], v[196:199], v[80:83]
	v_mfma_f32_16x16x32_bf16 v[76:79], v[166:169], v[204:207], v[76:79]
	v_mfma_f32_16x16x32_bf16 v[72:75], v[174:177], v[204:207], v[72:75]
	v_mfma_f32_16x16x32_bf16 v[64:67], v[166:169], v[212:215], v[64:67]
	v_mfma_f32_16x16x32_bf16 v[60:63], v[174:177], v[212:215], v[60:63]
	v_mfma_f32_16x16x32_bf16 v[92:95], v[170:173], v[192:195], v[92:95]
	v_mfma_f32_16x16x32_bf16 v[88:91], v[184:187], v[192:195], v[88:91]
	v_mfma_f32_16x16x32_bf16 v[84:87], v[170:173], v[200:203], v[84:87]
	v_mfma_f32_16x16x32_bf16 v[80:83], v[184:187], v[200:203], v[80:83]
	v_mfma_f32_16x16x32_bf16 v[76:79], v[170:173], v[208:211], v[76:79]
	v_mfma_f32_16x16x32_bf16 v[72:75], v[184:187], v[208:211], v[72:75]
	v_mfma_f32_16x16x32_bf16 v[64:67], v[170:173], v[216:219], v[64:67]
	v_mfma_f32_16x16x32_bf16 v[60:63], v[184:187], v[216:219], v[60:63]
	s_waitcnt vmcnt(8)
	s_barrier
	s_add_i32 s52, s52, 2
	s_add_u32 s46, s46, 0x100
	s_addc_u32 s47, s47, 0
	s_add_u32 s35, s35, 0x100
	s_addc_u32 s45, s45, 0
	s_cmp_gt_u32 s52, 13
	s_cbranch_scc0 .LBB0_564
	s_branch .Lasym_J_564

; #define PG8_BAR __builtin_amdgcn_s_barrier()
; template <class Epi, class Sched, bool ALIGN_EPI = false, bool SP2 = false>
; __device__ __forceinline__ void gemm_phase(PG8_LAS unsigned char* lds, const Gemm g, const Sched& S, const Epi& E, int tid_in) {
;     ...
;         if constexpr (ALIGN_EPI) { if (wr == 0) PG8_BAR; }
.Lasym_J_564:
	s_cmp_eq_u32 s86, 1
	s_cbranch_scc0 .Lww_done_p3
	v_readlane_b32 s98, v248, 0
	s_nop 3
	s_cmp_eq_u32 s98, 0
	s_cbranch_scc0 .Lww_bar_p3
	v_readlane_b32 s98, v248, 32
	s_nop 3
	s_cmp_eq_u32 s98, 1
	s_cbranch_scc0 .Lww_bar_p3
	v_mov_b32_e32 v246, 0x3500
	s_mov_b32 s98, 0

; #define PG8_STAGE(bufoff, gbase, voff) do { _Pragma("unroll") for (int _i = 0; _i < 2; ++_i) \
;         __builtin_amdgcn_global_load_lds((const unsigned*)((const char*)(gbase) + (voff)[_i]), (PG8_LAS unsigned*)(lds + (bufoff) + ldsw + _i * 8192), 16, 0, 0); } while (0)
; #define PG8_LDA(dst, b, h) do { _Pragma("unroll") for (int m = 0; m < 4; ++m) _Pragma("unroll") for (int k = 0; k < 2; ++k) dst[m][k] = *(const PG8_LAS bf16x8*)(lds + PG8_SA(b, h) + aoff + m * 2048 + k * 1024); } while (0)
; #define PG8_LDB(dst, b, h) do { _Pragma("unroll") for (int n = 0; n < 2; ++n) _Pragma("unroll") for (int k = 0; k < 2; ++k) dst[n][k] = *(const PG8_LAS bf16x8*)(lds + PG8_SB(b, h) + boff + n * 2048 + k * 1024); } while (0)
; #define PG8_SCHED __builtin_amdgcn_sched_barrier(0)
; template <class Epi, class Sched, bool ALIGN_EPI = false, bool SP2 = false>
; __device__ __forceinline__ void gemm_phase(PG8_LAS unsigned char* lds, const Gemm g, const Sched& S, const Epi& E, int tid_in) {
;     ...
;             const bool last = (t == nt - 2);
;             const char* a1 = cA + (size_t)(t + 1) * kstep;
;             const char* a2 = last ? nA : cA + (size_t)(t + 2) * kstep; const char* b2 = last ? nB : cB + (size_t)(t + 2) * kstep;
;             const char* a3 = a2 + kstep; const char* b3 = b2 + kstep;
;             if (last && has_next) S.a_ready(nxt);
;             if constexpr (SP2) {
;             PG8_LDB(B0, 0, 0); PG8_LDB(B1, 0, 1); PG8_SCHED; PG8_LDA(At, 0, 0); PG8_STAGE(PG8_SA(1, 1), a1 + hstep, voffA);
;     ...
;         for (int a = 0; a < 2; ++a)
; #pragma unroll
;             for (int b = 0; b < 2; ++b)
; #pragma unroll
;                 for (int m = 0; m < 4; ++m)
; #pragma unroll
;                     for (int n = 0; n < 2; ++n) acc[a][b][m][n] = (f32x4){0.f, 0.f, 0.f, 0.f};
.LBB0_1147:
	s_ashr_i32 s23, s22, 31
	s_lshl_b64 s[24:25], s[22:23], 19
	s_add_u32 s24, s38, s24
	s_addc_u32 s25, s39, s25
	s_and_b64 s[26:27], s[4:5], exec
	s_cselect_b32 s23, s25, s31
	s_cselect_b32 s29, s24, s30
	s_ashr_i32 s21, s20, 31
	s_lshl_b64 s[26:27], s[20:21], 19
	s_add_u32 s26, s44, s26
	s_addc_u32 s27, s45, s27
	s_and_b64 s[36:37], s[4:5], exec
	s_cselect_b32 s21, s27, s35
	s_cselect_b32 s57, s26, s34
	s_add_u32 s30, s30, 0x40080
	s_addc_u32 s31, s31, 0
	s_add_u32 s58, s34, 0x100
	v_mov_b32_e32 v0, 0
	s_addc_u32 s59, s35, 0
	s_mov_b32 s60, -2
	s_waitcnt lgkmcnt(0)
	v_mov_b32_e32 v1, v0
	v_mov_b32_e32 v2, v0
	v_mov_b32_e32 v3, v0
	v_mov_b32_e32 v4, v0
	v_mov_b32_e32 v5, v0
	v_mov_b32_e32 v6, v0
	v_mov_b32_e32 v7, v0
	v_mov_b32_e32 v16, v0
	v_mov_b32_e32 v17, v0
	v_mov_b32_e32 v18, v0
	v_mov_b32_e32 v19, v0
	v_mov_b32_e32 v20, v0
	v_mov_b32_e32 v21, v0
	v_mov_b32_e32 v22, v0
	v_mov_b32_e32 v23, v0
	v_mov_b32_e32 v32, v0
	v_mov_b32_e32 v33, v0
	v_mov_b32_e32 v34, v0
	v_mov_b32_e32 v35, v0
	v_mov_b32_e32 v36, v0
	v_mov_b32_e32 v37, v0
	v_mov_b32_e32 v38, v0
	v_mov_b32_e32 v39, v0
	v_mov_b32_e32 v48, v0
	v_mov_b32_e32 v49, v0
	v_mov_b32_e32 v50, v0
	v_mov_b32_e32 v51, v0
	v_mov_b32_e32 v52, v0
	v_mov_b32_e32 v53, v0
	v_mov_b32_e32 v54, v0
	v_mov_b32_e32 v55, v0
	v_mov_b32_e32 v8, v0
	v_mov_b32_e32 v9, v0
	v_mov_b32_e32 v10, v0
	v_mov_b32_e32 v11, v0
	v_mov_b32_e32 v12, v0
	v_mov_b32_e32 v13, v0
	v_mov_b32_e32 v14, v0
	v_mov_b32_e32 v15, v0
	v_mov_b32_e32 v24, v0
	v_mov_b32_e32 v25, v0
	v_mov_b32_e32 v26, v0
	v_mov_b32_e32 v27, v0
	v_mov_b32_e32 v28, v0
	v_mov_b32_e32 v29, v0
	v_mov_b32_e32 v30, v0
	v_mov_b32_e32 v31, v0
	v_mov_b32_e32 v40, v0
	v_mov_b32_e32 v41, v0
	v_mov_b32_e32 v42, v0
	v_mov_b32_e32 v43, v0
	v_mov_b32_e32 v44, v0
	v_mov_b32_e32 v45, v0
	v_mov_b32_e32 v46, v0
	v_mov_b32_e32 v47, v0
	v_mov_b32_e32 v56, v0
	v_mov_b32_e32 v57, v0
	v_mov_b32_e32 v58, v0
	v_mov_b32_e32 v59, v0
	v_mov_b32_e32 v60, v0
	v_mov_b32_e32 v61, v0
	v_mov_b32_e32 v62, v0
	v_mov_b32_e32 v63, v0
	v_mov_b32_e32 v64, v0
	v_mov_b32_e32 v65, v0
	v_mov_b32_e32 v66, v0
	v_mov_b32_e32 v67, v0
	v_mov_b32_e32 v68, v0
	v_mov_b32_e32 v69, v0
	v_mov_b32_e32 v70, v0
	v_mov_b32_e32 v71, v0
	v_mov_b32_e32 v80, v0
	v_mov_b32_e32 v81, v0
	v_mov_b32_e32 v82, v0
	v_mov_b32_e32 v83, v0
	v_mov_b32_e32 v84, v0
	v_mov_b32_e32 v85, v0
	v_mov_b32_e32 v86, v0
	v_mov_b32_e32 v87, v0
	v_mov_b32_e32 v96, v0
	v_mov_b32_e32 v97, v0
	v_mov_b32_e32 v98, v0
	v_mov_b32_e32 v99, v0
	v_mov_b32_e32 v100, v0
	v_mov_b32_e32 v101, v0
	v_mov_b32_e32 v102, v0
	v_mov_b32_e32 v103, v0
	v_mov_b32_e32 v112, v0
	v_mov_b32_e32 v113, v0
	v_mov_b32_e32 v114, v0
	v_mov_b32_e32 v115, v0
	v_mov_b32_e32 v116, v0
	v_mov_b32_e32 v117, v0
	v_mov_b32_e32 v118, v0
	v_mov_b32_e32 v119, v0
	v_mov_b32_e32 v72, v0
	v_mov_b32_e32 v73, v0
	v_mov_b32_e32 v74, v0
	v_mov_b32_e32 v75, v0
	v_mov_b32_e32 v76, v0
	v_mov_b32_e32 v77, v0
	v_mov_b32_e32 v78, v0
	v_mov_b32_e32 v79, v0
	v_mov_b32_e32 v88, v0
	v_mov_b32_e32 v89, v0
	v_mov_b32_e32 v90, v0
	v_mov_b32_e32 v91, v0
	v_mov_b32_e32 v92, v0
	v_mov_b32_e32 v93, v0
	v_mov_b32_e32 v94, v0
	v_mov_b32_e32 v95, v0
	v_mov_b32_e32 v104, v0
	v_mov_b32_e32 v105, v0
	v_mov_b32_e32 v106, v0
	v_mov_b32_e32 v107, v0
	v_mov_b32_e32 v108, v0
	v_mov_b32_e32 v109, v0
	v_mov_b32_e32 v110, v0
	v_mov_b32_e32 v111, v0
	v_mov_b32_e32 v120, v0
	v_mov_b32_e32 v121, v0
	v_mov_b32_e32 v122, v0
	v_mov_b32_e32 v123, v0
	v_mov_b32_e32 v124, v0
	v_mov_b32_e32 v125, v0
	v_mov_b32_e32 v126, v0
	v_mov_b32_e32 v127, v0
	s_cmp_lg_u64 s[18:19], 0
	s_cbranch_scc0 .Lasym_T_1148
.LBB0_1148:
	s_add_u32 s34, s30, 0xfffc0080
	s_addc_u32 s35, s31, -1
	s_cmp_eq_u32 s60, 12
	s_cselect_b32 s37, s23, s35
	s_cselect_b32 s36, s29, s34
	s_cselect_b32 s35, s21, s59
	s_cselect_b32 s34, s57, s58
	s_add_i32 m0, s1, 0xc000
	ds_read_b128 v[128:131], v191
	global_load_lds_dwordx4 v160, s[30:31]
	s_add_i32 m0, s1, 0xe000
	ds_read_b128 v[132:135], v191 offset:1024
	global_load_lds_dwordx4 v162, s[30:31]
	ds_read_b128 v[136:139], v191 offset:2048
	ds_read_b128 v[140:143], v191 offset:3072
	ds_read_b128 v[144:147], v192
	ds_read_b128 v[148:151], v192 offset:1024
	ds_read_b128 v[168:171], v192 offset:2048
	ds_read_b128 v[172:175], v192 offset:3072
	ds_read_b128 v[176:179], v193
	ds_read_b128 v[180:183], v193 offset:1024
	ds_read_b128 v[194:197], v193 offset:2048
	ds_read_b128 v[198:201], v193 offset:3072
	ds_read_b128 v[202:205], v193 offset:4096
	ds_read_b128 v[206:209], v193 offset:5120
	ds_read_b128 v[210:213], v193 offset:6144
	ds_read_b128 v[214:217], v193 offset:7168
	s_waitcnt lgkmcnt(0)
	s_barrier
; #define PG8_STAGE(bufoff, gbase, voff) do { _Pragma("unroll") for (int _i = 0; _i < 2; ++_i) \
;         __builtin_amdgcn_global_load_lds((const unsigned*)((const char*)(gbase) + (voff)[_i]), (PG8_LAS unsigned*)(lds + (bufoff) + ldsw + _i * 8192), 16, 0, 0); } while (0)
; #define PG8_LDA(dst, b, h) do { _Pragma("unroll") for (int m = 0; m < 4; ++m) _Pragma("unroll") for (int k = 0; k < 2; ++k) dst[m][k] = *(const PG8_LAS bf16x8*)(lds + PG8_SA(b, h) + aoff + m * 2048 + k * 1024); } while (0)
; #define PG8_MMA(ai, bj, At, Bt) do { __builtin_amdgcn_s_setprio(1); _Pragma("unroll") for (int m = 0; m < 4; ++m) _Pragma("unroll") for (int n = 0; n < 2; ++n) _Pragma("unroll") for (int k = 0; k < 2; ++k) \
;         acc[ai][bj][m][n] = __builtin_amdgcn_mfma_f32_16x16x32_bf16(Bt[n][k], At[m][k], acc[ai][bj][m][n], 0, 0, 0); __builtin_amdgcn_s_setprio(0); } while (0)
; #define PG8_WAIT_V(n) asm volatile("s_waitcnt vmcnt(" #n ")" ::: "memory")
; #define PG8_WAIT_L(n) asm volatile("s_waitcnt lgkmcnt(" #n ")" ::: "memory")
; #define PG8_BAR __builtin_amdgcn_s_barrier()
; #define PG8_SCHED __builtin_amdgcn_sched_barrier(0)
; template <class Epi, class Sched, bool ALIGN_EPI = false, bool SP2 = false>
; __device__ __forceinline__ void gemm_phase(PG8_LAS unsigned char* lds, const Gemm g, const Sched& S, const Epi& E, int tid_in) {
;     ...
;             PG8_WAIT_V(8); PG8_WAIT_L(0); PG8_BAR; PG8_MMA(0, 0, At, B0); PG8_MMA(0, 1, At, B1); PG8_BAR; PG8_SCHED;
;             PG8_LDA(At, 0, 1); PG8_STAGE(PG8_SB(0, 0), b2, voffB); PG8_STAGE(PG8_SB(0, 1), b2 + hstep, voffB); PG8_STAGE(PG8_SA(0, 0), a2, voffA);
;             PG8_WAIT_V(8); PG8_WAIT_L(0); PG8_BAR; PG8_MMA(1, 0, At, B0); PG8_MMA(1, 1, At, B1); PG8_BAR; PG8_SCHED;
	v_mfma_f32_16x16x32_bf16 v[124:127], v[128:131], v[176:179], v[124:127]
	v_mfma_f32_16x16x32_bf16 v[120:123], v[136:139], v[176:179], v[120:123]
	v_mfma_f32_16x16x32_bf16 v[108:111], v[128:131], v[194:197], v[108:111]
	v_mfma_f32_16x16x32_bf16 v[104:107], v[136:139], v[194:197], v[104:107]
	v_mfma_f32_16x16x32_bf16 v[92:95], v[128:131], v[202:205], v[92:95]
	v_mfma_f32_16x16x32_bf16 v[88:91], v[136:139], v[202:205], v[88:91]
	v_mfma_f32_16x16x32_bf16 v[76:79], v[128:131], v[210:213], v[76:79]
	v_mfma_f32_16x16x32_bf16 v[72:75], v[136:139], v[210:213], v[72:75]
	v_mfma_f32_16x16x32_bf16 v[124:127], v[132:135], v[180:183], v[124:127]
	v_mfma_f32_16x16x32_bf16 v[120:123], v[140:143], v[180:183], v[120:123]
	v_mfma_f32_16x16x32_bf16 v[108:111], v[132:135], v[198:201], v[108:111]
	v_mfma_f32_16x16x32_bf16 v[104:107], v[140:143], v[198:201], v[104:107]
	v_mfma_f32_16x16x32_bf16 v[92:95], v[132:135], v[206:209], v[92:95]
	v_mfma_f32_16x16x32_bf16 v[88:91], v[140:143], v[206:209], v[88:91]
	v_mfma_f32_16x16x32_bf16 v[76:79], v[132:135], v[214:217], v[76:79]
	v_mfma_f32_16x16x32_bf16 v[72:75], v[140:143], v[214:217], v[72:75]
	v_mfma_f32_16x16x32_bf16 v[116:119], v[144:147], v[176:179], v[116:119]
	v_mfma_f32_16x16x32_bf16 v[112:115], v[168:171], v[176:179], v[112:115]
	v_mfma_f32_16x16x32_bf16 v[100:103], v[144:147], v[194:197], v[100:103]
	v_mfma_f32_16x16x32_bf16 v[96:99], v[168:171], v[194:197], v[96:99]
	v_mfma_f32_16x16x32_bf16 v[84:87], v[144:147], v[202:205], v[84:87]
	v_mfma_f32_16x16x32_bf16 v[80:83], v[168:171], v[202:205], v[80:83]
	v_mfma_f32_16x16x32_bf16 v[68:71], v[144:147], v[210:213], v[68:71]
	v_mfma_f32_16x16x32_bf16 v[64:67], v[168:171], v[210:213], v[64:67]
	v_mfma_f32_16x16x32_bf16 v[116:119], v[148:151], v[180:183], v[116:119]
	v_mfma_f32_16x16x32_bf16 v[112:115], v[172:175], v[180:183], v[112:115]
	v_mfma_f32_16x16x32_bf16 v[100:103], v[148:151], v[198:201], v[100:103]
	v_mfma_f32_16x16x32_bf16 v[96:99], v[172:175], v[198:201], v[96:99]
	v_mfma_f32_16x16x32_bf16 v[84:87], v[148:151], v[206:209], v[84:87]
	v_mfma_f32_16x16x32_bf16 v[80:83], v[172:175], v[206:209], v[80:83]
	v_mfma_f32_16x16x32_bf16 v[68:71], v[148:151], v[214:217], v[68:71]
	v_mfma_f32_16x16x32_bf16 v[64:67], v[172:175], v[214:217], v[64:67]
	s_waitcnt vmcnt(8)
	s_barrier
	s_add_u32 s98, s34, s16
	s_addc_u32 s99, s35, s17
	s_add_u32 s100, s36, s16
	s_addc_u32 s101, s37, s17
	s_add_i32 s61, s54, s0
	s_mov_b32 m0, s61
	ds_read_b128 v[176:179], v193 offset:16384
	global_load_lds_dwordx4 v154, s[34:35]
	s_add_i32 m0, s61, 0x2000
	s_add_u32 s62, s34, 0x40000
	s_addc_u32 s63, s35, 0
	s_add_i32 s61, s55, s0
	global_load_lds_dwordx4 v158, s[34:35]
	s_mov_b32 m0, s61
	ds_read_b128 v[180:183], v193 offset:17408
	global_load_lds_dwordx4 v154, s[62:63]
	s_add_i32 m0, s61, 0x2000
	ds_read_b128 v[194:197], v193 offset:18432
	global_load_lds_dwordx4 v158, s[62:63]
	s_mov_b32 m0, s1
	ds_read_b128 v[198:201], v193 offset:19456
	global_load_lds_dwordx4 v152, s[36:37]
	s_mov_b32 m0, s46
	ds_read_b128 v[202:205], v193 offset:20480
	global_load_lds_dwordx4 v156, s[36:37]
	ds_read_b128 v[206:209], v193 offset:21504
	ds_read_b128 v[210:213], v193 offset:22528
	ds_read_b128 v[214:217], v193 offset:23552
	s_waitcnt lgkmcnt(0)
	s_barrier
	v_mfma_f32_16x16x32_bf16 v[60:63], v[128:131], v[176:179], v[60:63]
	v_mfma_f32_16x16x32_bf16 v[56:59], v[136:139], v[176:179], v[56:59]
	v_mfma_f32_16x16x32_bf16 v[44:47], v[128:131], v[194:197], v[44:47]
	v_mfma_f32_16x16x32_bf16 v[40:43], v[136:139], v[194:197], v[40:43]
	v_mfma_f32_16x16x32_bf16 v[28:31], v[128:131], v[202:205], v[28:31]
	v_mfma_f32_16x16x32_bf16 v[24:27], v[136:139], v[202:205], v[24:27]
	v_mfma_f32_16x16x32_bf16 v[12:15], v[128:131], v[210:213], v[12:15]
	v_mfma_f32_16x16x32_bf16 v[8:11], v[136:139], v[210:213], v[8:11]
	v_mfma_f32_16x16x32_bf16 v[60:63], v[132:135], v[180:183], v[60:63]
	v_mfma_f32_16x16x32_bf16 v[56:59], v[140:143], v[180:183], v[56:59]
	v_mfma_f32_16x16x32_bf16 v[44:47], v[132:135], v[198:201], v[44:47]
	v_mfma_f32_16x16x32_bf16 v[40:43], v[140:143], v[198:201], v[40:43]
	v_mfma_f32_16x16x32_bf16 v[28:31], v[132:135], v[206:209], v[28:31]
	v_mfma_f32_16x16x32_bf16 v[24:27], v[140:143], v[206:209], v[24:27]
	v_mfma_f32_16x16x32_bf16 v[12:15], v[132:135], v[214:217], v[12:15]
	v_mfma_f32_16x16x32_bf16 v[8:11], v[140:143], v[214:217], v[8:11]
	v_mfma_f32_16x16x32_bf16 v[52:55], v[144:147], v[176:179], v[52:55]
	v_mfma_f32_16x16x32_bf16 v[48:51], v[168:171], v[176:179], v[48:51]
	v_mfma_f32_16x16x32_bf16 v[36:39], v[144:147], v[194:197], v[36:39]
	v_mfma_f32_16x16x32_bf16 v[32:35], v[168:171], v[194:197], v[32:35]
	v_mfma_f32_16x16x32_bf16 v[20:23], v[144:147], v[202:205], v[20:23]
	v_mfma_f32_16x16x32_bf16 v[16:19], v[168:171], v[202:205], v[16:19]
	v_mfma_f32_16x16x32_bf16 v[4:7], v[144:147], v[210:213], v[4:7]
	v_mfma_f32_16x16x32_bf16 v[0:3], v[168:171], v[210:213], v[0:3]
	v_mfma_f32_16x16x32_bf16 v[52:55], v[148:151], v[180:183], v[52:55]
	v_mfma_f32_16x16x32_bf16 v[48:51], v[172:175], v[180:183], v[48:51]
	v_mfma_f32_16x16x32_bf16 v[36:39], v[148:151], v[198:201], v[36:39]
	v_mfma_f32_16x16x32_bf16 v[32:35], v[172:175], v[198:201], v[32:35]
	v_mfma_f32_16x16x32_bf16 v[20:23], v[148:151], v[206:209], v[20:23]
	v_mfma_f32_16x16x32_bf16 v[16:19], v[172:175], v[206:209], v[16:19]
	v_mfma_f32_16x16x32_bf16 v[4:7], v[148:151], v[214:217], v[4:7]
	v_mfma_f32_16x16x32_bf16 v[0:3], v[172:175], v[214:217], v[0:3]
	s_waitcnt vmcnt(8)
	s_barrier
; #define PG8_STAGE(bufoff, gbase, voff) do { _Pragma("unroll") for (int _i = 0; _i < 2; ++_i) \
;         __builtin_amdgcn_global_load_lds((const unsigned*)((const char*)(gbase) + (voff)[_i]), (PG8_LAS unsigned*)(lds + (bufoff) + ldsw + _i * 8192), 16, 0, 0); } while (0)
; #define PG8_LDA(dst, b, h) do { _Pragma("unroll") for (int m = 0; m < 4; ++m) _Pragma("unroll") for (int k = 0; k < 2; ++k) dst[m][k] = *(const PG8_LAS bf16x8*)(lds + PG8_SA(b, h) + aoff + m * 2048 + k * 1024); } while (0)
; #define PG8_LDB(dst, b, h) do { _Pragma("unroll") for (int n = 0; n < 2; ++n) _Pragma("unroll") for (int k = 0; k < 2; ++k) dst[n][k] = *(const PG8_LAS bf16x8*)(lds + PG8_SB(b, h) + boff + n * 2048 + k * 1024); } while (0)
; #define PG8_MMA(ai, bj, At, Bt) do { __builtin_amdgcn_s_setprio(1); _Pragma("unroll") for (int m = 0; m < 4; ++m) _Pragma("unroll") for (int n = 0; n < 2; ++n) _Pragma("unroll") for (int k = 0; k < 2; ++k) \
;         acc[ai][bj][m][n] = __builtin_amdgcn_mfma_f32_16x16x32_bf16(Bt[n][k], At[m][k], acc[ai][bj][m][n], 0, 0, 0); __builtin_amdgcn_s_setprio(0); } while (0)
; #define PG8_WAIT_V(n) asm volatile("s_waitcnt vmcnt(" #n ")" ::: "memory")
; #define PG8_WAIT_L(n) asm volatile("s_waitcnt lgkmcnt(" #n ")" ::: "memory")
; #define PG8_BAR __builtin_amdgcn_s_barrier()
; #define PG8_SCHED __builtin_amdgcn_sched_barrier(0)
; template <class Epi, class Sched, bool ALIGN_EPI = false, bool SP2 = false>
; __device__ __forceinline__ void gemm_phase(PG8_LAS unsigned char* lds, const Gemm g, const Sched& S, const Epi& E, int tid_in) {
;     ...
;             PG8_LDB(B0, 1, 0); PG8_LDB(B1, 1, 1); PG8_SCHED; PG8_LDA(At, 1, 0); PG8_STAGE(PG8_SA(0, 1), a2 + hstep, voffA);
;             PG8_WAIT_V(8); PG8_WAIT_L(0); PG8_BAR; PG8_MMA(0, 0, At, B0); PG8_MMA(0, 1, At, B1); PG8_BAR; PG8_SCHED;
;             PG8_LDA(At, 1, 1); PG8_STAGE(PG8_SB(1, 0), b3, voffB); PG8_STAGE(PG8_SB(1, 1), b3 + hstep, voffB); PG8_STAGE(PG8_SA(1, 0), a3, voffA);
;             PG8_WAIT_V(8); PG8_WAIT_L(0); PG8_BAR; PG8_MMA(1, 0, At, B0); PG8_MMA(1, 1, At, B1); PG8_BAR; PG8_SCHED;
	s_add_i32 s61, 0, 0x18000
	s_add_i32 s62, 0, 0x1c000
	s_add_u32 s36, s36, 0x40000
	s_addc_u32 s37, s37, 0
	s_mov_b32 m0, s47
	s_nop 0
	global_load_lds_dwordx4 v152, s[36:37]
	s_mov_b32 m0, s48
	s_nop 0
	global_load_lds_dwordx4 v156, s[36:37]
	v_add_u32_e32 v140, s61, v187
	v_add_u32_e32 v172, s62, v187
	ds_read_b128 v[128:131], v140
	ds_read_b128 v[132:135], v140 offset:1024
	ds_read_b128 v[136:139], v140 offset:2048
	ds_read_b128 v[140:143], v140 offset:3072
	ds_read_b128 v[144:147], v172
	ds_read_b128 v[148:151], v172 offset:1024
	ds_read_b128 v[168:171], v172 offset:2048
	ds_read_b128 v[172:175], v172 offset:3072
	ds_read_b128 v[176:179], v193 offset:32768
	ds_read_b128 v[180:183], v193 offset:33792
	ds_read_b128 v[194:197], v193 offset:34816
	ds_read_b128 v[198:201], v193 offset:35840
	ds_read_b128 v[202:205], v193 offset:36864
	ds_read_b128 v[206:209], v193 offset:37888
	ds_read_b128 v[210:213], v193 offset:38912
	ds_read_b128 v[214:217], v193 offset:39936
	s_waitcnt lgkmcnt(0)
	s_barrier
	v_mfma_f32_16x16x32_bf16 v[124:127], v[128:131], v[176:179], v[124:127]
	v_mfma_f32_16x16x32_bf16 v[120:123], v[136:139], v[176:179], v[120:123]
	v_mfma_f32_16x16x32_bf16 v[108:111], v[128:131], v[194:197], v[108:111]
	v_mfma_f32_16x16x32_bf16 v[104:107], v[136:139], v[194:197], v[104:107]
	v_mfma_f32_16x16x32_bf16 v[92:95], v[128:131], v[202:205], v[92:95]
	v_mfma_f32_16x16x32_bf16 v[88:91], v[136:139], v[202:205], v[88:91]
	v_mfma_f32_16x16x32_bf16 v[76:79], v[128:131], v[210:213], v[76:79]
	v_mfma_f32_16x16x32_bf16 v[72:75], v[136:139], v[210:213], v[72:75]
	v_mfma_f32_16x16x32_bf16 v[124:127], v[132:135], v[180:183], v[124:127]
	v_mfma_f32_16x16x32_bf16 v[120:123], v[140:143], v[180:183], v[120:123]
	v_mfma_f32_16x16x32_bf16 v[108:111], v[132:135], v[198:201], v[108:111]
	v_mfma_f32_16x16x32_bf16 v[104:107], v[140:143], v[198:201], v[104:107]
	v_mfma_f32_16x16x32_bf16 v[92:95], v[132:135], v[206:209], v[92:95]
	v_mfma_f32_16x16x32_bf16 v[88:91], v[140:143], v[206:209], v[88:91]
	v_mfma_f32_16x16x32_bf16 v[76:79], v[132:135], v[214:217], v[76:79]
	v_mfma_f32_16x16x32_bf16 v[72:75], v[140:143], v[214:217], v[72:75]
	v_mfma_f32_16x16x32_bf16 v[116:119], v[144:147], v[176:179], v[116:119]
	v_mfma_f32_16x16x32_bf16 v[112:115], v[168:171], v[176:179], v[112:115]
	v_mfma_f32_16x16x32_bf16 v[100:103], v[144:147], v[194:197], v[100:103]
	v_mfma_f32_16x16x32_bf16 v[96:99], v[168:171], v[194:197], v[96:99]
	v_mfma_f32_16x16x32_bf16 v[84:87], v[144:147], v[202:205], v[84:87]
	v_mfma_f32_16x16x32_bf16 v[80:83], v[168:171], v[202:205], v[80:83]
	v_mfma_f32_16x16x32_bf16 v[68:71], v[144:147], v[210:213], v[68:71]
	v_mfma_f32_16x16x32_bf16 v[64:67], v[168:171], v[210:213], v[64:67]
	v_mfma_f32_16x16x32_bf16 v[116:119], v[148:151], v[180:183], v[116:119]
	v_mfma_f32_16x16x32_bf16 v[112:115], v[172:175], v[180:183], v[112:115]
	v_mfma_f32_16x16x32_bf16 v[100:103], v[148:151], v[198:201], v[100:103]
	v_mfma_f32_16x16x32_bf16 v[96:99], v[172:175], v[198:201], v[96:99]
	v_mfma_f32_16x16x32_bf16 v[84:87], v[148:151], v[206:209], v[84:87]
	v_mfma_f32_16x16x32_bf16 v[80:83], v[172:175], v[206:209], v[80:83]
	v_mfma_f32_16x16x32_bf16 v[68:71], v[148:151], v[214:217], v[68:71]
	v_mfma_f32_16x16x32_bf16 v[64:67], v[172:175], v[214:217], v[64:67]
	s_waitcnt vmcnt(8)
	s_barrier
	s_add_i32 s36, s61, s0
	s_mov_b32 m0, s36
	ds_read_b128 v[176:179], v193 offset:49152
	global_load_lds_dwordx4 v154, s[98:99]
	s_add_i32 m0, s36, 0x2000
	s_add_u32 s34, s34, 0x40080
	s_addc_u32 s35, s35, 0
	s_add_i32 s36, s62, s0
	global_load_lds_dwordx4 v158, s[98:99]
	s_mov_b32 m0, s36
	ds_read_b128 v[180:183], v193 offset:50176
	global_load_lds_dwordx4 v154, s[34:35]
	s_add_i32 m0, s36, 0x2000
	ds_read_b128 v[194:197], v193 offset:51200
	global_load_lds_dwordx4 v158, s[34:35]
	s_mov_b32 m0, s50
	ds_read_b128 v[198:201], v193 offset:52224
	global_load_lds_dwordx4 v152, s[100:101]
	s_mov_b32 m0, s51
	ds_read_b128 v[202:205], v193 offset:53248
	global_load_lds_dwordx4 v156, s[100:101]
	ds_read_b128 v[206:209], v193 offset:54272
	ds_read_b128 v[210:213], v193 offset:55296
	ds_read_b128 v[214:217], v193 offset:56320
	s_waitcnt lgkmcnt(0)
	s_barrier
	v_mfma_f32_16x16x32_bf16 v[60:63], v[128:131], v[176:179], v[60:63]
	v_mfma_f32_16x16x32_bf16 v[56:59], v[136:139], v[176:179], v[56:59]
	v_mfma_f32_16x16x32_bf16 v[44:47], v[128:131], v[194:197], v[44:47]
	v_mfma_f32_16x16x32_bf16 v[40:43], v[136:139], v[194:197], v[40:43]
	v_mfma_f32_16x16x32_bf16 v[28:31], v[128:131], v[202:205], v[28:31]
	v_mfma_f32_16x16x32_bf16 v[24:27], v[136:139], v[202:205], v[24:27]
	v_mfma_f32_16x16x32_bf16 v[12:15], v[128:131], v[210:213], v[12:15]
	v_mfma_f32_16x16x32_bf16 v[8:11], v[136:139], v[210:213], v[8:11]
	v_mfma_f32_16x16x32_bf16 v[60:63], v[132:135], v[180:183], v[60:63]
	v_mfma_f32_16x16x32_bf16 v[56:59], v[140:143], v[180:183], v[56:59]
	v_mfma_f32_16x16x32_bf16 v[44:47], v[132:135], v[198:201], v[44:47]
	v_mfma_f32_16x16x32_bf16 v[40:43], v[140:143], v[198:201], v[40:43]
	v_mfma_f32_16x16x32_bf16 v[28:31], v[132:135], v[206:209], v[28:31]
	v_mfma_f32_16x16x32_bf16 v[24:27], v[140:143], v[206:209], v[24:27]
	v_mfma_f32_16x16x32_bf16 v[12:15], v[132:135], v[214:217], v[12:15]
	v_mfma_f32_16x16x32_bf16 v[8:11], v[140:143], v[214:217], v[8:11]
	v_mfma_f32_16x16x32_bf16 v[52:55], v[144:147], v[176:179], v[52:55]
	v_mfma_f32_16x16x32_bf16 v[48:51], v[168:171], v[176:179], v[48:51]
	v_mfma_f32_16x16x32_bf16 v[36:39], v[144:147], v[194:197], v[36:39]
	v_mfma_f32_16x16x32_bf16 v[32:35], v[168:171], v[194:197], v[32:35]
	v_mfma_f32_16x16x32_bf16 v[20:23], v[144:147], v[202:205], v[20:23]
	v_mfma_f32_16x16x32_bf16 v[16:19], v[168:171], v[202:205], v[16:19]
	v_mfma_f32_16x16x32_bf16 v[4:7], v[144:147], v[210:213], v[4:7]
	v_mfma_f32_16x16x32_bf16 v[0:3], v[168:171], v[210:213], v[0:3]
	v_mfma_f32_16x16x32_bf16 v[52:55], v[148:151], v[180:183], v[52:55]
	v_mfma_f32_16x16x32_bf16 v[48:51], v[172:175], v[180:183], v[48:51]
	v_mfma_f32_16x16x32_bf16 v[36:39], v[148:151], v[198:201], v[36:39]
	v_mfma_f32_16x16x32_bf16 v[32:35], v[172:175], v[198:201], v[32:35]
	v_mfma_f32_16x16x32_bf16 v[20:23], v[148:151], v[206:209], v[20:23]
	v_mfma_f32_16x16x32_bf16 v[16:19], v[172:175], v[206:209], v[16:19]
	v_mfma_f32_16x16x32_bf16 v[4:7], v[148:151], v[214:217], v[4:7]
	v_mfma_f32_16x16x32_bf16 v[0:3], v[172:175], v[214:217], v[0:3]
	s_waitcnt vmcnt(8)
	s_barrier
	s_add_i32 s60, s60, 2
	s_add_u32 s30, s30, 0x100
	s_addc_u32 s31, s31, 0
	s_add_u32 s58, s58, 0x100
	s_addc_u32 s59, s59, 0
	s_cmp_gt_u32 s60, 13
	s_cbranch_scc0 .LBB0_1148
	s_branch .Lasym_J_1148

; #define PG8_BAR __builtin_amdgcn_s_barrier()
; template <class Epi, class Sched, bool ALIGN_EPI = false, bool SP2 = false>
; __device__ __forceinline__ void gemm_phase(PG8_LAS unsigned char* lds, const Gemm g, const Sched& S, const Epi& E, int tid_in) {
;     ...
;         if constexpr (ALIGN_EPI) { if (wr == 0) PG8_BAR; }
.Lasym_J_1148:
	s_and_b64 vcc, exec, s[18:19]
	s_cbranch_vccz .LBB0_1151
	s_barrier

; #define PG8_STAGE(bufoff, gbase, voff) do { _Pragma("unroll") for (int _i = 0; _i < 2; ++_i) \
;         __builtin_amdgcn_global_load_lds((const unsigned*)((const char*)(gbase) + (voff)[_i]), (PG8_LAS unsigned*)(lds + (bufoff) + ldsw + _i * 8192), 16, 0, 0); } while (0)
; #define PG8_LDA(dst, b, h) do { _Pragma("unroll") for (int m = 0; m < 4; ++m) _Pragma("unroll") for (int k = 0; k < 2; ++k) dst[m][k] = *(const PG8_LAS bf16x8*)(lds + PG8_SA(b, h) + aoff + m * 2048 + k * 1024); } while (0)
; #define PG8_LDB(dst, b, h) do { _Pragma("unroll") for (int n = 0; n < 2; ++n) _Pragma("unroll") for (int k = 0; k < 2; ++k) dst[n][k] = *(const PG8_LAS bf16x8*)(lds + PG8_SB(b, h) + boff + n * 2048 + k * 1024); } while (0)
; #define PG8_SCHED __builtin_amdgcn_sched_barrier(0)
; template <class Epi, class Sched, bool ALIGN_EPI = false, bool SP2 = false>
; __device__ __forceinline__ void gemm_phase(PG8_LAS unsigned char* lds, const Gemm g, const Sched& S, const Epi& E, int tid_in) {
;     ...
;             const bool last = (t == nt - 2);
;             const char* a1 = cA + (size_t)(t + 1) * kstep;
;             const char* a2 = last ? nA : cA + (size_t)(t + 2) * kstep; const char* b2 = last ? nB : cB + (size_t)(t + 2) * kstep;
;             const char* a3 = a2 + kstep; const char* b3 = b2 + kstep;
;             if (last && has_next) S.a_ready(nxt);
;             if constexpr (SP2) {
;             PG8_LDB(B0, 0, 0); PG8_LDB(B1, 0, 1); PG8_SCHED; PG8_LDA(At, 0, 0); PG8_STAGE(PG8_SA(1, 1), a1 + hstep, voffA);
;     ...
;         for (int a = 0; a < 2; ++a)
; #pragma unroll
;             for (int b = 0; b < 2; ++b)
; #pragma unroll
;                 for (int m = 0; m < 4; ++m)
; #pragma unroll
;                     for (int n = 0; n < 2; ++n) acc[a][b][m][n] = (f32x4){0.f, 0.f, 0.f, 0.f};
.LBB0_1237:
	s_ashr_i32 s17, s16, 31
	s_lshl_b64 s[18:19], s[16:17], 19
	s_add_u32 s18, s1, s18
	s_addc_u32 s19, s30, s19
	s_and_b64 s[20:21], s[2:3], exec
	s_cselect_b32 s17, s19, s25
	s_cselect_b32 s54, s18, s24
	s_ashr_i32 s15, s14, 31
	s_lshl_b64 s[20:21], s[14:15], 19
	s_add_u32 s20, s31, s20
	s_addc_u32 s21, s34, s21
	s_and_b64 s[28:29], s[2:3], exec
	s_cselect_b32 s15, s21, s27
	s_cselect_b32 s55, s20, s26
	s_add_u32 s24, s24, 0x40080
	s_addc_u32 s25, s25, 0
	s_add_u32 s56, s26, 0x100
	v_mov_b32_e32 v0, 0
	s_addc_u32 s57, s27, 0
	s_mov_b32 s58, -2
	v_mov_b32_e32 v1, v0
	v_mov_b32_e32 v2, v0
	v_mov_b32_e32 v3, v0
	v_mov_b32_e32 v4, v0
	v_mov_b32_e32 v5, v0
	v_mov_b32_e32 v6, v0
	v_mov_b32_e32 v7, v0
	v_mov_b32_e32 v16, v0
	v_mov_b32_e32 v17, v0
	v_mov_b32_e32 v18, v0
	v_mov_b32_e32 v19, v0
	v_mov_b32_e32 v20, v0
	v_mov_b32_e32 v21, v0
	v_mov_b32_e32 v22, v0
	v_mov_b32_e32 v23, v0
	v_mov_b32_e32 v32, v0
	v_mov_b32_e32 v33, v0
	v_mov_b32_e32 v34, v0
	v_mov_b32_e32 v35, v0
	v_mov_b32_e32 v36, v0
	v_mov_b32_e32 v37, v0
	v_mov_b32_e32 v38, v0
	v_mov_b32_e32 v39, v0
	v_mov_b32_e32 v48, v0
	v_mov_b32_e32 v49, v0
	v_mov_b32_e32 v50, v0
	v_mov_b32_e32 v51, v0
	v_mov_b32_e32 v52, v0
	v_mov_b32_e32 v53, v0
	v_mov_b32_e32 v54, v0
	v_mov_b32_e32 v55, v0
	v_mov_b32_e32 v8, v0
	v_mov_b32_e32 v9, v0
	v_mov_b32_e32 v10, v0
	v_mov_b32_e32 v11, v0
	v_mov_b32_e32 v12, v0
	v_mov_b32_e32 v13, v0
	v_mov_b32_e32 v14, v0
	v_mov_b32_e32 v15, v0
	v_mov_b32_e32 v24, v0
	v_mov_b32_e32 v25, v0
	v_mov_b32_e32 v26, v0
	v_mov_b32_e32 v27, v0
	v_mov_b32_e32 v28, v0
	v_mov_b32_e32 v29, v0
	v_mov_b32_e32 v30, v0
	v_mov_b32_e32 v31, v0
	v_mov_b32_e32 v40, v0
	v_mov_b32_e32 v41, v0
	v_mov_b32_e32 v42, v0
	v_mov_b32_e32 v43, v0
	v_mov_b32_e32 v44, v0
	v_mov_b32_e32 v45, v0
	v_mov_b32_e32 v46, v0
	v_mov_b32_e32 v47, v0
	v_mov_b32_e32 v56, v0
	v_mov_b32_e32 v57, v0
	v_mov_b32_e32 v58, v0
	v_mov_b32_e32 v59, v0
	v_mov_b32_e32 v60, v0
	v_mov_b32_e32 v61, v0
	v_mov_b32_e32 v62, v0
	v_mov_b32_e32 v63, v0
	v_mov_b32_e32 v64, v0
	v_mov_b32_e32 v65, v0
	v_mov_b32_e32 v66, v0
	v_mov_b32_e32 v67, v0
	v_mov_b32_e32 v68, v0
	v_mov_b32_e32 v69, v0
	v_mov_b32_e32 v70, v0
	v_mov_b32_e32 v71, v0
	v_mov_b32_e32 v80, v0
	v_mov_b32_e32 v81, v0
	v_mov_b32_e32 v82, v0
	v_mov_b32_e32 v83, v0
	v_mov_b32_e32 v84, v0
	v_mov_b32_e32 v85, v0
	v_mov_b32_e32 v86, v0
	v_mov_b32_e32 v87, v0
	v_mov_b32_e32 v96, v0
	v_mov_b32_e32 v97, v0
	v_mov_b32_e32 v98, v0
	v_mov_b32_e32 v99, v0
	v_mov_b32_e32 v100, v0
	v_mov_b32_e32 v101, v0
	v_mov_b32_e32 v102, v0
	v_mov_b32_e32 v103, v0
	v_mov_b32_e32 v112, v0
	v_mov_b32_e32 v113, v0
	v_mov_b32_e32 v114, v0
	v_mov_b32_e32 v115, v0
	v_mov_b32_e32 v116, v0
	v_mov_b32_e32 v117, v0
	v_mov_b32_e32 v118, v0
	v_mov_b32_e32 v119, v0
	v_mov_b32_e32 v72, v0
	v_mov_b32_e32 v73, v0
	v_mov_b32_e32 v74, v0
	v_mov_b32_e32 v75, v0
	v_mov_b32_e32 v76, v0
	v_mov_b32_e32 v77, v0
	v_mov_b32_e32 v78, v0
	v_mov_b32_e32 v79, v0
	v_mov_b32_e32 v88, v0
	v_mov_b32_e32 v89, v0
	v_mov_b32_e32 v90, v0
	v_mov_b32_e32 v91, v0
	v_mov_b32_e32 v92, v0
	v_mov_b32_e32 v93, v0
	v_mov_b32_e32 v94, v0
	v_mov_b32_e32 v95, v0
	v_mov_b32_e32 v104, v0
	v_mov_b32_e32 v105, v0
	v_mov_b32_e32 v106, v0
	v_mov_b32_e32 v107, v0
	v_mov_b32_e32 v108, v0
	v_mov_b32_e32 v109, v0
	v_mov_b32_e32 v110, v0
	v_mov_b32_e32 v111, v0
	v_mov_b32_e32 v120, v0
	v_mov_b32_e32 v121, v0
	v_mov_b32_e32 v122, v0
	v_mov_b32_e32 v123, v0
	v_mov_b32_e32 v124, v0
	v_mov_b32_e32 v125, v0
	v_mov_b32_e32 v126, v0
	v_mov_b32_e32 v127, v0
	s_cmp_lg_u64 s[12:13], 0
	s_cbranch_scc0 .Lasym_T_1238
.LBB0_1238:
	s_add_u32 s26, s24, 0xfffc0080
	s_addc_u32 s27, s25, -1
	s_cmp_eq_u32 s58, 12
	s_cselect_b32 s29, s17, s27
	s_cselect_b32 s28, s54, s26
	s_cselect_b32 s27, s15, s57
	s_cselect_b32 s26, s55, s56
	s_add_i32 m0, s23, 0xc000
	ds_read_b128 v[144:147], v154
	global_load_lds_dwordx4 v136, s[24:25]
	s_add_i32 m0, s23, 0xe000
	ds_read_b128 v[158:161], v154 offset:1024
	global_load_lds_dwordx4 v138, s[24:25]
	ds_read_b128 v[162:165], v154 offset:2048
	ds_read_b128 v[166:169], v154 offset:3072
	ds_read_b128 v[170:173], v155
	ds_read_b128 v[174:177], v155 offset:1024
	ds_read_b128 v[178:181], v155 offset:2048
	ds_read_b128 v[182:185], v155 offset:3072
	ds_read_b128 v[186:189], v156
	ds_read_b128 v[190:193], v156 offset:1024
	ds_read_b128 v[194:197], v156 offset:2048
	ds_read_b128 v[198:201], v156 offset:3072
	ds_read_b128 v[202:205], v156 offset:4096
	ds_read_b128 v[206:209], v156 offset:5120
	ds_read_b128 v[210:213], v156 offset:6144
	ds_read_b128 v[214:217], v156 offset:7168
	s_waitcnt lgkmcnt(0)
	s_barrier
; #define PG8_STAGE(bufoff, gbase, voff) do { _Pragma("unroll") for (int _i = 0; _i < 2; ++_i) \
;         __builtin_amdgcn_global_load_lds((const unsigned*)((const char*)(gbase) + (voff)[_i]), (PG8_LAS unsigned*)(lds + (bufoff) + ldsw + _i * 8192), 16, 0, 0); } while (0)
; #define PG8_LDA(dst, b, h) do { _Pragma("unroll") for (int m = 0; m < 4; ++m) _Pragma("unroll") for (int k = 0; k < 2; ++k) dst[m][k] = *(const PG8_LAS bf16x8*)(lds + PG8_SA(b, h) + aoff + m * 2048 + k * 1024); } while (0)
; #define PG8_MMA(ai, bj, At, Bt) do { __builtin_amdgcn_s_setprio(1); _Pragma("unroll") for (int m = 0; m < 4; ++m) _Pragma("unroll") for (int n = 0; n < 2; ++n) _Pragma("unroll") for (int k = 0; k < 2; ++k) \
;         acc[ai][bj][m][n] = __builtin_amdgcn_mfma_f32_16x16x32_bf16(Bt[n][k], At[m][k], acc[ai][bj][m][n], 0, 0, 0); __builtin_amdgcn_s_setprio(0); } while (0)
; #define PG8_WAIT_V(n) asm volatile("s_waitcnt vmcnt(" #n ")" ::: "memory")
; #define PG8_WAIT_L(n) asm volatile("s_waitcnt lgkmcnt(" #n ")" ::: "memory")
; #define PG8_BAR __builtin_amdgcn_s_barrier()
; #define PG8_SCHED __builtin_amdgcn_sched_barrier(0)
; template <class Epi, class Sched, bool ALIGN_EPI = false, bool SP2 = false>
; __device__ __forceinline__ void gemm_phase(PG8_LAS unsigned char* lds, const Gemm g, const Sched& S, const Epi& E, int tid_in) {
;     ...
;             PG8_WAIT_V(8); PG8_WAIT_L(0); PG8_BAR; PG8_MMA(0, 0, At, B0); PG8_MMA(0, 1, At, B1); PG8_BAR; PG8_SCHED;
;             PG8_LDA(At, 0, 1); PG8_STAGE(PG8_SB(0, 0), b2, voffB); PG8_STAGE(PG8_SB(0, 1), b2 + hstep, voffB); PG8_STAGE(PG8_SA(0, 0), a2, voffA);
;             PG8_WAIT_V(8); PG8_WAIT_L(0); PG8_BAR; PG8_MMA(1, 0, At, B0); PG8_MMA(1, 1, At, B1); PG8_BAR; PG8_SCHED;
	v_mfma_f32_16x16x32_bf16 v[124:127], v[144:147], v[186:189], v[124:127]
	v_mfma_f32_16x16x32_bf16 v[120:123], v[162:165], v[186:189], v[120:123]
	v_mfma_f32_16x16x32_bf16 v[108:111], v[144:147], v[194:197], v[108:111]
	v_mfma_f32_16x16x32_bf16 v[104:107], v[162:165], v[194:197], v[104:107]
	v_mfma_f32_16x16x32_bf16 v[92:95], v[144:147], v[202:205], v[92:95]
	v_mfma_f32_16x16x32_bf16 v[88:91], v[162:165], v[202:205], v[88:91]
	v_mfma_f32_16x16x32_bf16 v[76:79], v[144:147], v[210:213], v[76:79]
	v_mfma_f32_16x16x32_bf16 v[72:75], v[162:165], v[210:213], v[72:75]
	v_mfma_f32_16x16x32_bf16 v[124:127], v[158:161], v[190:193], v[124:127]
	v_mfma_f32_16x16x32_bf16 v[120:123], v[166:169], v[190:193], v[120:123]
	v_mfma_f32_16x16x32_bf16 v[108:111], v[158:161], v[198:201], v[108:111]
	v_mfma_f32_16x16x32_bf16 v[104:107], v[166:169], v[198:201], v[104:107]
	v_mfma_f32_16x16x32_bf16 v[92:95], v[158:161], v[206:209], v[92:95]
	v_mfma_f32_16x16x32_bf16 v[88:91], v[166:169], v[206:209], v[88:91]
	v_mfma_f32_16x16x32_bf16 v[76:79], v[158:161], v[214:217], v[76:79]
	v_mfma_f32_16x16x32_bf16 v[72:75], v[166:169], v[214:217], v[72:75]
	v_mfma_f32_16x16x32_bf16 v[116:119], v[170:173], v[186:189], v[116:119]
	v_mfma_f32_16x16x32_bf16 v[112:115], v[178:181], v[186:189], v[112:115]
	v_mfma_f32_16x16x32_bf16 v[100:103], v[170:173], v[194:197], v[100:103]
	v_mfma_f32_16x16x32_bf16 v[96:99], v[178:181], v[194:197], v[96:99]
	v_mfma_f32_16x16x32_bf16 v[84:87], v[170:173], v[202:205], v[84:87]
	v_mfma_f32_16x16x32_bf16 v[80:83], v[178:181], v[202:205], v[80:83]
	v_mfma_f32_16x16x32_bf16 v[68:71], v[170:173], v[210:213], v[68:71]
	v_mfma_f32_16x16x32_bf16 v[64:67], v[178:181], v[210:213], v[64:67]
	v_mfma_f32_16x16x32_bf16 v[116:119], v[174:177], v[190:193], v[116:119]
	v_mfma_f32_16x16x32_bf16 v[112:115], v[182:185], v[190:193], v[112:115]
	v_mfma_f32_16x16x32_bf16 v[100:103], v[174:177], v[198:201], v[100:103]
	v_mfma_f32_16x16x32_bf16 v[96:99], v[182:185], v[198:201], v[96:99]
	v_mfma_f32_16x16x32_bf16 v[84:87], v[174:177], v[206:209], v[84:87]
	v_mfma_f32_16x16x32_bf16 v[80:83], v[182:185], v[206:209], v[80:83]
	v_mfma_f32_16x16x32_bf16 v[68:71], v[174:177], v[214:217], v[68:71]
	v_mfma_f32_16x16x32_bf16 v[64:67], v[182:185], v[214:217], v[64:67]
	s_waitcnt vmcnt(8)
	s_barrier
	s_add_u32 s98, s26, s10
	s_addc_u32 s99, s27, s11
	s_add_u32 s100, s28, s10
	s_addc_u32 s101, s29, s11
	s_add_i32 s59, s47, s0
	s_mov_b32 m0, s59
	ds_read_b128 v[186:189], v156 offset:16384
	global_load_lds_dwordx4 v132, s[26:27]
	s_add_i32 m0, s59, 0x2000
	s_add_u32 s60, s26, 0x40000
	s_addc_u32 s61, s27, 0
	s_add_i32 s59, s48, s0
	global_load_lds_dwordx4 v128, s[26:27]
	s_mov_b32 m0, s59
	ds_read_b128 v[190:193], v156 offset:17408
	global_load_lds_dwordx4 v132, s[60:61]
	s_add_i32 m0, s59, 0x2000
	ds_read_b128 v[194:197], v156 offset:18432
	global_load_lds_dwordx4 v128, s[60:61]
	s_mov_b32 m0, s23
	ds_read_b128 v[198:201], v156 offset:19456
	global_load_lds_dwordx4 v134, s[28:29]
	s_mov_b32 m0, s37
	ds_read_b128 v[202:205], v156 offset:20480
	global_load_lds_dwordx4 v130, s[28:29]
	ds_read_b128 v[206:209], v156 offset:21504
	ds_read_b128 v[210:213], v156 offset:22528
	ds_read_b128 v[214:217], v156 offset:23552
	s_waitcnt lgkmcnt(0)
	s_barrier
	v_mfma_f32_16x16x32_bf16 v[60:63], v[144:147], v[186:189], v[60:63]
	v_mfma_f32_16x16x32_bf16 v[56:59], v[162:165], v[186:189], v[56:59]
	v_mfma_f32_16x16x32_bf16 v[44:47], v[144:147], v[194:197], v[44:47]
	v_mfma_f32_16x16x32_bf16 v[40:43], v[162:165], v[194:197], v[40:43]
	v_mfma_f32_16x16x32_bf16 v[28:31], v[144:147], v[202:205], v[28:31]
	v_mfma_f32_16x16x32_bf16 v[24:27], v[162:165], v[202:205], v[24:27]
	v_mfma_f32_16x16x32_bf16 v[12:15], v[144:147], v[210:213], v[12:15]
	v_mfma_f32_16x16x32_bf16 v[8:11], v[162:165], v[210:213], v[8:11]
	v_mfma_f32_16x16x32_bf16 v[60:63], v[158:161], v[190:193], v[60:63]
	v_mfma_f32_16x16x32_bf16 v[56:59], v[166:169], v[190:193], v[56:59]
	v_mfma_f32_16x16x32_bf16 v[44:47], v[158:161], v[198:201], v[44:47]
	v_mfma_f32_16x16x32_bf16 v[40:43], v[166:169], v[198:201], v[40:43]
	v_mfma_f32_16x16x32_bf16 v[28:31], v[158:161], v[206:209], v[28:31]
	v_mfma_f32_16x16x32_bf16 v[24:27], v[166:169], v[206:209], v[24:27]
	v_mfma_f32_16x16x32_bf16 v[12:15], v[158:161], v[214:217], v[12:15]
	v_mfma_f32_16x16x32_bf16 v[8:11], v[166:169], v[214:217], v[8:11]
	v_mfma_f32_16x16x32_bf16 v[52:55], v[170:173], v[186:189], v[52:55]
	v_mfma_f32_16x16x32_bf16 v[48:51], v[178:181], v[186:189], v[48:51]
	v_mfma_f32_16x16x32_bf16 v[36:39], v[170:173], v[194:197], v[36:39]
	v_mfma_f32_16x16x32_bf16 v[32:35], v[178:181], v[194:197], v[32:35]
	v_mfma_f32_16x16x32_bf16 v[20:23], v[170:173], v[202:205], v[20:23]
	v_mfma_f32_16x16x32_bf16 v[16:19], v[178:181], v[202:205], v[16:19]
	v_mfma_f32_16x16x32_bf16 v[4:7], v[170:173], v[210:213], v[4:7]
	v_mfma_f32_16x16x32_bf16 v[0:3], v[178:181], v[210:213], v[0:3]
	v_mfma_f32_16x16x32_bf16 v[52:55], v[174:177], v[190:193], v[52:55]
	v_mfma_f32_16x16x32_bf16 v[48:51], v[182:185], v[190:193], v[48:51]
	v_mfma_f32_16x16x32_bf16 v[36:39], v[174:177], v[198:201], v[36:39]
	v_mfma_f32_16x16x32_bf16 v[32:35], v[182:185], v[198:201], v[32:35]
	v_mfma_f32_16x16x32_bf16 v[20:23], v[174:177], v[206:209], v[20:23]
	v_mfma_f32_16x16x32_bf16 v[16:19], v[182:185], v[206:209], v[16:19]
	v_mfma_f32_16x16x32_bf16 v[4:7], v[174:177], v[214:217], v[4:7]
	v_mfma_f32_16x16x32_bf16 v[0:3], v[182:185], v[214:217], v[0:3]
	s_waitcnt vmcnt(8)
	s_barrier
; #define PG8_STAGE(bufoff, gbase, voff) do { _Pragma("unroll") for (int _i = 0; _i < 2; ++_i) \
;         __builtin_amdgcn_global_load_lds((const unsigned*)((const char*)(gbase) + (voff)[_i]), (PG8_LAS unsigned*)(lds + (bufoff) + ldsw + _i * 8192), 16, 0, 0); } while (0)
; #define PG8_LDA(dst, b, h) do { _Pragma("unroll") for (int m = 0; m < 4; ++m) _Pragma("unroll") for (int k = 0; k < 2; ++k) dst[m][k] = *(const PG8_LAS bf16x8*)(lds + PG8_SA(b, h) + aoff + m * 2048 + k * 1024); } while (0)
; #define PG8_LDB(dst, b, h) do { _Pragma("unroll") for (int n = 0; n < 2; ++n) _Pragma("unroll") for (int k = 0; k < 2; ++k) dst[n][k] = *(const PG8_LAS bf16x8*)(lds + PG8_SB(b, h) + boff + n * 2048 + k * 1024); } while (0)
; #define PG8_MMA(ai, bj, At, Bt) do { __builtin_amdgcn_s_setprio(1); _Pragma("unroll") for (int m = 0; m < 4; ++m) _Pragma("unroll") for (int n = 0; n < 2; ++n) _Pragma("unroll") for (int k = 0; k < 2; ++k) \
;         acc[ai][bj][m][n] = __builtin_amdgcn_mfma_f32_16x16x32_bf16(Bt[n][k], At[m][k], acc[ai][bj][m][n], 0, 0, 0); __builtin_amdgcn_s_setprio(0); } while (0)
; #define PG8_WAIT_V(n) asm volatile("s_waitcnt vmcnt(" #n ")" ::: "memory")
; #define PG8_WAIT_L(n) asm volatile("s_waitcnt lgkmcnt(" #n ")" ::: "memory")
; #define PG8_BAR __builtin_amdgcn_s_barrier()
; #define PG8_SCHED __builtin_amdgcn_sched_barrier(0)
; template <class Epi, class Sched, bool ALIGN_EPI = false, bool SP2 = false>
; __device__ __forceinline__ void gemm_phase(PG8_LAS unsigned char* lds, const Gemm g, const Sched& S, const Epi& E, int tid_in) {
;     ...
;             PG8_LDB(B0, 1, 0); PG8_LDB(B1, 1, 1); PG8_SCHED; PG8_LDA(At, 1, 0); PG8_STAGE(PG8_SA(0, 1), a2 + hstep, voffA);
;             PG8_WAIT_V(8); PG8_WAIT_L(0); PG8_BAR; PG8_MMA(0, 0, At, B0); PG8_MMA(0, 1, At, B1); PG8_BAR; PG8_SCHED;
;             PG8_LDA(At, 1, 1); PG8_STAGE(PG8_SB(1, 0), b3, voffB); PG8_STAGE(PG8_SB(1, 1), b3 + hstep, voffB); PG8_STAGE(PG8_SA(1, 0), a3, voffA);
;             PG8_WAIT_V(8); PG8_WAIT_L(0); PG8_BAR; PG8_MMA(1, 0, At, B0); PG8_MMA(1, 1, At, B1); PG8_BAR; PG8_SCHED;
	s_add_i32 s59, 0, 0x18000
	s_add_i32 s60, 0, 0x1c000
	s_add_u32 s28, s28, 0x40000
	s_addc_u32 s29, s29, 0
	s_mov_b32 m0, s38
	v_add_u32_e32 v157, s59, v151
	global_load_lds_dwordx4 v134, s[28:29]
	s_mov_b32 m0, s39
	ds_read_b128 v[144:147], v157
	global_load_lds_dwordx4 v130, s[28:29]
	ds_read_b128 v[158:161], v157 offset:1024
	ds_read_b128 v[162:165], v157 offset:2048
	ds_read_b128 v[166:169], v157 offset:3072
	v_add_u32_e32 v157, s60, v151
	ds_read_b128 v[170:173], v157
	ds_read_b128 v[174:177], v157 offset:1024
	ds_read_b128 v[178:181], v157 offset:2048
	ds_read_b128 v[182:185], v157 offset:3072
	ds_read_b128 v[186:189], v156 offset:32768
	ds_read_b128 v[190:193], v156 offset:33792
	ds_read_b128 v[194:197], v156 offset:34816
	ds_read_b128 v[198:201], v156 offset:35840
	ds_read_b128 v[202:205], v156 offset:36864
	ds_read_b128 v[206:209], v156 offset:37888
	ds_read_b128 v[210:213], v156 offset:38912
	ds_read_b128 v[214:217], v156 offset:39936
	s_waitcnt lgkmcnt(0)
	s_barrier
	v_mfma_f32_16x16x32_bf16 v[124:127], v[144:147], v[186:189], v[124:127]
	v_mfma_f32_16x16x32_bf16 v[120:123], v[162:165], v[186:189], v[120:123]
	v_mfma_f32_16x16x32_bf16 v[108:111], v[144:147], v[194:197], v[108:111]
	v_mfma_f32_16x16x32_bf16 v[104:107], v[162:165], v[194:197], v[104:107]
	v_mfma_f32_16x16x32_bf16 v[92:95], v[144:147], v[202:205], v[92:95]
	v_mfma_f32_16x16x32_bf16 v[88:91], v[162:165], v[202:205], v[88:91]
	v_mfma_f32_16x16x32_bf16 v[76:79], v[144:147], v[210:213], v[76:79]
	v_mfma_f32_16x16x32_bf16 v[72:75], v[162:165], v[210:213], v[72:75]
	v_mfma_f32_16x16x32_bf16 v[124:127], v[158:161], v[190:193], v[124:127]
	v_mfma_f32_16x16x32_bf16 v[120:123], v[166:169], v[190:193], v[120:123]
	v_mfma_f32_16x16x32_bf16 v[108:111], v[158:161], v[198:201], v[108:111]
	v_mfma_f32_16x16x32_bf16 v[104:107], v[166:169], v[198:201], v[104:107]
	v_mfma_f32_16x16x32_bf16 v[92:95], v[158:161], v[206:209], v[92:95]
	v_mfma_f32_16x16x32_bf16 v[88:91], v[166:169], v[206:209], v[88:91]
	v_mfma_f32_16x16x32_bf16 v[76:79], v[158:161], v[214:217], v[76:79]
	v_mfma_f32_16x16x32_bf16 v[72:75], v[166:169], v[214:217], v[72:75]
	v_mfma_f32_16x16x32_bf16 v[116:119], v[170:173], v[186:189], v[116:119]
	v_mfma_f32_16x16x32_bf16 v[112:115], v[178:181], v[186:189], v[112:115]
	v_mfma_f32_16x16x32_bf16 v[100:103], v[170:173], v[194:197], v[100:103]
	v_mfma_f32_16x16x32_bf16 v[96:99], v[178:181], v[194:197], v[96:99]
	v_mfma_f32_16x16x32_bf16 v[84:87], v[170:173], v[202:205], v[84:87]
	v_mfma_f32_16x16x32_bf16 v[80:83], v[178:181], v[202:205], v[80:83]
	v_mfma_f32_16x16x32_bf16 v[68:71], v[170:173], v[210:213], v[68:71]
	v_mfma_f32_16x16x32_bf16 v[64:67], v[178:181], v[210:213], v[64:67]
	v_mfma_f32_16x16x32_bf16 v[116:119], v[174:177], v[190:193], v[116:119]
	v_mfma_f32_16x16x32_bf16 v[112:115], v[182:185], v[190:193], v[112:115]
	v_mfma_f32_16x16x32_bf16 v[100:103], v[174:177], v[198:201], v[100:103]
	v_mfma_f32_16x16x32_bf16 v[96:99], v[182:185], v[198:201], v[96:99]
	v_mfma_f32_16x16x32_bf16 v[84:87], v[174:177], v[206:209], v[84:87]
	v_mfma_f32_16x16x32_bf16 v[80:83], v[182:185], v[206:209], v[80:83]
	v_mfma_f32_16x16x32_bf16 v[68:71], v[174:177], v[214:217], v[68:71]
	v_mfma_f32_16x16x32_bf16 v[64:67], v[182:185], v[214:217], v[64:67]
	s_waitcnt vmcnt(8)
	s_barrier
	s_add_i32 s28, s59, s0
	s_mov_b32 m0, s28
	ds_read_b128 v[186:189], v156 offset:49152
	global_load_lds_dwordx4 v132, s[98:99]
	s_add_i32 m0, s28, 0x2000
	s_add_u32 s26, s26, 0x40080
	s_addc_u32 s27, s27, 0
	s_add_i32 s28, s60, s0
	global_load_lds_dwordx4 v128, s[98:99]
	s_mov_b32 m0, s28
	ds_read_b128 v[190:193], v156 offset:50176
	global_load_lds_dwordx4 v132, s[26:27]
	s_add_i32 m0, s28, 0x2000
	ds_read_b128 v[194:197], v156 offset:51200
	global_load_lds_dwordx4 v128, s[26:27]
	s_mov_b32 m0, s44
	ds_read_b128 v[198:201], v156 offset:52224
	global_load_lds_dwordx4 v134, s[100:101]
	s_mov_b32 m0, s45
	ds_read_b128 v[202:205], v156 offset:53248
	global_load_lds_dwordx4 v130, s[100:101]
	ds_read_b128 v[206:209], v156 offset:54272
	ds_read_b128 v[210:213], v156 offset:55296
	ds_read_b128 v[214:217], v156 offset:56320
	s_waitcnt lgkmcnt(0)
	s_barrier
	v_mfma_f32_16x16x32_bf16 v[60:63], v[144:147], v[186:189], v[60:63]
	v_mfma_f32_16x16x32_bf16 v[56:59], v[162:165], v[186:189], v[56:59]
	v_mfma_f32_16x16x32_bf16 v[44:47], v[144:147], v[194:197], v[44:47]
	v_mfma_f32_16x16x32_bf16 v[40:43], v[162:165], v[194:197], v[40:43]
	v_mfma_f32_16x16x32_bf16 v[28:31], v[144:147], v[202:205], v[28:31]
	v_mfma_f32_16x16x32_bf16 v[24:27], v[162:165], v[202:205], v[24:27]
	v_mfma_f32_16x16x32_bf16 v[12:15], v[144:147], v[210:213], v[12:15]
	v_mfma_f32_16x16x32_bf16 v[8:11], v[162:165], v[210:213], v[8:11]
	v_mfma_f32_16x16x32_bf16 v[60:63], v[158:161], v[190:193], v[60:63]
	v_mfma_f32_16x16x32_bf16 v[56:59], v[166:169], v[190:193], v[56:59]
	v_mfma_f32_16x16x32_bf16 v[44:47], v[158:161], v[198:201], v[44:47]
	v_mfma_f32_16x16x32_bf16 v[40:43], v[166:169], v[198:201], v[40:43]
	v_mfma_f32_16x16x32_bf16 v[28:31], v[158:161], v[206:209], v[28:31]
	v_mfma_f32_16x16x32_bf16 v[24:27], v[166:169], v[206:209], v[24:27]
	v_mfma_f32_16x16x32_bf16 v[12:15], v[158:161], v[214:217], v[12:15]
	v_mfma_f32_16x16x32_bf16 v[8:11], v[166:169], v[214:217], v[8:11]
	v_mfma_f32_16x16x32_bf16 v[52:55], v[170:173], v[186:189], v[52:55]
	v_mfma_f32_16x16x32_bf16 v[48:51], v[178:181], v[186:189], v[48:51]
	v_mfma_f32_16x16x32_bf16 v[36:39], v[170:173], v[194:197], v[36:39]
	v_mfma_f32_16x16x32_bf16 v[32:35], v[178:181], v[194:197], v[32:35]
	v_mfma_f32_16x16x32_bf16 v[20:23], v[170:173], v[202:205], v[20:23]
	v_mfma_f32_16x16x32_bf16 v[16:19], v[178:181], v[202:205], v[16:19]
	v_mfma_f32_16x16x32_bf16 v[4:7], v[170:173], v[210:213], v[4:7]
	v_mfma_f32_16x16x32_bf16 v[0:3], v[178:181], v[210:213], v[0:3]
	v_mfma_f32_16x16x32_bf16 v[52:55], v[174:177], v[190:193], v[52:55]
	v_mfma_f32_16x16x32_bf16 v[48:51], v[182:185], v[190:193], v[48:51]
	v_mfma_f32_16x16x32_bf16 v[36:39], v[174:177], v[198:201], v[36:39]
	v_mfma_f32_16x16x32_bf16 v[32:35], v[182:185], v[198:201], v[32:35]
	v_mfma_f32_16x16x32_bf16 v[20:23], v[174:177], v[206:209], v[20:23]
	v_mfma_f32_16x16x32_bf16 v[16:19], v[182:185], v[206:209], v[16:19]
	v_mfma_f32_16x16x32_bf16 v[4:7], v[174:177], v[214:217], v[4:7]
	v_mfma_f32_16x16x32_bf16 v[0:3], v[182:185], v[214:217], v[0:3]
	s_waitcnt vmcnt(8)
	s_barrier
	s_add_i32 s58, s58, 2
	s_add_u32 s24, s24, 0x100
	s_addc_u32 s25, s25, 0
	s_add_u32 s56, s56, 0x100
	s_addc_u32 s57, s57, 0
	s_cmp_gt_u32 s58, 13
	s_cbranch_scc0 .LBB0_1238
	s_branch .Lasym_J_1238

; #define PG8_BAR __builtin_amdgcn_s_barrier()
; template <class Epi, class Sched, bool ALIGN_EPI = false, bool SP2 = false>
; __device__ __forceinline__ void gemm_phase(PG8_LAS unsigned char* lds, const Gemm g, const Sched& S, const Epi& E, int tid_in) {
;     ...
;         if constexpr (ALIGN_EPI) { if (wr == 0) PG8_BAR; }
.Lasym_J_1238:
	s_cmp_eq_u32 s50, 1
	s_cbranch_scc0 .Lww_done_p9
	v_readlane_b32 s98, v248, 0
	s_nop 3
	s_cmp_eq_u32 s98, 0
	s_cbranch_scc0 .Lww_bar_p9
	v_readlane_b32 s98, v248, 32
	s_nop 3
	s_cmp_eq_u32 s98, 1
	s_cbranch_scc0 .Lww_bar_p9
	v_mov_b32_e32 v246, 0x3500
	s_mov_b32 s98, 0

; #define PG8_STAGE(bufoff, gbase, voff) do { _Pragma("unroll") for (int _i = 0; _i < 2; ++_i) \
;         __builtin_amdgcn_global_load_lds((const unsigned*)((const char*)(gbase) + (voff)[_i]), (PG8_LAS unsigned*)(lds + (bufoff) + ldsw + _i * 8192), 16, 0, 0); } while (0)
; #define PG8_LDA(dst, b, h) do { _Pragma("unroll") for (int m = 0; m < 4; ++m) _Pragma("unroll") for (int k = 0; k < 2; ++k) dst[m][k] = *(const PG8_LAS bf16x8*)(lds + PG8_SA(b, h) + aoff + m * 2048 + k * 1024); } while (0)
; #define PG8_LDB(dst, b, h) do { _Pragma("unroll") for (int n = 0; n < 2; ++n) _Pragma("unroll") for (int k = 0; k < 2; ++k) dst[n][k] = *(const PG8_LAS bf16x8*)(lds + PG8_SB(b, h) + boff + n * 2048 + k * 1024); } while (0)
; #define PG8_MMA(ai, bj, At, Bt) do { __builtin_amdgcn_s_setprio(1); _Pragma("unroll") for (int m = 0; m < 4; ++m) _Pragma("unroll") for (int n = 0; n < 2; ++n) _Pragma("unroll") for (int k = 0; k < 2; ++k) \
;         acc[ai][bj][m][n] = __builtin_amdgcn_mfma_f32_16x16x32_bf16(Bt[n][k], At[m][k], acc[ai][bj][m][n], 0, 0, 0); __builtin_amdgcn_s_setprio(0); } while (0)
; #define PG8_WAIT_V(n) asm volatile("s_waitcnt vmcnt(" #n ")" ::: "memory")
; #define PG8_WAIT_L(n) asm volatile("s_waitcnt lgkmcnt(" #n ")" ::: "memory")
; template <class Epi, class Sched, bool ALIGN_EPI = false, bool SP2 = false>
; __device__ __forceinline__ void gemm_phase(PG8_LAS unsigned char* lds, const Gemm g, const Sched& S, const Epi& E, int tid_in) {
;     ...
;             const bool last = (t == nt - 2);
;             const char* a1 = cA + (size_t)(t + 1) * kstep;
;             const char* a2 = last ? nA : cA + (size_t)(t + 2) * kstep; const char* b2 = last ? nB : cB + (size_t)(t + 2) * kstep;
;             const char* a3 = a2 + kstep; const char* b3 = b2 + kstep;
;             if (last && has_next) S.a_ready(nxt);
;             if constexpr (SP2) {
;             PG8_LDB(B0, 0, 0); PG8_LDB(B1, 0, 1); PG8_SCHED; PG8_LDA(At, 0, 0); PG8_STAGE(PG8_SA(1, 1), a1 + hstep, voffA);
;             PG8_WAIT_V(8); PG8_WAIT_L(0); PG8_BAR; PG8_MMA(0, 0, At, B0); PG8_MMA(0, 1, At, B1); PG8_BAR; PG8_SCHED;
;     ...
;         for (int a = 0; a < 2; ++a)
; #pragma unroll
;             for (int b = 0; b < 2; ++b)
; #pragma unroll
;                 for (int m = 0; m < 4; ++m)
; #pragma unroll
;                     for (int n = 0; n < 2; ++n) acc[a][b][m][n] = (f32x4){0.f, 0.f, 0.f, 0.f};
.LBB0_1320:
	s_add_u32 s48, s22, 0x100
	v_mov_b32_e32 v0, 0
	s_addc_u32 s49, s23, 0
	s_mov_b32 s50, -2
	v_mov_b32_e32 v1, v0
	v_mov_b32_e32 v2, v0
	v_mov_b32_e32 v3, v0
	v_mov_b32_e32 v4, v0
	v_mov_b32_e32 v5, v0
	v_mov_b32_e32 v6, v0
	v_mov_b32_e32 v7, v0
	v_mov_b32_e32 v20, v0
	v_mov_b32_e32 v21, v0
	v_mov_b32_e32 v22, v0
	v_mov_b32_e32 v23, v0
	v_mov_b32_e32 v16, v0
	v_mov_b32_e32 v17, v0
	v_mov_b32_e32 v18, v0
	v_mov_b32_e32 v19, v0
	v_mov_b32_e32 v36, v0
	v_mov_b32_e32 v37, v0
	v_mov_b32_e32 v38, v0
	v_mov_b32_e32 v39, v0
	v_mov_b32_e32 v32, v0
	v_mov_b32_e32 v33, v0
	v_mov_b32_e32 v34, v0
	v_mov_b32_e32 v35, v0
	v_mov_b32_e32 v52, v0
	v_mov_b32_e32 v53, v0
	v_mov_b32_e32 v54, v0
	v_mov_b32_e32 v55, v0
	v_mov_b32_e32 v48, v0
	v_mov_b32_e32 v49, v0
	v_mov_b32_e32 v50, v0
	v_mov_b32_e32 v51, v0
	v_mov_b32_e32 v12, v0
	v_mov_b32_e32 v13, v0
	v_mov_b32_e32 v14, v0
	v_mov_b32_e32 v15, v0
	v_mov_b32_e32 v8, v0
	v_mov_b32_e32 v9, v0
	v_mov_b32_e32 v10, v0
	v_mov_b32_e32 v11, v0
	v_mov_b32_e32 v28, v0
	v_mov_b32_e32 v29, v0
	v_mov_b32_e32 v30, v0
	v_mov_b32_e32 v31, v0
	v_mov_b32_e32 v24, v0
	v_mov_b32_e32 v25, v0
	v_mov_b32_e32 v26, v0
	v_mov_b32_e32 v27, v0
	v_mov_b32_e32 v44, v0
	v_mov_b32_e32 v45, v0
	v_mov_b32_e32 v46, v0
	v_mov_b32_e32 v47, v0
	v_mov_b32_e32 v40, v0
	v_mov_b32_e32 v41, v0
	v_mov_b32_e32 v42, v0
	v_mov_b32_e32 v43, v0
	v_mov_b32_e32 v60, v0
	v_mov_b32_e32 v61, v0
	v_mov_b32_e32 v62, v0
	v_mov_b32_e32 v63, v0
	v_mov_b32_e32 v56, v0
	v_mov_b32_e32 v57, v0
	v_mov_b32_e32 v58, v0
	v_mov_b32_e32 v59, v0
	s_waitcnt vmcnt(0)
	v_mov_b32_e32 v68, v0
	v_mov_b32_e32 v69, v0
	v_mov_b32_e32 v70, v0
	v_mov_b32_e32 v71, v0
	v_mov_b32_e32 v64, v0
	v_mov_b32_e32 v65, v0
	v_mov_b32_e32 v66, v0
	v_mov_b32_e32 v67, v0
	v_mov_b32_e32 v84, v0
	v_mov_b32_e32 v85, v0
	v_mov_b32_e32 v86, v0
	v_mov_b32_e32 v87, v0
	v_mov_b32_e32 v80, v0
	v_mov_b32_e32 v81, v0
	v_mov_b32_e32 v82, v0
	v_mov_b32_e32 v83, v0
	v_mov_b32_e32 v100, v0
	v_mov_b32_e32 v101, v0
	v_mov_b32_e32 v102, v0
	v_mov_b32_e32 v103, v0
	v_mov_b32_e32 v96, v0
	v_mov_b32_e32 v97, v0
	v_mov_b32_e32 v98, v0
	v_mov_b32_e32 v99, v0
	v_mov_b32_e32 v116, v0
	v_mov_b32_e32 v117, v0
	v_mov_b32_e32 v118, v0
	v_mov_b32_e32 v119, v0
	v_mov_b32_e32 v112, v0
	v_mov_b32_e32 v113, v0
	v_mov_b32_e32 v114, v0
	v_mov_b32_e32 v115, v0
	v_mov_b32_e32 v76, v0
	v_mov_b32_e32 v77, v0
	v_mov_b32_e32 v78, v0
	v_mov_b32_e32 v79, v0
	v_mov_b32_e32 v72, v0
	v_mov_b32_e32 v73, v0
	v_mov_b32_e32 v74, v0
	v_mov_b32_e32 v75, v0
	v_mov_b32_e32 v92, v0
	v_mov_b32_e32 v93, v0
	v_mov_b32_e32 v94, v0
	v_mov_b32_e32 v95, v0
	v_mov_b32_e32 v88, v0
	v_mov_b32_e32 v89, v0
	v_mov_b32_e32 v90, v0
	v_mov_b32_e32 v91, v0
	v_mov_b32_e32 v108, v0
	v_mov_b32_e32 v109, v0
	v_mov_b32_e32 v110, v0
	v_mov_b32_e32 v111, v0
	v_mov_b32_e32 v104, v0
	v_mov_b32_e32 v105, v0
	v_mov_b32_e32 v106, v0
	v_mov_b32_e32 v107, v0
	v_mov_b32_e32 v124, v0
	v_mov_b32_e32 v125, v0
	v_mov_b32_e32 v126, v0
	v_mov_b32_e32 v127, v0
	v_mov_b32_e32 v120, v0
	v_mov_b32_e32 v121, v0
	v_mov_b32_e32 v122, v0
	v_mov_b32_e32 v123, v0
	s_cmp_lg_u64 s[12:13], 0
	s_cbranch_scc0 .Lasym_T_1321
.LBB0_1321:
	s_add_u32 s2, s20, 0x100
	s_addc_u32 s3, s21, 0
	s_cmp_eq_u32 s50, 40
	s_cselect_b32 s25, s17, s3
	s_cselect_b32 s24, s16, s2
	s_cselect_b32 s23, s19, s49
	s_cselect_b32 s22, s18, s48
	s_add_i32 m0, s34, 0xc000
	ds_read_b128 v[128:131], v195
	global_load_lds_dwordx4 v168, s[20:21]
	s_add_i32 m0, s34, 0xe000
	ds_read_b128 v[132:135], v195 offset:1024
	global_load_lds_dwordx4 v170, s[20:21]
	ds_read_b128 v[136:139], v195 offset:2048
	ds_read_b128 v[140:143], v195 offset:3072
	ds_read_b128 v[144:147], v196
	ds_read_b128 v[148:151], v196 offset:1024
	ds_read_b128 v[152:155], v196 offset:2048
	ds_read_b128 v[156:159], v196 offset:3072
	ds_read_b128 v[176:179], v197
	ds_read_b128 v[180:183], v197 offset:1024
	ds_read_b128 v[184:187], v197 offset:2048
	ds_read_b128 v[188:191], v197 offset:3072
	ds_read_b128 v[198:201], v197 offset:4096
	ds_read_b128 v[202:205], v197 offset:5120
	ds_read_b128 v[206:209], v197 offset:6144
	ds_read_b128 v[210:213], v197 offset:7168
	s_waitcnt lgkmcnt(0)
	s_barrier
	v_mfma_f32_16x16x32_bf16 v[120:123], v[128:131], v[176:179], v[120:123]
	v_mfma_f32_16x16x32_bf16 v[124:127], v[136:139], v[176:179], v[124:127]
	v_mfma_f32_16x16x32_bf16 v[104:107], v[128:131], v[184:187], v[104:107]
	v_mfma_f32_16x16x32_bf16 v[108:111], v[136:139], v[184:187], v[108:111]
	v_mfma_f32_16x16x32_bf16 v[88:91], v[128:131], v[198:201], v[88:91]
	v_mfma_f32_16x16x32_bf16 v[92:95], v[136:139], v[198:201], v[92:95]
	v_mfma_f32_16x16x32_bf16 v[72:75], v[128:131], v[206:209], v[72:75]
	v_mfma_f32_16x16x32_bf16 v[76:79], v[136:139], v[206:209], v[76:79]
	v_mfma_f32_16x16x32_bf16 v[120:123], v[132:135], v[180:183], v[120:123]
	v_mfma_f32_16x16x32_bf16 v[124:127], v[140:143], v[180:183], v[124:127]
	v_mfma_f32_16x16x32_bf16 v[104:107], v[132:135], v[188:191], v[104:107]
	v_mfma_f32_16x16x32_bf16 v[108:111], v[140:143], v[188:191], v[108:111]
	v_mfma_f32_16x16x32_bf16 v[88:91], v[132:135], v[202:205], v[88:91]
	v_mfma_f32_16x16x32_bf16 v[92:95], v[140:143], v[202:205], v[92:95]
	v_mfma_f32_16x16x32_bf16 v[72:75], v[132:135], v[210:213], v[72:75]
	v_mfma_f32_16x16x32_bf16 v[76:79], v[140:143], v[210:213], v[76:79]
	v_mfma_f32_16x16x32_bf16 v[112:115], v[144:147], v[176:179], v[112:115]
	v_mfma_f32_16x16x32_bf16 v[116:119], v[152:155], v[176:179], v[116:119]
	v_mfma_f32_16x16x32_bf16 v[96:99], v[144:147], v[184:187], v[96:99]
	v_mfma_f32_16x16x32_bf16 v[100:103], v[152:155], v[184:187], v[100:103]
	v_mfma_f32_16x16x32_bf16 v[80:83], v[144:147], v[198:201], v[80:83]
	v_mfma_f32_16x16x32_bf16 v[84:87], v[152:155], v[198:201], v[84:87]
	v_mfma_f32_16x16x32_bf16 v[64:67], v[144:147], v[206:209], v[64:67]
	v_mfma_f32_16x16x32_bf16 v[68:71], v[152:155], v[206:209], v[68:71]
	v_mfma_f32_16x16x32_bf16 v[112:115], v[148:151], v[180:183], v[112:115]
	v_mfma_f32_16x16x32_bf16 v[116:119], v[156:159], v[180:183], v[116:119]
	v_mfma_f32_16x16x32_bf16 v[96:99], v[148:151], v[188:191], v[96:99]
	v_mfma_f32_16x16x32_bf16 v[100:103], v[156:159], v[188:191], v[100:103]
	v_mfma_f32_16x16x32_bf16 v[80:83], v[148:151], v[202:205], v[80:83]
	v_mfma_f32_16x16x32_bf16 v[84:87], v[156:159], v[202:205], v[84:87]
	v_mfma_f32_16x16x32_bf16 v[64:67], v[148:151], v[210:213], v[64:67]
	v_mfma_f32_16x16x32_bf16 v[68:71], v[156:159], v[210:213], v[68:71]
	s_waitcnt vmcnt(8)
	s_barrier
; #define PG8_STAGE(bufoff, gbase, voff) do { _Pragma("unroll") for (int _i = 0; _i < 2; ++_i) \
;         __builtin_amdgcn_global_load_lds((const unsigned*)((const char*)(gbase) + (voff)[_i]), (PG8_LAS unsigned*)(lds + (bufoff) + ldsw + _i * 8192), 16, 0, 0); } while (0)
; #define PG8_LDA(dst, b, h) do { _Pragma("unroll") for (int m = 0; m < 4; ++m) _Pragma("unroll") for (int k = 0; k < 2; ++k) dst[m][k] = *(const PG8_LAS bf16x8*)(lds + PG8_SA(b, h) + aoff + m * 2048 + k * 1024); } while (0)
; #define PG8_LDB(dst, b, h) do { _Pragma("unroll") for (int n = 0; n < 2; ++n) _Pragma("unroll") for (int k = 0; k < 2; ++k) dst[n][k] = *(const PG8_LAS bf16x8*)(lds + PG8_SB(b, h) + boff + n * 2048 + k * 1024); } while (0)
; #define PG8_MMA(ai, bj, At, Bt) do { __builtin_amdgcn_s_setprio(1); _Pragma("unroll") for (int m = 0; m < 4; ++m) _Pragma("unroll") for (int n = 0; n < 2; ++n) _Pragma("unroll") for (int k = 0; k < 2; ++k) \
;         acc[ai][bj][m][n] = __builtin_amdgcn_mfma_f32_16x16x32_bf16(Bt[n][k], At[m][k], acc[ai][bj][m][n], 0, 0, 0); __builtin_amdgcn_s_setprio(0); } while (0)
; #define PG8_WAIT_V(n) asm volatile("s_waitcnt vmcnt(" #n ")" ::: "memory")
; #define PG8_WAIT_L(n) asm volatile("s_waitcnt lgkmcnt(" #n ")" ::: "memory")
; #define PG8_BAR __builtin_amdgcn_s_barrier()
; #define PG8_SCHED __builtin_amdgcn_sched_barrier(0)
; template <class Epi, class Sched, bool ALIGN_EPI = false, bool SP2 = false>
; __device__ __forceinline__ void gemm_phase(PG8_LAS unsigned char* lds, const Gemm g, const Sched& S, const Epi& E, int tid_in) {
;     ...
;             PG8_LDA(At, 0, 1); PG8_STAGE(PG8_SB(0, 0), b2, voffB); PG8_STAGE(PG8_SB(0, 1), b2 + hstep, voffB); PG8_STAGE(PG8_SA(0, 0), a2, voffA);
;             PG8_WAIT_V(8); PG8_WAIT_L(0); PG8_BAR; PG8_MMA(1, 0, At, B0); PG8_MMA(1, 1, At, B1); PG8_BAR; PG8_SCHED;
;             PG8_LDB(B0, 1, 0); PG8_LDB(B1, 1, 1); PG8_SCHED; PG8_LDA(At, 1, 0); PG8_STAGE(PG8_SA(0, 1), a2 + hstep, voffA);
;             PG8_WAIT_V(8); PG8_WAIT_L(0); PG8_BAR; PG8_MMA(0, 0, At, B0); PG8_MMA(0, 1, At, B1); PG8_BAR; PG8_SCHED;
	s_add_u32 s98, s22, s10
	s_addc_u32 s99, s23, s11
	s_add_u32 s100, s24, s10
	s_addc_u32 s101, s25, s11
	s_add_i32 s20, s42, s31
	s_mov_b32 m0, s20
	ds_read_b128 v[176:179], v197 offset:16384
	global_load_lds_dwordx4 v162, s[22:23]
	s_add_i32 m0, s20, 0x2000
	s_add_u32 s20, s22, 0xb0000
	s_addc_u32 s21, s23, 0
	s_add_i32 s51, s43, s31
	global_load_lds_dwordx4 v166, s[22:23]
	s_mov_b32 m0, s51
	ds_read_b128 v[180:183], v197 offset:17408
	global_load_lds_dwordx4 v162, s[20:21]
	s_add_i32 m0, s51, 0x2000
	ds_read_b128 v[184:187], v197 offset:18432
	global_load_lds_dwordx4 v166, s[20:21]
	s_mov_b32 m0, s34
	ds_read_b128 v[188:191], v197 offset:19456
	global_load_lds_dwordx4 v160, s[24:25]
	s_mov_b32 m0, s35
	ds_read_b128 v[198:201], v197 offset:20480
	global_load_lds_dwordx4 v164, s[24:25]
	ds_read_b128 v[202:205], v197 offset:21504
	ds_read_b128 v[206:209], v197 offset:22528
	ds_read_b128 v[210:213], v197 offset:23552
	s_waitcnt lgkmcnt(0)
	s_barrier
	v_mfma_f32_16x16x32_bf16 v[56:59], v[128:131], v[176:179], v[56:59]
	v_mfma_f32_16x16x32_bf16 v[60:63], v[136:139], v[176:179], v[60:63]
	v_mfma_f32_16x16x32_bf16 v[40:43], v[128:131], v[184:187], v[40:43]
	v_mfma_f32_16x16x32_bf16 v[44:47], v[136:139], v[184:187], v[44:47]
	v_mfma_f32_16x16x32_bf16 v[24:27], v[128:131], v[198:201], v[24:27]
	v_mfma_f32_16x16x32_bf16 v[28:31], v[136:139], v[198:201], v[28:31]
	v_mfma_f32_16x16x32_bf16 v[8:11], v[128:131], v[206:209], v[8:11]
	v_mfma_f32_16x16x32_bf16 v[12:15], v[136:139], v[206:209], v[12:15]
	v_mfma_f32_16x16x32_bf16 v[56:59], v[132:135], v[180:183], v[56:59]
	v_mfma_f32_16x16x32_bf16 v[60:63], v[140:143], v[180:183], v[60:63]
	v_mfma_f32_16x16x32_bf16 v[40:43], v[132:135], v[188:191], v[40:43]
	v_mfma_f32_16x16x32_bf16 v[44:47], v[140:143], v[188:191], v[44:47]
	v_mfma_f32_16x16x32_bf16 v[24:27], v[132:135], v[202:205], v[24:27]
	v_mfma_f32_16x16x32_bf16 v[28:31], v[140:143], v[202:205], v[28:31]
	v_mfma_f32_16x16x32_bf16 v[8:11], v[132:135], v[210:213], v[8:11]
	v_mfma_f32_16x16x32_bf16 v[12:15], v[140:143], v[210:213], v[12:15]
	v_mfma_f32_16x16x32_bf16 v[48:51], v[144:147], v[176:179], v[48:51]
	v_mfma_f32_16x16x32_bf16 v[52:55], v[152:155], v[176:179], v[52:55]
	v_mfma_f32_16x16x32_bf16 v[32:35], v[144:147], v[184:187], v[32:35]
	v_mfma_f32_16x16x32_bf16 v[36:39], v[152:155], v[184:187], v[36:39]
	v_mfma_f32_16x16x32_bf16 v[16:19], v[144:147], v[198:201], v[16:19]
	v_mfma_f32_16x16x32_bf16 v[20:23], v[152:155], v[198:201], v[20:23]
	v_mfma_f32_16x16x32_bf16 v[4:7], v[144:147], v[206:209], v[4:7]
	v_mfma_f32_16x16x32_bf16 v[0:3], v[152:155], v[206:209], v[0:3]
	v_mfma_f32_16x16x32_bf16 v[48:51], v[148:151], v[180:183], v[48:51]
	v_mfma_f32_16x16x32_bf16 v[52:55], v[156:159], v[180:183], v[52:55]
	v_mfma_f32_16x16x32_bf16 v[32:35], v[148:151], v[188:191], v[32:35]
	v_mfma_f32_16x16x32_bf16 v[36:39], v[156:159], v[188:191], v[36:39]
	v_mfma_f32_16x16x32_bf16 v[16:19], v[148:151], v[202:205], v[16:19]
	v_mfma_f32_16x16x32_bf16 v[20:23], v[156:159], v[202:205], v[20:23]
	v_mfma_f32_16x16x32_bf16 v[4:7], v[148:151], v[210:213], v[4:7]
	v_mfma_f32_16x16x32_bf16 v[0:3], v[156:159], v[210:213], v[0:3]
	s_waitcnt vmcnt(8)
	s_barrier
	s_add_i32 s51, 0, 0x18000
	s_add_i32 s52, 0, 0x1c000
	s_add_u32 s20, s24, 0xb0000
	s_addc_u32 s21, s25, 0
	s_mov_b32 m0, s36
	s_nop 0
	global_load_lds_dwordx4 v160, s[20:21]
	s_mov_b32 m0, s37
	s_nop 0
	global_load_lds_dwordx4 v164, s[20:21]
	v_add_u32_e32 v140, s51, v193
	v_add_u32_e32 v156, s52, v193
	ds_read_b128 v[128:131], v140
	ds_read_b128 v[132:135], v140 offset:1024
	ds_read_b128 v[136:139], v140 offset:2048
	ds_read_b128 v[140:143], v140 offset:3072
	ds_read_b128 v[144:147], v156
	ds_read_b128 v[148:151], v156 offset:1024
	ds_read_b128 v[152:155], v156 offset:2048
	ds_read_b128 v[156:159], v156 offset:3072
	ds_read_b128 v[176:179], v197 offset:32768
	ds_read_b128 v[180:183], v197 offset:33792
	ds_read_b128 v[184:187], v197 offset:34816
	ds_read_b128 v[188:191], v197 offset:35840
	ds_read_b128 v[198:201], v197 offset:36864
	ds_read_b128 v[202:205], v197 offset:37888
	ds_read_b128 v[206:209], v197 offset:38912
	ds_read_b128 v[210:213], v197 offset:39936
	s_waitcnt lgkmcnt(0)
	s_barrier
	v_mfma_f32_16x16x32_bf16 v[120:123], v[128:131], v[176:179], v[120:123]
	v_mfma_f32_16x16x32_bf16 v[124:127], v[136:139], v[176:179], v[124:127]
	v_mfma_f32_16x16x32_bf16 v[104:107], v[128:131], v[184:187], v[104:107]
	v_mfma_f32_16x16x32_bf16 v[108:111], v[136:139], v[184:187], v[108:111]
	v_mfma_f32_16x16x32_bf16 v[88:91], v[128:131], v[198:201], v[88:91]
	v_mfma_f32_16x16x32_bf16 v[92:95], v[136:139], v[198:201], v[92:95]
	v_mfma_f32_16x16x32_bf16 v[72:75], v[128:131], v[206:209], v[72:75]
	v_mfma_f32_16x16x32_bf16 v[76:79], v[136:139], v[206:209], v[76:79]
	v_mfma_f32_16x16x32_bf16 v[120:123], v[132:135], v[180:183], v[120:123]
	v_mfma_f32_16x16x32_bf16 v[124:127], v[140:143], v[180:183], v[124:127]
	v_mfma_f32_16x16x32_bf16 v[104:107], v[132:135], v[188:191], v[104:107]
	v_mfma_f32_16x16x32_bf16 v[108:111], v[140:143], v[188:191], v[108:111]
	v_mfma_f32_16x16x32_bf16 v[88:91], v[132:135], v[202:205], v[88:91]
	v_mfma_f32_16x16x32_bf16 v[92:95], v[140:143], v[202:205], v[92:95]
	v_mfma_f32_16x16x32_bf16 v[72:75], v[132:135], v[210:213], v[72:75]
	v_mfma_f32_16x16x32_bf16 v[76:79], v[140:143], v[210:213], v[76:79]
	v_mfma_f32_16x16x32_bf16 v[112:115], v[144:147], v[176:179], v[112:115]
	v_mfma_f32_16x16x32_bf16 v[116:119], v[152:155], v[176:179], v[116:119]
	v_mfma_f32_16x16x32_bf16 v[96:99], v[144:147], v[184:187], v[96:99]
	v_mfma_f32_16x16x32_bf16 v[100:103], v[152:155], v[184:187], v[100:103]
	v_mfma_f32_16x16x32_bf16 v[80:83], v[144:147], v[198:201], v[80:83]
	v_mfma_f32_16x16x32_bf16 v[84:87], v[152:155], v[198:201], v[84:87]
	v_mfma_f32_16x16x32_bf16 v[64:67], v[144:147], v[206:209], v[64:67]
	v_mfma_f32_16x16x32_bf16 v[68:71], v[152:155], v[206:209], v[68:71]
	v_mfma_f32_16x16x32_bf16 v[112:115], v[148:151], v[180:183], v[112:115]
	v_mfma_f32_16x16x32_bf16 v[116:119], v[156:159], v[180:183], v[116:119]
	v_mfma_f32_16x16x32_bf16 v[96:99], v[148:151], v[188:191], v[96:99]
	v_mfma_f32_16x16x32_bf16 v[100:103], v[156:159], v[188:191], v[100:103]
	v_mfma_f32_16x16x32_bf16 v[80:83], v[148:151], v[202:205], v[80:83]
	v_mfma_f32_16x16x32_bf16 v[84:87], v[156:159], v[202:205], v[84:87]
	v_mfma_f32_16x16x32_bf16 v[64:67], v[148:151], v[210:213], v[64:67]
	v_mfma_f32_16x16x32_bf16 v[68:71], v[156:159], v[210:213], v[68:71]
	s_waitcnt vmcnt(8)
	s_barrier
; #define PG8_STAGE(bufoff, gbase, voff) do { _Pragma("unroll") for (int _i = 0; _i < 2; ++_i) \
;         __builtin_amdgcn_global_load_lds((const unsigned*)((const char*)(gbase) + (voff)[_i]), (PG8_LAS unsigned*)(lds + (bufoff) + ldsw + _i * 8192), 16, 0, 0); } while (0)
; #define PG8_LDA(dst, b, h) do { _Pragma("unroll") for (int m = 0; m < 4; ++m) _Pragma("unroll") for (int k = 0; k < 2; ++k) dst[m][k] = *(const PG8_LAS bf16x8*)(lds + PG8_SA(b, h) + aoff + m * 2048 + k * 1024); } while (0)
; #define PG8_LDB(dst, b, h) do { _Pragma("unroll") for (int n = 0; n < 2; ++n) _Pragma("unroll") for (int k = 0; k < 2; ++k) dst[n][k] = *(const PG8_LAS bf16x8*)(lds + PG8_SB(b, h) + boff + n * 2048 + k * 1024); } while (0)
; #define PG8_MMA(ai, bj, At, Bt) do { __builtin_amdgcn_s_setprio(1); _Pragma("unroll") for (int m = 0; m < 4; ++m) _Pragma("unroll") for (int n = 0; n < 2; ++n) _Pragma("unroll") for (int k = 0; k < 2; ++k) \
;         acc[ai][bj][m][n] = __builtin_amdgcn_mfma_f32_16x16x32_bf16(Bt[n][k], At[m][k], acc[ai][bj][m][n], 0, 0, 0); __builtin_amdgcn_s_setprio(0); } while (0)
; #define PG8_WAIT_V(n) asm volatile("s_waitcnt vmcnt(" #n ")" ::: "memory")
; #define PG8_WAIT_L(n) asm volatile("s_waitcnt lgkmcnt(" #n ")" ::: "memory")
; template <class Epi, class Sched, bool ALIGN_EPI = false, bool SP2 = false>
; __device__ __forceinline__ void gemm_phase(PG8_LAS unsigned char* lds, const Gemm g, const Sched& S, const Epi& E, int tid_in) {
;     ...
;             const bool last = (t == nt - 2);
;             const char* a1 = cA + (size_t)(t + 1) * kstep;
;             const char* a2 = last ? nA : cA + (size_t)(t + 2) * kstep; const char* b2 = last ? nB : cB + (size_t)(t + 2) * kstep;
;             const char* a3 = a2 + kstep; const char* b3 = b2 + kstep;
;             if (last && has_next) S.a_ready(nxt);
;             if constexpr (SP2) {
;             PG8_LDB(B0, 0, 0); PG8_LDB(B1, 0, 1); PG8_SCHED; PG8_LDA(At, 0, 0); PG8_STAGE(PG8_SA(1, 1), a1 + hstep, voffA);
;             PG8_WAIT_V(8); PG8_WAIT_L(0); PG8_BAR; PG8_MMA(0, 0, At, B0); PG8_MMA(0, 1, At, B1); PG8_BAR; PG8_SCHED;
;     ...
;             PG8_LDA(At, 1, 1); PG8_STAGE(PG8_SB(1, 0), b3, voffB); PG8_STAGE(PG8_SB(1, 1), b3 + hstep, voffB); PG8_STAGE(PG8_SA(1, 0), a3, voffA);
;             PG8_WAIT_V(8); PG8_WAIT_L(0); PG8_BAR; PG8_MMA(1, 0, At, B0); PG8_MMA(1, 1, At, B1); PG8_BAR; PG8_SCHED;
	s_add_i32 s20, s51, s31
	s_mov_b32 m0, s20
	ds_read_b128 v[176:179], v197 offset:49152
	global_load_lds_dwordx4 v162, s[98:99]
	s_add_i32 m0, s20, 0x2000
	s_add_u32 s20, s22, 0xb0080
	s_addc_u32 s21, s23, 0
	s_add_i32 s22, s52, s31
	global_load_lds_dwordx4 v166, s[98:99]
	s_mov_b32 m0, s22
	ds_read_b128 v[180:183], v197 offset:50176
	global_load_lds_dwordx4 v162, s[20:21]
	s_add_i32 m0, s22, 0x2000
	ds_read_b128 v[184:187], v197 offset:51200
	global_load_lds_dwordx4 v166, s[20:21]
	s_mov_b32 m0, s39
	ds_read_b128 v[188:191], v197 offset:52224
	global_load_lds_dwordx4 v160, s[100:101]
	s_mov_b32 m0, s40
	ds_read_b128 v[198:201], v197 offset:53248
	global_load_lds_dwordx4 v164, s[100:101]
	ds_read_b128 v[202:205], v197 offset:54272
	ds_read_b128 v[206:209], v197 offset:55296
	ds_read_b128 v[210:213], v197 offset:56320
	s_waitcnt lgkmcnt(0)
	s_barrier
	v_mfma_f32_16x16x32_bf16 v[56:59], v[128:131], v[176:179], v[56:59]
	v_mfma_f32_16x16x32_bf16 v[60:63], v[136:139], v[176:179], v[60:63]
	v_mfma_f32_16x16x32_bf16 v[40:43], v[128:131], v[184:187], v[40:43]
	v_mfma_f32_16x16x32_bf16 v[44:47], v[136:139], v[184:187], v[44:47]
	v_mfma_f32_16x16x32_bf16 v[24:27], v[128:131], v[198:201], v[24:27]
	v_mfma_f32_16x16x32_bf16 v[28:31], v[136:139], v[198:201], v[28:31]
	v_mfma_f32_16x16x32_bf16 v[8:11], v[128:131], v[206:209], v[8:11]
	v_mfma_f32_16x16x32_bf16 v[12:15], v[136:139], v[206:209], v[12:15]
	v_mfma_f32_16x16x32_bf16 v[56:59], v[132:135], v[180:183], v[56:59]
	v_mfma_f32_16x16x32_bf16 v[60:63], v[140:143], v[180:183], v[60:63]
	v_mfma_f32_16x16x32_bf16 v[40:43], v[132:135], v[188:191], v[40:43]
	v_mfma_f32_16x16x32_bf16 v[44:47], v[140:143], v[188:191], v[44:47]
	v_mfma_f32_16x16x32_bf16 v[24:27], v[132:135], v[202:205], v[24:27]
	v_mfma_f32_16x16x32_bf16 v[28:31], v[140:143], v[202:205], v[28:31]
	v_mfma_f32_16x16x32_bf16 v[8:11], v[132:135], v[210:213], v[8:11]
	v_mfma_f32_16x16x32_bf16 v[12:15], v[140:143], v[210:213], v[12:15]
	v_mfma_f32_16x16x32_bf16 v[48:51], v[144:147], v[176:179], v[48:51]
	v_mfma_f32_16x16x32_bf16 v[52:55], v[152:155], v[176:179], v[52:55]
	v_mfma_f32_16x16x32_bf16 v[32:35], v[144:147], v[184:187], v[32:35]
	v_mfma_f32_16x16x32_bf16 v[36:39], v[152:155], v[184:187], v[36:39]
	v_mfma_f32_16x16x32_bf16 v[16:19], v[144:147], v[198:201], v[16:19]
	v_mfma_f32_16x16x32_bf16 v[20:23], v[152:155], v[198:201], v[20:23]
	v_mfma_f32_16x16x32_bf16 v[4:7], v[144:147], v[206:209], v[4:7]
	v_mfma_f32_16x16x32_bf16 v[0:3], v[152:155], v[206:209], v[0:3]
	v_mfma_f32_16x16x32_bf16 v[48:51], v[148:151], v[180:183], v[48:51]
	v_mfma_f32_16x16x32_bf16 v[52:55], v[156:159], v[180:183], v[52:55]
	v_mfma_f32_16x16x32_bf16 v[32:35], v[148:151], v[188:191], v[32:35]
	v_mfma_f32_16x16x32_bf16 v[36:39], v[156:159], v[188:191], v[36:39]
	v_mfma_f32_16x16x32_bf16 v[16:19], v[148:151], v[202:205], v[16:19]
	v_mfma_f32_16x16x32_bf16 v[20:23], v[156:159], v[202:205], v[20:23]
	v_mfma_f32_16x16x32_bf16 v[4:7], v[148:151], v[210:213], v[4:7]
	v_mfma_f32_16x16x32_bf16 v[0:3], v[156:159], v[210:213], v[0:3]
	s_waitcnt vmcnt(8)
	s_barrier
	s_add_i32 s50, s50, 2
	s_add_u32 s48, s48, 0x100
	s_addc_u32 s49, s49, 0
	s_cmp_gt_u32 s50, 41
	s_mov_b64 s[20:21], s[2:3]
	s_cbranch_scc0 .LBB0_1321
	s_branch .Lasym_J_1321
.Lasym_T_1321:
	s_add_u32 s2, s20, 0x100
	s_addc_u32 s3, s21, 0
	s_cmp_eq_u32 s50, 40
	s_cselect_b32 s25, s17, s3
	s_cselect_b32 s24, s16, s2
	s_cselect_b32 s23, s19, s49
	s_cselect_b32 s22, s18, s48
	s_add_i32 m0, s34, 0xc000
	ds_read_b128 v[128:131], v195
	global_load_lds_dwordx4 v168, s[20:21]
	s_add_i32 m0, s34, 0xe000
	ds_read_b128 v[132:135], v195 offset:1024
	global_load_lds_dwordx4 v170, s[20:21]
	ds_read_b128 v[136:139], v195 offset:2048
	ds_read_b128 v[140:143], v195 offset:3072
	ds_read_b128 v[144:147], v196
	ds_read_b128 v[148:151], v196 offset:1024
	ds_read_b128 v[152:155], v196 offset:2048
	ds_read_b128 v[156:159], v196 offset:3072
	ds_read_b128 v[176:179], v197
	ds_read_b128 v[180:183], v197 offset:1024
	ds_read_b128 v[184:187], v197 offset:2048
	ds_read_b128 v[188:191], v197 offset:3072
	ds_read_b128 v[198:201], v197 offset:4096
	ds_read_b128 v[202:205], v197 offset:5120
	ds_read_b128 v[206:209], v197 offset:6144
	ds_read_b128 v[210:213], v197 offset:7168
	s_waitcnt vmcnt(8)
	s_waitcnt lgkmcnt(0)
	s_barrier
	v_mfma_f32_16x16x32_bf16 v[120:123], v[128:131], v[176:179], v[120:123]
	v_mfma_f32_16x16x32_bf16 v[124:127], v[136:139], v[176:179], v[124:127]
	v_mfma_f32_16x16x32_bf16 v[104:107], v[128:131], v[184:187], v[104:107]
	v_mfma_f32_16x16x32_bf16 v[108:111], v[136:139], v[184:187], v[108:111]
	v_mfma_f32_16x16x32_bf16 v[88:91], v[128:131], v[198:201], v[88:91]
	v_mfma_f32_16x16x32_bf16 v[92:95], v[136:139], v[198:201], v[92:95]
	v_mfma_f32_16x16x32_bf16 v[72:75], v[128:131], v[206:209], v[72:75]
	v_mfma_f32_16x16x32_bf16 v[76:79], v[136:139], v[206:209], v[76:79]
	v_mfma_f32_16x16x32_bf16 v[120:123], v[132:135], v[180:183], v[120:123]
	v_mfma_f32_16x16x32_bf16 v[124:127], v[140:143], v[180:183], v[124:127]
	v_mfma_f32_16x16x32_bf16 v[104:107], v[132:135], v[188:191], v[104:107]
	v_mfma_f32_16x16x32_bf16 v[108:111], v[140:143], v[188:191], v[108:111]
	v_mfma_f32_16x16x32_bf16 v[88:91], v[132:135], v[202:205], v[88:91]
	v_mfma_f32_16x16x32_bf16 v[92:95], v[140:143], v[202:205], v[92:95]
	v_mfma_f32_16x16x32_bf16 v[72:75], v[132:135], v[210:213], v[72:75]
	v_mfma_f32_16x16x32_bf16 v[76:79], v[140:143], v[210:213], v[76:79]
	v_mfma_f32_16x16x32_bf16 v[112:115], v[144:147], v[176:179], v[112:115]
	v_mfma_f32_16x16x32_bf16 v[116:119], v[152:155], v[176:179], v[116:119]
	v_mfma_f32_16x16x32_bf16 v[96:99], v[144:147], v[184:187], v[96:99]
	v_mfma_f32_16x16x32_bf16 v[100:103], v[152:155], v[184:187], v[100:103]
	v_mfma_f32_16x16x32_bf16 v[80:83], v[144:147], v[198:201], v[80:83]
	v_mfma_f32_16x16x32_bf16 v[84:87], v[152:155], v[198:201], v[84:87]
	v_mfma_f32_16x16x32_bf16 v[64:67], v[144:147], v[206:209], v[64:67]
	v_mfma_f32_16x16x32_bf16 v[68:71], v[152:155], v[206:209], v[68:71]
	v_mfma_f32_16x16x32_bf16 v[112:115], v[148:151], v[180:183], v[112:115]
	v_mfma_f32_16x16x32_bf16 v[116:119], v[156:159], v[180:183], v[116:119]
	v_mfma_f32_16x16x32_bf16 v[96:99], v[148:151], v[188:191], v[96:99]
	v_mfma_f32_16x16x32_bf16 v[100:103], v[156:159], v[188:191], v[100:103]
	v_mfma_f32_16x16x32_bf16 v[80:83], v[148:151], v[202:205], v[80:83]
	v_mfma_f32_16x16x32_bf16 v[84:87], v[156:159], v[202:205], v[84:87]
	v_mfma_f32_16x16x32_bf16 v[64:67], v[148:151], v[210:213], v[64:67]
	v_mfma_f32_16x16x32_bf16 v[68:71], v[156:159], v[210:213], v[68:71]
	s_barrier
; #define PG8_STAGE(bufoff, gbase, voff) do { _Pragma("unroll") for (int _i = 0; _i < 2; ++_i) \
;         __builtin_amdgcn_global_load_lds((const unsigned*)((const char*)(gbase) + (voff)[_i]), (PG8_LAS unsigned*)(lds + (bufoff) + ldsw + _i * 8192), 16, 0, 0); } while (0)
; #define PG8_LDA(dst, b, h) do { _Pragma("unroll") for (int m = 0; m < 4; ++m) _Pragma("unroll") for (int k = 0; k < 2; ++k) dst[m][k] = *(const PG8_LAS bf16x8*)(lds + PG8_SA(b, h) + aoff + m * 2048 + k * 1024); } while (0)
; #define PG8_LDB(dst, b, h) do { _Pragma("unroll") for (int n = 0; n < 2; ++n) _Pragma("unroll") for (int k = 0; k < 2; ++k) dst[n][k] = *(const PG8_LAS bf16x8*)(lds + PG8_SB(b, h) + boff + n * 2048 + k * 1024); } while (0)
; #define PG8_MMA(ai, bj, At, Bt) do { __builtin_amdgcn_s_setprio(1); _Pragma("unroll") for (int m = 0; m < 4; ++m) _Pragma("unroll") for (int n = 0; n < 2; ++n) _Pragma("unroll") for (int k = 0; k < 2; ++k) \
;         acc[ai][bj][m][n] = __builtin_amdgcn_mfma_f32_16x16x32_bf16(Bt[n][k], At[m][k], acc[ai][bj][m][n], 0, 0, 0); __builtin_amdgcn_s_setprio(0); } while (0)
; #define PG8_WAIT_V(n) asm volatile("s_waitcnt vmcnt(" #n ")" ::: "memory")
; #define PG8_WAIT_L(n) asm volatile("s_waitcnt lgkmcnt(" #n ")" ::: "memory")
; #define PG8_BAR __builtin_amdgcn_s_barrier()
; #define PG8_SCHED __builtin_amdgcn_sched_barrier(0)
; template <class Epi, class Sched, bool ALIGN_EPI = false, bool SP2 = false>
; __device__ __forceinline__ void gemm_phase(PG8_LAS unsigned char* lds, const Gemm g, const Sched& S, const Epi& E, int tid_in) {
;     ...
;             PG8_LDA(At, 0, 1); PG8_STAGE(PG8_SB(0, 0), b2, voffB); PG8_STAGE(PG8_SB(0, 1), b2 + hstep, voffB); PG8_STAGE(PG8_SA(0, 0), a2, voffA);
;             PG8_WAIT_V(8); PG8_WAIT_L(0); PG8_BAR; PG8_MMA(1, 0, At, B0); PG8_MMA(1, 1, At, B1); PG8_BAR; PG8_SCHED;
;             PG8_LDB(B0, 1, 0); PG8_LDB(B1, 1, 1); PG8_SCHED; PG8_LDA(At, 1, 0); PG8_STAGE(PG8_SA(0, 1), a2 + hstep, voffA);
;             PG8_WAIT_V(8); PG8_WAIT_L(0); PG8_BAR; PG8_MMA(0, 0, At, B0); PG8_MMA(0, 1, At, B1); PG8_BAR; PG8_SCHED;
	s_add_u32 s98, s22, s10
	s_addc_u32 s99, s23, s11
	s_add_u32 s100, s24, s10
	s_addc_u32 s101, s25, s11
	s_add_i32 s20, s42, s31
	s_mov_b32 m0, s20
	ds_read_b128 v[176:179], v197 offset:16384
	global_load_lds_dwordx4 v162, s[22:23]
	s_add_i32 m0, s20, 0x2000
	s_add_u32 s20, s22, 0xb0000
	s_addc_u32 s21, s23, 0
	s_add_i32 s51, s43, s31
	global_load_lds_dwordx4 v166, s[22:23]
	s_mov_b32 m0, s51
	ds_read_b128 v[180:183], v197 offset:17408
	global_load_lds_dwordx4 v162, s[20:21]
	s_add_i32 m0, s51, 0x2000
	ds_read_b128 v[184:187], v197 offset:18432
	global_load_lds_dwordx4 v166, s[20:21]
	s_mov_b32 m0, s34
	ds_read_b128 v[188:191], v197 offset:19456
	global_load_lds_dwordx4 v160, s[24:25]
	s_mov_b32 m0, s35
	ds_read_b128 v[198:201], v197 offset:20480
	global_load_lds_dwordx4 v164, s[24:25]
	ds_read_b128 v[202:205], v197 offset:21504
	ds_read_b128 v[206:209], v197 offset:22528
	ds_read_b128 v[210:213], v197 offset:23552
	s_waitcnt vmcnt(8)
	s_waitcnt lgkmcnt(0)
	s_barrier
	v_mfma_f32_16x16x32_bf16 v[56:59], v[128:131], v[176:179], v[56:59]
	v_mfma_f32_16x16x32_bf16 v[60:63], v[136:139], v[176:179], v[60:63]
	v_mfma_f32_16x16x32_bf16 v[40:43], v[128:131], v[184:187], v[40:43]
	v_mfma_f32_16x16x32_bf16 v[44:47], v[136:139], v[184:187], v[44:47]
	v_mfma_f32_16x16x32_bf16 v[24:27], v[128:131], v[198:201], v[24:27]
	v_mfma_f32_16x16x32_bf16 v[28:31], v[136:139], v[198:201], v[28:31]
	v_mfma_f32_16x16x32_bf16 v[8:11], v[128:131], v[206:209], v[8:11]
	v_mfma_f32_16x16x32_bf16 v[12:15], v[136:139], v[206:209], v[12:15]
	v_mfma_f32_16x16x32_bf16 v[56:59], v[132:135], v[180:183], v[56:59]
	v_mfma_f32_16x16x32_bf16 v[60:63], v[140:143], v[180:183], v[60:63]
	v_mfma_f32_16x16x32_bf16 v[40:43], v[132:135], v[188:191], v[40:43]
	v_mfma_f32_16x16x32_bf16 v[44:47], v[140:143], v[188:191], v[44:47]
	v_mfma_f32_16x16x32_bf16 v[24:27], v[132:135], v[202:205], v[24:27]
	v_mfma_f32_16x16x32_bf16 v[28:31], v[140:143], v[202:205], v[28:31]
	v_mfma_f32_16x16x32_bf16 v[8:11], v[132:135], v[210:213], v[8:11]
	v_mfma_f32_16x16x32_bf16 v[12:15], v[140:143], v[210:213], v[12:15]
	v_mfma_f32_16x16x32_bf16 v[48:51], v[144:147], v[176:179], v[48:51]
	v_mfma_f32_16x16x32_bf16 v[52:55], v[152:155], v[176:179], v[52:55]
	v_mfma_f32_16x16x32_bf16 v[32:35], v[144:147], v[184:187], v[32:35]
	v_mfma_f32_16x16x32_bf16 v[36:39], v[152:155], v[184:187], v[36:39]
	v_mfma_f32_16x16x32_bf16 v[16:19], v[144:147], v[198:201], v[16:19]
	v_mfma_f32_16x16x32_bf16 v[20:23], v[152:155], v[198:201], v[20:23]
	v_mfma_f32_16x16x32_bf16 v[4:7], v[144:147], v[206:209], v[4:7]
	v_mfma_f32_16x16x32_bf16 v[0:3], v[152:155], v[206:209], v[0:3]
	v_mfma_f32_16x16x32_bf16 v[48:51], v[148:151], v[180:183], v[48:51]
	v_mfma_f32_16x16x32_bf16 v[52:55], v[156:159], v[180:183], v[52:55]
	v_mfma_f32_16x16x32_bf16 v[32:35], v[148:151], v[188:191], v[32:35]
	v_mfma_f32_16x16x32_bf16 v[36:39], v[156:159], v[188:191], v[36:39]
	v_mfma_f32_16x16x32_bf16 v[16:19], v[148:151], v[202:205], v[16:19]
	v_mfma_f32_16x16x32_bf16 v[20:23], v[156:159], v[202:205], v[20:23]
	v_mfma_f32_16x16x32_bf16 v[4:7], v[148:151], v[210:213], v[4:7]
	v_mfma_f32_16x16x32_bf16 v[0:3], v[156:159], v[210:213], v[0:3]
	s_barrier
	s_add_i32 s51, 0, 0x18000
	s_add_i32 s52, 0, 0x1c000
	s_add_u32 s20, s24, 0xb0000
	s_addc_u32 s21, s25, 0
	s_mov_b32 m0, s36
	s_nop 0
	global_load_lds_dwordx4 v160, s[20:21]
	s_mov_b32 m0, s37
	s_nop 0
	global_load_lds_dwordx4 v164, s[20:21]
	v_add_u32_e32 v140, s51, v193
	v_add_u32_e32 v156, s52, v193
	ds_read_b128 v[128:131], v140
	ds_read_b128 v[132:135], v140 offset:1024
	ds_read_b128 v[136:139], v140 offset:2048
	ds_read_b128 v[140:143], v140 offset:3072
	ds_read_b128 v[144:147], v156
	ds_read_b128 v[148:151], v156 offset:1024
	ds_read_b128 v[152:155], v156 offset:2048
	ds_read_b128 v[156:159], v156 offset:3072
	ds_read_b128 v[176:179], v197 offset:32768
	ds_read_b128 v[180:183], v197 offset:33792
	ds_read_b128 v[184:187], v197 offset:34816
	ds_read_b128 v[188:191], v197 offset:35840
	ds_read_b128 v[198:201], v197 offset:36864
	ds_read_b128 v[202:205], v197 offset:37888
	ds_read_b128 v[206:209], v197 offset:38912
	ds_read_b128 v[210:213], v197 offset:39936
	s_waitcnt vmcnt(8)
	s_waitcnt lgkmcnt(0)
	s_barrier
	v_mfma_f32_16x16x32_bf16 v[120:123], v[128:131], v[176:179], v[120:123]
	v_mfma_f32_16x16x32_bf16 v[124:127], v[136:139], v[176:179], v[124:127]
	v_mfma_f32_16x16x32_bf16 v[104:107], v[128:131], v[184:187], v[104:107]
	v_mfma_f32_16x16x32_bf16 v[108:111], v[136:139], v[184:187], v[108:111]
	v_mfma_f32_16x16x32_bf16 v[88:91], v[128:131], v[198:201], v[88:91]
	v_mfma_f32_16x16x32_bf16 v[92:95], v[136:139], v[198:201], v[92:95]
	v_mfma_f32_16x16x32_bf16 v[72:75], v[128:131], v[206:209], v[72:75]
	v_mfma_f32_16x16x32_bf16 v[76:79], v[136:139], v[206:209], v[76:79]
	v_mfma_f32_16x16x32_bf16 v[120:123], v[132:135], v[180:183], v[120:123]
	v_mfma_f32_16x16x32_bf16 v[124:127], v[140:143], v[180:183], v[124:127]
	v_mfma_f32_16x16x32_bf16 v[104:107], v[132:135], v[188:191], v[104:107]
	v_mfma_f32_16x16x32_bf16 v[108:111], v[140:143], v[188:191], v[108:111]
	v_mfma_f32_16x16x32_bf16 v[88:91], v[132:135], v[202:205], v[88:91]
	v_mfma_f32_16x16x32_bf16 v[92:95], v[140:143], v[202:205], v[92:95]
	v_mfma_f32_16x16x32_bf16 v[72:75], v[132:135], v[210:213], v[72:75]
	v_mfma_f32_16x16x32_bf16 v[76:79], v[140:143], v[210:213], v[76:79]
	v_mfma_f32_16x16x32_bf16 v[112:115], v[144:147], v[176:179], v[112:115]
	v_mfma_f32_16x16x32_bf16 v[116:119], v[152:155], v[176:179], v[116:119]
	v_mfma_f32_16x16x32_bf16 v[96:99], v[144:147], v[184:187], v[96:99]
	v_mfma_f32_16x16x32_bf16 v[100:103], v[152:155], v[184:187], v[100:103]
	v_mfma_f32_16x16x32_bf16 v[80:83], v[144:147], v[198:201], v[80:83]
	v_mfma_f32_16x16x32_bf16 v[84:87], v[152:155], v[198:201], v[84:87]
	v_mfma_f32_16x16x32_bf16 v[64:67], v[144:147], v[206:209], v[64:67]
	v_mfma_f32_16x16x32_bf16 v[68:71], v[152:155], v[206:209], v[68:71]
	v_mfma_f32_16x16x32_bf16 v[112:115], v[148:151], v[180:183], v[112:115]
	v_mfma_f32_16x16x32_bf16 v[116:119], v[156:159], v[180:183], v[116:119]
	v_mfma_f32_16x16x32_bf16 v[96:99], v[148:151], v[188:191], v[96:99]
	v_mfma_f32_16x16x32_bf16 v[100:103], v[156:159], v[188:191], v[100:103]
	v_mfma_f32_16x16x32_bf16 v[80:83], v[148:151], v[202:205], v[80:83]
	v_mfma_f32_16x16x32_bf16 v[84:87], v[156:159], v[202:205], v[84:87]
	v_mfma_f32_16x16x32_bf16 v[64:67], v[148:151], v[210:213], v[64:67]
	v_mfma_f32_16x16x32_bf16 v[68:71], v[156:159], v[210:213], v[68:71]
	s_barrier
; __device__ __forceinline__ float bf_lo(unsigned w) { return __uint_as_float(w << 16); }
; __device__ __forceinline__ float bf_hi(unsigned w) { return __uint_as_float(w & 0xffff0000u); }
; #define PG8_STAGE(bufoff, gbase, voff) do { _Pragma("unroll") for (int _i = 0; _i < 2; ++_i) \
;         __builtin_amdgcn_global_load_lds((const unsigned*)((const char*)(gbase) + (voff)[_i]), (PG8_LAS unsigned*)(lds + (bufoff) + ldsw + _i * 8192), 16, 0, 0); } while (0)
; #define PG8_LDA(dst, b, h) do { _Pragma("unroll") for (int m = 0; m < 4; ++m) _Pragma("unroll") for (int k = 0; k < 2; ++k) dst[m][k] = *(const PG8_LAS bf16x8*)(lds + PG8_SA(b, h) + aoff + m * 2048 + k * 1024); } while (0)
; #define PG8_MMA(ai, bj, At, Bt) do { __builtin_amdgcn_s_setprio(1); _Pragma("unroll") for (int m = 0; m < 4; ++m) _Pragma("unroll") for (int n = 0; n < 2; ++n) _Pragma("unroll") for (int k = 0; k < 2; ++k) \
;         acc[ai][bj][m][n] = __builtin_amdgcn_mfma_f32_16x16x32_bf16(Bt[n][k], At[m][k], acc[ai][bj][m][n], 0, 0, 0); __builtin_amdgcn_s_setprio(0); } while (0)
; #define PG8_WAIT_V(n) asm volatile("s_waitcnt vmcnt(" #n ")" ::: "memory")
;     __device__ __forceinline__ void operator()(const f32x4 (&acc)[2][2][4][2], const Unit& u, int wr, int wc, int fr, int fq) const {
;     ...
;                 for (int m = 0; m < 4; ++m) { const size_t off = (size_t)(row0 + ai * HALF + m * 16) * 1024 + col0;
; #pragma unroll
;                     for (int bj = 0; bj < 2; ++bj) bw[m][bj] = *(const u32x4*)(bb + off + bj * HALF); }
; #pragma unroll
;                 for (int m = 0; m < 4; ++m)
; #pragma unroll
;                     for (int bj = 0; bj < 2; ++bj) { bs[m][bj][0] = (f32x4){bf_lo(bw[m][bj][0]), bf_hi(bw[m][bj][0]), bf_lo(bw[m][bj][1]), bf_hi(bw[m][bj][1])};
;                         bs[m][bj][1] = (f32x4){bf_lo(bw[m][bj][2]), bf_hi(bw[m][bj][2]), bf_lo(bw[m][bj][3]), bf_hi(bw[m][bj][3])}; }
; template <class Epi, class Sched, bool ALIGN_EPI = false, bool SP2 = false>
; __device__ __forceinline__ void gemm_phase(PG8_LAS unsigned char* lds, const Gemm g, const Sched& S, const Epi& E, int tid_in) {
;     ...
;             PG8_LDA(At, 1, 1); PG8_STAGE(PG8_SB(1, 0), b3, voffB); PG8_STAGE(PG8_SB(1, 1), b3 + hstep, voffB); PG8_STAGE(PG8_SA(1, 0), a3, voffA);
;             PG8_WAIT_V(8); PG8_WAIT_L(0); PG8_BAR; PG8_MMA(1, 0, At, B0); PG8_MMA(1, 1, At, B1); PG8_BAR; PG8_SCHED;
	s_add_i32 s20, s51, s31
	s_mov_b32 m0, s20
	ds_read_b128 v[176:179], v197 offset:49152
	global_load_lds_dwordx4 v162, s[98:99]
	s_add_i32 m0, s20, 0x2000
	s_add_u32 s20, s22, 0xb0080
	s_addc_u32 s21, s23, 0
	s_add_i32 s22, s52, s31
	global_load_lds_dwordx4 v166, s[98:99]
	s_mov_b32 m0, s22
	ds_read_b128 v[180:183], v197 offset:50176
	global_load_lds_dwordx4 v162, s[20:21]
	s_add_i32 m0, s22, 0x2000
	ds_read_b128 v[184:187], v197 offset:51200
	global_load_lds_dwordx4 v166, s[20:21]
	s_mov_b32 m0, s39
	ds_read_b128 v[188:191], v197 offset:52224
	global_load_lds_dwordx4 v160, s[100:101]
	s_mov_b32 m0, s40
	ds_read_b128 v[198:201], v197 offset:53248
	global_load_lds_dwordx4 v164, s[100:101]
	ds_read_b128 v[202:205], v197 offset:54272
	ds_read_b128 v[206:209], v197 offset:55296
	ds_read_b128 v[210:213], v197 offset:56320
	s_waitcnt vmcnt(8)
	s_waitcnt lgkmcnt(0)
	s_barrier
	v_mfma_f32_16x16x32_bf16 v[56:59], v[128:131], v[176:179], v[56:59]
	v_mfma_f32_16x16x32_bf16 v[60:63], v[136:139], v[176:179], v[60:63]
	v_mfma_f32_16x16x32_bf16 v[40:43], v[128:131], v[184:187], v[40:43]
	v_mfma_f32_16x16x32_bf16 v[44:47], v[136:139], v[184:187], v[44:47]
	v_mfma_f32_16x16x32_bf16 v[24:27], v[128:131], v[198:201], v[24:27]
	v_mfma_f32_16x16x32_bf16 v[28:31], v[136:139], v[198:201], v[28:31]
	v_mfma_f32_16x16x32_bf16 v[8:11], v[128:131], v[206:209], v[8:11]
	v_mfma_f32_16x16x32_bf16 v[12:15], v[136:139], v[206:209], v[12:15]
	v_mfma_f32_16x16x32_bf16 v[56:59], v[132:135], v[180:183], v[56:59]
	v_mfma_f32_16x16x32_bf16 v[60:63], v[140:143], v[180:183], v[60:63]
	v_mfma_f32_16x16x32_bf16 v[40:43], v[132:135], v[188:191], v[40:43]
	v_mfma_f32_16x16x32_bf16 v[44:47], v[140:143], v[188:191], v[44:47]
	v_mfma_f32_16x16x32_bf16 v[24:27], v[132:135], v[202:205], v[24:27]
	v_mfma_f32_16x16x32_bf16 v[28:31], v[140:143], v[202:205], v[28:31]
	v_mfma_f32_16x16x32_bf16 v[8:11], v[132:135], v[210:213], v[8:11]
	v_mfma_f32_16x16x32_bf16 v[12:15], v[140:143], v[210:213], v[12:15]
	v_mfma_f32_16x16x32_bf16 v[48:51], v[144:147], v[176:179], v[48:51]
	v_mfma_f32_16x16x32_bf16 v[52:55], v[152:155], v[176:179], v[52:55]
	v_mfma_f32_16x16x32_bf16 v[32:35], v[144:147], v[184:187], v[32:35]
	v_mfma_f32_16x16x32_bf16 v[36:39], v[152:155], v[184:187], v[36:39]
	v_mfma_f32_16x16x32_bf16 v[16:19], v[144:147], v[198:201], v[16:19]
	v_mfma_f32_16x16x32_bf16 v[20:23], v[152:155], v[198:201], v[20:23]
	v_mfma_f32_16x16x32_bf16 v[4:7], v[144:147], v[206:209], v[4:7]
	v_mfma_f32_16x16x32_bf16 v[0:3], v[152:155], v[206:209], v[0:3]
	v_mfma_f32_16x16x32_bf16 v[48:51], v[148:151], v[180:183], v[48:51]
	v_mfma_f32_16x16x32_bf16 v[52:55], v[156:159], v[180:183], v[52:55]
	v_mfma_f32_16x16x32_bf16 v[32:35], v[148:151], v[188:191], v[32:35]
	v_mfma_f32_16x16x32_bf16 v[36:39], v[156:159], v[188:191], v[36:39]
	v_mfma_f32_16x16x32_bf16 v[16:19], v[148:151], v[202:205], v[16:19]
	v_mfma_f32_16x16x32_bf16 v[20:23], v[156:159], v[202:205], v[20:23]
	v_mfma_f32_16x16x32_bf16 v[4:7], v[148:151], v[210:213], v[4:7]
	v_mfma_f32_16x16x32_bf16 v[0:3], v[156:159], v[210:213], v[0:3]
	s_barrier
	s_add_i32 s50, s50, 2
	s_add_u32 s48, s48, 0x100
	s_addc_u32 s49, s49, 0
	s_cmp_gt_u32 s50, 41
	s_mov_b64 s[20:21], s[2:3]
	s_cbranch_scc0 .Lasym_T_1321
.Lasym_J_1321:
	s_and_b64 vcc, exec, s[12:13]
	s_cbranch_vccz .LBB0_1324
	s_barrier
.LBB0_1324:
	v_lshl_add_u32 v180, s46, 8, v192
	v_lshl_or_b32 v176, s47, 8, v194
	v_or_b32_e32 v190, 16, v180
	v_or_b32_e32 v188, 32, v180
	v_or_b32_e32 v186, 48, v180
	v_ashrrev_i32_e32 v177, 31, v176
	v_ashrrev_i32_e32 v181, 31, v180
	v_ashrrev_i32_e32 v191, 31, v190
	v_ashrrev_i32_e32 v189, 31, v188
	v_ashrrev_i32_e32 v187, 31, v186
	v_lshl_add_u64 v[178:179], v[176:177], 1, s[8:9]
	v_lshlrev_b64 v[128:129], 11, v[180:181]
	v_lshlrev_b64 v[136:137], 11, v[190:191]
	v_lshlrev_b64 v[144:145], 11, v[188:189]
	v_lshlrev_b64 v[152:153], 11, v[186:187]
	v_lshl_add_u64 v[132:133], v[178:179], 0, v[128:129]
	v_lshl_add_u64 v[140:141], v[178:179], 0, v[136:137]
	v_lshl_add_u64 v[148:149], v[178:179], 0, v[144:145]
	v_lshl_add_u64 v[156:157], v[178:179], 0, v[152:153]
	global_load_dwordx4 v[128:131], v[132:133], off
	s_nop 0
	global_load_dwordx4 v[132:135], v[132:133], off offset:256
	s_nop 0
	global_load_dwordx4 v[136:139], v[140:141], off
	s_nop 0
	global_load_dwordx4 v[140:143], v[140:141], off offset:256
	s_nop 0
	global_load_dwordx4 v[144:147], v[148:149], off
	s_nop 0
	global_load_dwordx4 v[148:151], v[148:149], off offset:256
	s_nop 0
	global_load_dwordx4 v[152:155], v[156:157], off
	s_nop 0
	global_load_dwordx4 v[156:159], v[156:157], off offset:256
	v_cndmask_b32_e64 v182, 0, 1, s[14:15]
	v_cmp_ne_u32_e64 s[2:3], 1, v182
	s_andn2_b64 vcc, exec, s[14:15]
	v_lshlrev_b64 v[176:177], 2, v[176:177]
	s_cbranch_vccnz .LBB0_1326
; __device__ __forceinline__ unsigned cvt_pk_bf16(float lo, float hi) { f32x2 v = {lo, hi}; bf16x2_t b = __builtin_convertvector(v, bf16x2_t); return __builtin_bit_cast(unsigned, b); }
;     __device__ __forceinline__ void operator()(const f32x4 (&acc)[2][2][4][2], const Unit& u, int wr, int wc, int fr, int fq) const {
;     ...
;             for (int m = 0; m < 4; ++m) { const int row = row0 + ai * HALF + m * 16; const size_t off = (size_t)row * 1024 + col0; float ss = 0.f;
; #pragma unroll
;                 for (int bj = 0; bj < 2; ++bj) { const f32x4 v0 = bs[m][bj][0] + acc[ai][bj][m][0] * alpha, v1 = bs[m][bj][1] + acc[ai][bj][m][1] * alpha;
;                     ss += ((v0[0] * v0[0] + v0[1] * v0[1]) + (v0[2] * v0[2] + v0[3] * v0[3])) + ((v1[0] * v1[0] + v1[1] * v1[1]) + (v1[2] * v1[2] + v1[3] * v1[3]));
;                     if (of) { *(f32x4*)(of + off + bj * HALF) = v0; *(f32x4*)(of + off + bj * HALF + 4) = v1; }
;                     if (ob) { u32x4 w; w.x = cvt_pk_bf16(v0[0], v0[1]); w.y = cvt_pk_bf16(v0[2], v0[3]); w.z = cvt_pk_bf16(v1[0], v1[1]); w.w = cvt_pk_bf16(v1[2], v1[3]); *(u32x4*)(ob + off + bj * HALF) = w; } }
	v_lshlrev_b64 v[222:223], 12, v[180:181]
	s_waitcnt vmcnt(0)
	v_lshlrev_b32_e32 v224, 16, v130
	v_and_b32_e32 v225, 0xffff0000, v130
	v_lshlrev_b32_e32 v130, 16, v131
	v_and_b32_e32 v131, 0xffff0000, v131
	v_lshlrev_b32_e32 v220, 16, v132
	v_and_b32_e32 v221, 0xffff0000, v132
	v_lshlrev_b32_e32 v132, 16, v133
	v_and_b32_e32 v133, 0xffff0000, v133
	v_lshl_add_u64 v[222:223], s[4:5], 0, v[222:223]
	v_pk_fma_f32 v[126:127], v[126:127], 0.5, v[130:131] op_sel_hi:[1,0,1]
	v_lshlrev_b32_e32 v130, 16, v128
	v_and_b32_e32 v131, 0xffff0000, v128
	v_lshlrev_b32_e32 v128, 16, v129
	v_and_b32_e32 v129, 0xffff0000, v129
	v_lshlrev_b32_e32 v218, 16, v134
	v_and_b32_e32 v219, 0xffff0000, v134
	v_lshlrev_b32_e32 v134, 16, v135
	v_and_b32_e32 v135, 0xffff0000, v135
	v_lshl_add_u64 v[222:223], v[222:223], 0, v[176:177]
	v_pk_fma_f32 v[122:123], v[122:123], 0.5, v[128:129] op_sel_hi:[1,0,1]
	v_pk_fma_f32 v[120:121], v[120:121], 0.5, v[130:131] op_sel_hi:[1,0,1]
	v_pk_fma_f32 v[114:115], v[114:115], 0.5, v[132:133] op_sel_hi:[1,0,1]
	v_pk_fma_f32 v[112:113], v[112:113], 0.5, v[220:221] op_sel_hi:[1,0,1]
	v_pk_fma_f32 v[124:125], v[124:125], 0.5, v[224:225] op_sel_hi:[1,0,1]
	global_store_dwordx4 v[222:223], v[120:123], off
	global_store_dwordx4 v[222:223], v[124:127], off offset:16
	v_pk_fma_f32 v[118:119], v[118:119], 0.5, v[134:135] op_sel_hi:[1,0,1]
	v_pk_fma_f32 v[116:117], v[116:117], 0.5, v[218:219] op_sel_hi:[1,0,1]
	global_store_dwordx4 v[222:223], v[112:115], off offset:512
	global_store_dwordx4 v[222:223], v[116:119], off offset:528
	v_lshlrev_b32_e32 v212, 16, v140
	v_lshlrev_b64 v[112:113], 12, v[190:191]
	v_and_b32_e32 v213, 0xffff0000, v140
	v_lshlrev_b32_e32 v140, 16, v141
	v_and_b32_e32 v141, 0xffff0000, v141
	v_lshlrev_b32_e32 v216, 16, v136
	v_and_b32_e32 v217, 0xffff0000, v136
	v_lshlrev_b32_e32 v136, 16, v137
	v_and_b32_e32 v137, 0xffff0000, v137
	v_lshl_add_u64 v[112:113], s[4:5], 0, v[112:113]
	v_lshlrev_b32_e32 v210, 16, v142
	v_and_b32_e32 v211, 0xffff0000, v142
	v_lshlrev_b32_e32 v142, 16, v143
	v_and_b32_e32 v143, 0xffff0000, v143
	v_lshlrev_b32_e32 v214, 16, v138
	v_and_b32_e32 v215, 0xffff0000, v138
	v_lshlrev_b32_e32 v138, 16, v139
	v_and_b32_e32 v139, 0xffff0000, v139
	v_lshl_add_u64 v[112:113], v[112:113], 0, v[176:177]
	v_pk_fma_f32 v[106:107], v[106:107], 0.5, v[136:137] op_sel_hi:[1,0,1]
	v_pk_fma_f32 v[104:105], v[104:105], 0.5, v[216:217] op_sel_hi:[1,0,1]
	v_pk_fma_f32 v[98:99], v[98:99], 0.5, v[140:141] op_sel_hi:[1,0,1]
	v_pk_fma_f32 v[96:97], v[96:97], 0.5, v[212:213] op_sel_hi:[1,0,1]
	v_pk_fma_f32 v[110:111], v[110:111], 0.5, v[138:139] op_sel_hi:[1,0,1]
	v_pk_fma_f32 v[108:109], v[108:109], 0.5, v[214:215] op_sel_hi:[1,0,1]
	global_store_dwordx4 v[112:113], v[104:107], off
	global_store_dwordx4 v[112:113], v[108:111], off offset:16
	v_pk_fma_f32 v[102:103], v[102:103], 0.5, v[142:143] op_sel_hi:[1,0,1]
	v_pk_fma_f32 v[100:101], v[100:101], 0.5, v[210:211] op_sel_hi:[1,0,1]
	global_store_dwordx4 v[112:113], v[96:99], off offset:512
	global_store_dwordx4 v[112:113], v[100:103], off offset:528
	v_lshlrev_b32_e32 v204, 16, v148
	v_lshlrev_b64 v[96:97], 12, v[188:189]
	v_and_b32_e32 v205, 0xffff0000, v148
	v_lshlrev_b32_e32 v148, 16, v149
	v_and_b32_e32 v149, 0xffff0000, v149
	v_lshlrev_b32_e32 v208, 16, v144
	v_and_b32_e32 v209, 0xffff0000, v144
	v_lshlrev_b32_e32 v144, 16, v145
	v_and_b32_e32 v145, 0xffff0000, v145
	v_lshl_add_u64 v[96:97], s[4:5], 0, v[96:97]
	v_lshlrev_b32_e32 v202, 16, v150
	v_and_b32_e32 v203, 0xffff0000, v150
	v_lshlrev_b32_e32 v150, 16, v151
	v_and_b32_e32 v151, 0xffff0000, v151
	v_lshlrev_b32_e32 v206, 16, v146
	v_and_b32_e32 v207, 0xffff0000, v146
	v_lshlrev_b32_e32 v146, 16, v147
	v_and_b32_e32 v147, 0xffff0000, v147
	v_lshl_add_u64 v[96:97], v[96:97], 0, v[176:177]
	v_pk_fma_f32 v[90:91], v[90:91], 0.5, v[144:145] op_sel_hi:[1,0,1]
	v_pk_fma_f32 v[88:89], v[88:89], 0.5, v[208:209] op_sel_hi:[1,0,1]
	v_pk_fma_f32 v[82:83], v[82:83], 0.5, v[148:149] op_sel_hi:[1,0,1]
	v_pk_fma_f32 v[80:81], v[80:81], 0.5, v[204:205] op_sel_hi:[1,0,1]
	v_pk_fma_f32 v[94:95], v[94:95], 0.5, v[146:147] op_sel_hi:[1,0,1]
	v_pk_fma_f32 v[92:93], v[92:93], 0.5, v[206:207] op_sel_hi:[1,0,1]
	global_store_dwordx4 v[96:97], v[88:91], off
	global_store_dwordx4 v[96:97], v[92:95], off offset:16
	v_pk_fma_f32 v[86:87], v[86:87], 0.5, v[150:151] op_sel_hi:[1,0,1]
	v_pk_fma_f32 v[84:85], v[84:85], 0.5, v[202:203] op_sel_hi:[1,0,1]
	global_store_dwordx4 v[96:97], v[80:83], off offset:512
	global_store_dwordx4 v[96:97], v[84:87], off offset:528
	v_lshlrev_b32_e32 v182, 16, v158
	v_lshlrev_b64 v[80:81], 12, v[186:187]
	v_and_b32_e32 v183, 0xffff0000, v158
	v_lshlrev_b32_e32 v184, 16, v159
	v_and_b32_e32 v185, 0xffff0000, v159
	v_lshlrev_b32_e32 v158, 16, v156
	v_and_b32_e32 v159, 0xffff0000, v156
	v_lshlrev_b32_e32 v156, 16, v157
	v_and_b32_e32 v157, 0xffff0000, v157
	v_lshlrev_b32_e32 v200, 16, v152
	v_and_b32_e32 v201, 0xffff0000, v152
	v_lshlrev_b32_e32 v152, 16, v153
	v_and_b32_e32 v153, 0xffff0000, v153
	v_lshl_add_u64 v[80:81], s[4:5], 0, v[80:81]
	v_lshlrev_b32_e32 v198, 16, v154
	v_and_b32_e32 v199, 0xffff0000, v154
	v_lshlrev_b32_e32 v154, 16, v155
	v_and_b32_e32 v155, 0xffff0000, v155
	v_lshl_add_u64 v[80:81], v[80:81], 0, v[176:177]
	v_pk_fma_f32 v[74:75], v[74:75], 0.5, v[152:153] op_sel_hi:[1,0,1]
	v_pk_fma_f32 v[72:73], v[72:73], 0.5, v[200:201] op_sel_hi:[1,0,1]
	v_pk_fma_f32 v[66:67], v[66:67], 0.5, v[156:157] op_sel_hi:[1,0,1]
	v_pk_fma_f32 v[64:65], v[64:65], 0.5, v[158:159] op_sel_hi:[1,0,1]
	v_pk_fma_f32 v[78:79], v[78:79], 0.5, v[154:155] op_sel_hi:[1,0,1]
	v_pk_fma_f32 v[76:77], v[76:77], 0.5, v[198:199] op_sel_hi:[1,0,1]
	global_store_dwordx4 v[80:81], v[72:75], off
	global_store_dwordx4 v[80:81], v[76:79], off offset:16
	v_pk_fma_f32 v[70:71], v[70:71], 0.5, v[184:185] op_sel_hi:[1,0,1]
	v_pk_fma_f32 v[68:69], v[68:69], 0.5, v[182:183] op_sel_hi:[1,0,1]
	global_store_dwordx4 v[80:81], v[64:67], off offset:512
	global_store_dwordx4 v[80:81], v[68:71], off offset:528
